# v38 + removed per-segment s_setprio toggles in the four GEMM K-loops
# baseline (speedup 1.0000x reference)
; #define PG8_STAGE(bufoff, gbase, voff) do { _Pragma("unroll") for (int _i = 0; _i < 2; ++_i) \
;         __builtin_amdgcn_global_load_lds((const unsigned*)((const char*)(gbase) + (voff)[_i]), (PG8_LAS unsigned*)(lds + (bufoff) + ldsw + _i * 8192), 16, 0, 0); } while (0)
; #define PG8_LDA(dst, b, h) do { _Pragma("unroll") for (int m = 0; m < 4; ++m) _Pragma("unroll") for (int k = 0; k < 2; ++k) dst[m][k] = *(const PG8_LAS bf16x8*)(lds + PG8_SA(b, h) + aoff + m * 2048 + k * 1024); } while (0)
; #define PG8_LDB(dst, b, h) do { _Pragma("unroll") for (int n = 0; n < 2; ++n) _Pragma("unroll") for (int k = 0; k < 2; ++k) dst[n][k] = *(const PG8_LAS bf16x8*)(lds + PG8_SB(b, h) + boff + n * 2048 + k * 1024); } while (0)
; #define PG8_MMA(ai, bj, At, Bt) do { __builtin_amdgcn_s_setprio(1); _Pragma("unroll") for (int m = 0; m < 4; ++m) _Pragma("unroll") for (int n = 0; n < 2; ++n) _Pragma("unroll") for (int k = 0; k < 2; ++k) \
;         acc[ai][bj][m][n] = __builtin_amdgcn_mfma_f32_16x16x32_bf16(Bt[n][k], At[m][k], acc[ai][bj][m][n], 0, 0, 0); __builtin_amdgcn_s_setprio(0); } while (0)
; #define PG8_WAIT_V(n) asm volatile("s_waitcnt vmcnt(" #n ")" ::: "memory")
; #define PG8_WAIT_L(n) asm volatile("s_waitcnt lgkmcnt(" #n ")" ::: "memory")
; #define PG8_BAR __builtin_amdgcn_s_barrier()
; #define PG8_SCHED __builtin_amdgcn_sched_barrier(0)
; template <class Epi, class Sched, bool ALIGN_EPI = false, bool SP2 = false>
; __device__ __forceinline__ void gemm_phase(PG8_LAS unsigned char* lds, const Gemm g, const Sched& S, const Epi& E) {
;     ...
;         for (int t = 0; t < nt; t += 2) {
;             const bool last = (t == nt - 2);
;             const char* a1 = cA + (size_t)(t + 1) * kstep;
;             const char* a2 = last ? nA : cA + (size_t)(t + 2) * kstep; const char* b2 = last ? nB : cB + (size_t)(t + 2) * kstep;
;             const char* a3 = a2 + kstep; const char* b3 = b2 + kstep;
;             if (last && has_next) S.a_ready(nxt);
;             if constexpr (SP2) {
;             PG8_LDB(B0, 0, 0); PG8_LDB(B1, 0, 1); PG8_SCHED; PG8_LDA(At, 0, 0); PG8_STAGE(PG8_SA(1, 1), a1 + hstep, voffA);
;             PG8_WAIT_V(8); PG8_WAIT_L(0); PG8_BAR; PG8_MMA(0, 0, At, B0); PG8_MMA(0, 1, At, B1); PG8_BAR; PG8_SCHED;
;             PG8_LDA(At, 0, 1); PG8_STAGE(PG8_SB(0, 0), b2, voffB); PG8_STAGE(PG8_SB(0, 1), b2 + hstep, voffB); PG8_STAGE(PG8_SA(0, 0), a2, voffA);
.Lpeel_p1:
	s_add_u32 s10, s8, 0xfffc0080
	s_addc_u32 s11, s9, -1
	s_add_i32 s30, 0, 0x10000
	s_cmp_eq_u32 s43, 12
	s_cselect_b32 s15, s33, s11
	s_cselect_b32 s14, s34, s10
	v_add_u32_e32 v0, s30, v204
	s_cselect_b32 s11, s35, s42
	s_cselect_b32 s10, s40, s41
	s_add_i32 s51, 0, 0x14000
	ds_read_b128 v[18:21], v0
	ds_read_b128 v[22:25], v0 offset:1024
	ds_read_b128 v[26:29], v0 offset:2048
	ds_read_b128 v[30:33], v0 offset:3072
	v_add_u32_e32 v0, s51, v204
	ds_read_b128 v[46:49], v0
	ds_read_b128 v[54:57], v0 offset:1024
	ds_read_b128 v[170:173], v0 offset:2048
	ds_read_b128 v[174:177], v0 offset:3072
	v_lshl_add_u64 v[190:191], s[8:9], 0, v[166:167]
	s_add_i32 m0, s21, 0xc000
	ds_read_b128 v[178:181], v225
	ds_read_b128 v[182:185], v225 offset:1024
	ds_read_b128 v[186:189], v225 offset:2048
	ds_read_b128 v[226:229], v225 offset:3072
	ds_read_b128 v[230:233], v225 offset:4096
	ds_read_b128 v[234:237], v225 offset:5120
	ds_read_b128 v[238:241], v225 offset:6144
	ds_read_b128 v[242:245], v225 offset:7168
	global_load_lds_dwordx4 v[190:191], off
	v_lshl_add_u64 v[190:191], s[8:9], 0, v[168:169]
	s_add_i32 m0, s21, 0xe000
	s_nop 0
	global_load_lds_dwordx4 v[190:191], off
	s_waitcnt vmcnt(8)
	s_waitcnt lgkmcnt(0)
	s_barrier
	s_waitcnt lgkmcnt(0)
	v_mfma_f32_16x16x32_bf16 v[150:153], v[18:21], v[178:181], 0
	v_mfma_f32_16x16x32_bf16 v[146:149], v[26:29], v[178:181], 0
	v_mfma_f32_16x16x32_bf16 v[134:137], v[18:21], v[186:189], 0
	v_mfma_f32_16x16x32_bf16 v[130:133], v[26:29], v[186:189], 0
	v_mfma_f32_16x16x32_bf16 v[118:121], v[18:21], v[230:233], 0
	v_mfma_f32_16x16x32_bf16 v[114:117], v[26:29], v[230:233], 0
	v_mfma_f32_16x16x32_bf16 v[102:105], v[18:21], v[238:241], 0
	v_mfma_f32_16x16x32_bf16 v[98:101], v[26:29], v[238:241], 0
	v_mfma_f32_16x16x32_bf16 v[150:153], v[22:25], v[182:185], v[150:153]
	v_mfma_f32_16x16x32_bf16 v[146:149], v[30:33], v[182:185], v[146:149]
	v_mfma_f32_16x16x32_bf16 v[134:137], v[22:25], v[226:229], v[134:137]
	v_mfma_f32_16x16x32_bf16 v[130:133], v[30:33], v[226:229], v[130:133]
	v_mfma_f32_16x16x32_bf16 v[118:121], v[22:25], v[234:237], v[118:121]
	v_mfma_f32_16x16x32_bf16 v[114:117], v[30:33], v[234:237], v[114:117]
	v_mfma_f32_16x16x32_bf16 v[102:105], v[22:25], v[242:245], v[102:105]
	v_mfma_f32_16x16x32_bf16 v[98:101], v[30:33], v[242:245], v[98:101]
	v_mfma_f32_16x16x32_bf16 v[142:145], v[46:49], v[178:181], 0
	v_mfma_f32_16x16x32_bf16 v[138:141], v[170:173], v[178:181], 0
	v_mfma_f32_16x16x32_bf16 v[126:129], v[46:49], v[186:189], 0
	v_mfma_f32_16x16x32_bf16 v[122:125], v[170:173], v[186:189], 0
	v_mfma_f32_16x16x32_bf16 v[110:113], v[46:49], v[230:233], 0
	v_mfma_f32_16x16x32_bf16 v[106:109], v[170:173], v[230:233], 0
	v_mfma_f32_16x16x32_bf16 v[94:97], v[46:49], v[238:241], 0
	v_mfma_f32_16x16x32_bf16 v[90:93], v[170:173], v[238:241], 0
	v_mfma_f32_16x16x32_bf16 v[142:145], v[54:57], v[182:185], v[142:145]
	v_mfma_f32_16x16x32_bf16 v[138:141], v[174:177], v[182:185], v[138:141]
	v_mfma_f32_16x16x32_bf16 v[126:129], v[54:57], v[226:229], v[126:129]
	v_mfma_f32_16x16x32_bf16 v[122:125], v[174:177], v[226:229], v[122:125]
	v_mfma_f32_16x16x32_bf16 v[110:113], v[54:57], v[234:237], v[110:113]
	v_mfma_f32_16x16x32_bf16 v[106:109], v[174:177], v[234:237], v[106:109]
	v_mfma_f32_16x16x32_bf16 v[94:97], v[54:57], v[242:245], v[94:97]
	v_mfma_f32_16x16x32_bf16 v[90:93], v[174:177], v[242:245], v[90:93]
	s_barrier
	s_add_i32 s30, s30, s20
	v_lshl_add_u64 v[190:191], s[10:11], 0, v[156:157]
	s_mov_b32 m0, s30
	ds_read_b128 v[178:181], v225 offset:16384
	ds_read_b128 v[182:185], v225 offset:17408
	ds_read_b128 v[186:189], v225 offset:18432
	ds_read_b128 v[226:229], v225 offset:19456
	ds_read_b128 v[230:233], v225 offset:20480
	ds_read_b128 v[234:237], v225 offset:21504
	ds_read_b128 v[238:241], v225 offset:22528
	ds_read_b128 v[242:245], v225 offset:23552
	global_load_lds_dwordx4 v[190:191], off
	s_add_i32 m0, s30, 0x2000
	s_add_u32 s30, s10, 0x40000
	v_lshl_add_u64 v[198:199], s[10:11], 0, v[160:161]
	s_addc_u32 s31, s11, 0
	s_add_i32 s51, s51, s20
	global_load_lds_dwordx4 v[198:199], off
	v_lshl_add_u64 v[200:201], s[30:31], 0, v[156:157]
	s_mov_b32 m0, s51
	v_lshl_add_u64 v[250:251], s[14:15], 0, v[158:159]
	global_load_lds_dwordx4 v[200:201], off
	v_lshl_add_u64 v[200:201], s[30:31], 0, v[160:161]
	s_add_i32 m0, s51, 0x2000
	s_nop 0
	global_load_lds_dwordx4 v[200:201], off
	v_lshl_add_u64 v[200:201], s[14:15], 0, v[154:155]
	s_mov_b32 m0, s21
	s_nop 0
	global_load_lds_dwordx4 v[200:201], off
	s_mov_b32 m0, s45
	s_nop 0
	global_load_lds_dwordx4 v[250:251], off
	s_waitcnt vmcnt(8)
	s_waitcnt lgkmcnt(0)
	s_barrier
; #define PG8_STAGE(bufoff, gbase, voff) do { _Pragma("unroll") for (int _i = 0; _i < 2; ++_i) \
;         __builtin_amdgcn_global_load_lds((const unsigned*)((const char*)(gbase) + (voff)[_i]), (PG8_LAS unsigned*)(lds + (bufoff) + ldsw + _i * 8192), 16, 0, 0); } while (0)
; #define PG8_LDA(dst, b, h) do { _Pragma("unroll") for (int m = 0; m < 4; ++m) _Pragma("unroll") for (int k = 0; k < 2; ++k) dst[m][k] = *(const PG8_LAS bf16x8*)(lds + PG8_SA(b, h) + aoff + m * 2048 + k * 1024); } while (0)
; #define PG8_LDB(dst, b, h) do { _Pragma("unroll") for (int n = 0; n < 2; ++n) _Pragma("unroll") for (int k = 0; k < 2; ++k) dst[n][k] = *(const PG8_LAS bf16x8*)(lds + PG8_SB(b, h) + boff + n * 2048 + k * 1024); } while (0)
; #define PG8_MMA(ai, bj, At, Bt) do { __builtin_amdgcn_s_setprio(1); _Pragma("unroll") for (int m = 0; m < 4; ++m) _Pragma("unroll") for (int n = 0; n < 2; ++n) _Pragma("unroll") for (int k = 0; k < 2; ++k) \
;         acc[ai][bj][m][n] = __builtin_amdgcn_mfma_f32_16x16x32_bf16(Bt[n][k], At[m][k], acc[ai][bj][m][n], 0, 0, 0); __builtin_amdgcn_s_setprio(0); } while (0)
; #define PG8_WAIT_V(n) asm volatile("s_waitcnt vmcnt(" #n ")" ::: "memory")
; #define PG8_WAIT_L(n) asm volatile("s_waitcnt lgkmcnt(" #n ")" ::: "memory")
; #define PG8_BAR __builtin_amdgcn_s_barrier()
; #define PG8_SCHED __builtin_amdgcn_sched_barrier(0)
; template <class Epi, class Sched, bool ALIGN_EPI = false, bool SP2 = false>
; __device__ __forceinline__ void gemm_phase(PG8_LAS unsigned char* lds, const Gemm g, const Sched& S, const Epi& E) {
;     ...
;             PG8_WAIT_V(8); PG8_WAIT_L(0); PG8_BAR; PG8_MMA(1, 0, At, B0); PG8_MMA(1, 1, At, B1); PG8_BAR; PG8_SCHED;
;             PG8_LDB(B0, 1, 0); PG8_LDB(B1, 1, 1); PG8_SCHED; PG8_LDA(At, 1, 0); PG8_STAGE(PG8_SA(0, 1), a2 + hstep, voffA);
;             PG8_WAIT_V(8); PG8_WAIT_L(0); PG8_BAR; PG8_MMA(0, 0, At, B0); PG8_MMA(0, 1, At, B1); PG8_BAR; PG8_SCHED;
	s_waitcnt lgkmcnt(0)
	v_mfma_f32_16x16x32_bf16 v[86:89], v[18:21], v[178:181], 0
	v_mfma_f32_16x16x32_bf16 v[82:85], v[26:29], v[178:181], 0
	v_mfma_f32_16x16x32_bf16 v[70:73], v[18:21], v[186:189], 0
	v_mfma_f32_16x16x32_bf16 v[66:69], v[26:29], v[186:189], 0
	v_mfma_f32_16x16x32_bf16 v[50:53], v[18:21], v[230:233], 0
	v_mfma_f32_16x16x32_bf16 v[42:45], v[26:29], v[230:233], 0
	v_mfma_f32_16x16x32_bf16 v[14:17], v[18:21], v[238:241], 0
	v_mfma_f32_16x16x32_bf16 v[10:13], v[26:29], v[238:241], 0
	v_mfma_f32_16x16x32_bf16 v[86:89], v[22:25], v[182:185], v[86:89]
	v_mfma_f32_16x16x32_bf16 v[82:85], v[30:33], v[182:185], v[82:85]
	v_mfma_f32_16x16x32_bf16 v[70:73], v[22:25], v[226:229], v[70:73]
	v_mfma_f32_16x16x32_bf16 v[66:69], v[30:33], v[226:229], v[66:69]
	v_mfma_f32_16x16x32_bf16 v[50:53], v[22:25], v[234:237], v[50:53]
	v_mfma_f32_16x16x32_bf16 v[42:45], v[30:33], v[234:237], v[42:45]
	v_mfma_f32_16x16x32_bf16 v[14:17], v[22:25], v[242:245], v[14:17]
	v_mfma_f32_16x16x32_bf16 v[10:13], v[30:33], v[242:245], v[10:13]
	v_mfma_f32_16x16x32_bf16 v[38:41], v[46:49], v[230:233], 0
	v_mfma_f32_16x16x32_bf16 v[34:37], v[170:173], v[230:233], 0
	v_mfma_f32_16x16x32_bf16 v[6:9], v[46:49], v[238:241], 0
	v_mfma_f32_16x16x32_bf16 v[2:5], v[170:173], v[238:241], 0
	v_mfma_f32_16x16x32_bf16 v[18:21], v[46:49], v[178:181], 0
	v_mfma_f32_16x16x32_bf16 v[22:25], v[170:173], v[178:181], 0
	v_mfma_f32_16x16x32_bf16 v[26:29], v[46:49], v[186:189], 0
	v_mfma_f32_16x16x32_bf16 v[30:33], v[170:173], v[186:189], 0
	v_mfma_f32_16x16x32_bf16 v[38:41], v[54:57], v[234:237], v[38:41]
	v_mfma_f32_16x16x32_bf16 v[34:37], v[174:177], v[234:237], v[34:37]
	v_mfma_f32_16x16x32_bf16 v[6:9], v[54:57], v[242:245], v[6:9]
	v_mfma_f32_16x16x32_bf16 v[2:5], v[174:177], v[242:245], v[2:5]
	v_mfma_f32_16x16x32_bf16 v[18:21], v[54:57], v[182:185], v[18:21]
	v_mfma_f32_16x16x32_bf16 v[22:25], v[174:177], v[182:185], v[22:25]
	v_mfma_f32_16x16x32_bf16 v[26:29], v[54:57], v[226:229], v[26:29]
	v_mfma_f32_16x16x32_bf16 v[30:33], v[174:177], v[226:229], v[30:33]
	s_barrier
	s_add_i32 s30, 0, 0x18000
	v_add_u32_e32 v0, s30, v204
	s_add_i32 s31, 0, 0x1c000
	ds_read_b128 v[46:49], v0
	ds_read_b128 v[54:57], v0 offset:1024
	ds_read_b128 v[58:61], v0 offset:2048
	ds_read_b128 v[62:65], v0 offset:3072
	v_add_u32_e32 v0, s31, v204
	ds_read_b128 v[170:173], v0
	ds_read_b128 v[174:177], v0 offset:1024
	ds_read_b128 v[178:181], v0 offset:2048
	ds_read_b128 v[182:185], v0 offset:3072
	s_add_u32 s14, s14, 0x40000
	s_addc_u32 s15, s15, 0
	s_mov_b32 m0, s62
	v_lshl_add_u64 v[246:247], s[14:15], 0, v[154:155]
	ds_read_b128 v[74:77], v225 offset:32768
	ds_read_b128 v[78:81], v225 offset:33792
	ds_read_b128 v[186:189], v225 offset:34816
	ds_read_b128 v[226:229], v225 offset:35840
	ds_read_b128 v[230:233], v225 offset:36864
	ds_read_b128 v[234:237], v225 offset:37888
	ds_read_b128 v[238:241], v225 offset:38912
	ds_read_b128 v[242:245], v225 offset:39936
	global_load_lds_dwordx4 v[246:247], off
	v_lshl_add_u64 v[246:247], s[14:15], 0, v[158:159]
	s_mov_b32 m0, s63
	s_nop 0
	global_load_lds_dwordx4 v[246:247], off
	s_waitcnt vmcnt(8)
	s_waitcnt lgkmcnt(0)
	s_barrier
	s_waitcnt lgkmcnt(0)
	v_mfma_f32_16x16x32_bf16 v[150:153], v[46:49], v[74:77], v[150:153]
	v_mfma_f32_16x16x32_bf16 v[146:149], v[58:61], v[74:77], v[146:149]
	v_mfma_f32_16x16x32_bf16 v[134:137], v[46:49], v[186:189], v[134:137]
	v_mfma_f32_16x16x32_bf16 v[130:133], v[58:61], v[186:189], v[130:133]
	v_mfma_f32_16x16x32_bf16 v[118:121], v[46:49], v[230:233], v[118:121]
	v_mfma_f32_16x16x32_bf16 v[114:117], v[58:61], v[230:233], v[114:117]
	v_mfma_f32_16x16x32_bf16 v[102:105], v[46:49], v[238:241], v[102:105]
	v_mfma_f32_16x16x32_bf16 v[98:101], v[58:61], v[238:241], v[98:101]
	v_mfma_f32_16x16x32_bf16 v[150:153], v[54:57], v[78:81], v[150:153]
	v_mfma_f32_16x16x32_bf16 v[146:149], v[62:65], v[78:81], v[146:149]
	v_mfma_f32_16x16x32_bf16 v[134:137], v[54:57], v[226:229], v[134:137]
	v_mfma_f32_16x16x32_bf16 v[130:133], v[62:65], v[226:229], v[130:133]
	v_mfma_f32_16x16x32_bf16 v[118:121], v[54:57], v[234:237], v[118:121]
	v_mfma_f32_16x16x32_bf16 v[114:117], v[62:65], v[234:237], v[114:117]
	v_mfma_f32_16x16x32_bf16 v[102:105], v[54:57], v[242:245], v[102:105]
	v_mfma_f32_16x16x32_bf16 v[98:101], v[62:65], v[242:245], v[98:101]
	v_mfma_f32_16x16x32_bf16 v[142:145], v[170:173], v[74:77], v[142:145]
	v_mfma_f32_16x16x32_bf16 v[74:77], v[178:181], v[74:77], v[138:141]
	v_mfma_f32_16x16x32_bf16 v[138:141], v[182:185], v[78:81], v[74:77]
	v_mfma_f32_16x16x32_bf16 v[74:77], v[170:173], v[186:189], v[126:129]
	v_mfma_f32_16x16x32_bf16 v[126:129], v[174:177], v[226:229], v[74:77]
	v_mfma_f32_16x16x32_bf16 v[74:77], v[178:181], v[186:189], v[122:125]
	v_mfma_f32_16x16x32_bf16 v[122:125], v[182:185], v[226:229], v[74:77]
	v_mfma_f32_16x16x32_bf16 v[74:77], v[170:173], v[230:233], v[110:113]
	v_mfma_f32_16x16x32_bf16 v[110:113], v[174:177], v[234:237], v[74:77]
	v_mfma_f32_16x16x32_bf16 v[74:77], v[178:181], v[230:233], v[106:109]
	v_mfma_f32_16x16x32_bf16 v[106:109], v[182:185], v[234:237], v[74:77]
	v_mfma_f32_16x16x32_bf16 v[74:77], v[170:173], v[238:241], v[94:97]
	v_mfma_f32_16x16x32_bf16 v[94:97], v[174:177], v[242:245], v[74:77]
	v_mfma_f32_16x16x32_bf16 v[74:77], v[178:181], v[238:241], v[90:93]
	v_mfma_f32_16x16x32_bf16 v[142:145], v[174:177], v[78:81], v[142:145]
	v_mfma_f32_16x16x32_bf16 v[90:93], v[182:185], v[242:245], v[74:77]
	s_barrier
; #define PG8_STAGE(bufoff, gbase, voff) do { _Pragma("unroll") for (int _i = 0; _i < 2; ++_i) \
;         __builtin_amdgcn_global_load_lds((const unsigned*)((const char*)(gbase) + (voff)[_i]), (PG8_LAS unsigned*)(lds + (bufoff) + ldsw + _i * 8192), 16, 0, 0); } while (0)
; #define PG8_LDA(dst, b, h) do { _Pragma("unroll") for (int m = 0; m < 4; ++m) _Pragma("unroll") for (int k = 0; k < 2; ++k) dst[m][k] = *(const PG8_LAS bf16x8*)(lds + PG8_SA(b, h) + aoff + m * 2048 + k * 1024); } while (0)
; #define PG8_LDB(dst, b, h) do { _Pragma("unroll") for (int n = 0; n < 2; ++n) _Pragma("unroll") for (int k = 0; k < 2; ++k) dst[n][k] = *(const PG8_LAS bf16x8*)(lds + PG8_SB(b, h) + boff + n * 2048 + k * 1024); } while (0)
; #define PG8_MMA(ai, bj, At, Bt) do { __builtin_amdgcn_s_setprio(1); _Pragma("unroll") for (int m = 0; m < 4; ++m) _Pragma("unroll") for (int n = 0; n < 2; ++n) _Pragma("unroll") for (int k = 0; k < 2; ++k) \
;         acc[ai][bj][m][n] = __builtin_amdgcn_mfma_f32_16x16x32_bf16(Bt[n][k], At[m][k], acc[ai][bj][m][n], 0, 0, 0); __builtin_amdgcn_s_setprio(0); } while (0)
; #define PG8_WAIT_V(n) asm volatile("s_waitcnt vmcnt(" #n ")" ::: "memory")
; #define PG8_BAR __builtin_amdgcn_s_barrier()
; template <class Epi, class Sched, bool ALIGN_EPI = false, bool SP2 = false>
; __device__ __forceinline__ void gemm_phase(PG8_LAS unsigned char* lds, const Gemm g, const Sched& S, const Epi& E) {
;     ...
;         for (int t = 0; t < nt; t += 2) {
;             const bool last = (t == nt - 2);
;             const char* a1 = cA + (size_t)(t + 1) * kstep;
;             const char* a2 = last ? nA : cA + (size_t)(t + 2) * kstep; const char* b2 = last ? nB : cB + (size_t)(t + 2) * kstep;
;             const char* a3 = a2 + kstep; const char* b3 = b2 + kstep;
;             if (last && has_next) S.a_ready(nxt);
;             if constexpr (SP2) {
;             PG8_LDB(B0, 0, 0); PG8_LDB(B1, 0, 1); PG8_SCHED; PG8_LDA(At, 0, 0); PG8_STAGE(PG8_SA(1, 1), a1 + hstep, voffA);
;             PG8_WAIT_V(8); PG8_WAIT_L(0); PG8_BAR; PG8_MMA(0, 0, At, B0); PG8_MMA(0, 1, At, B1); PG8_BAR; PG8_SCHED;
;     ...
;             PG8_LDA(At, 1, 1); PG8_STAGE(PG8_SB(1, 0), b3, voffB); PG8_STAGE(PG8_SB(1, 1), b3 + hstep, voffB); PG8_STAGE(PG8_SA(1, 0), a3, voffA);
;             PG8_WAIT_V(8); PG8_WAIT_L(0); PG8_BAR; PG8_MMA(1, 0, At, B0); PG8_MMA(1, 1, At, B1); PG8_BAR; PG8_SCHED;
	s_add_i32 s14, s30, s20
	v_lshl_add_u64 v[78:79], v[190:191], 0, s[0:1]
	s_mov_b32 m0, s14
	s_nop 0
	ds_read_b128 v[74:77], v225 offset:49152
	ds_read_b128 v[186:189], v225 offset:50176
	ds_read_b128 v[226:229], v225 offset:51200
	ds_read_b128 v[230:233], v225 offset:52224
	ds_read_b128 v[234:237], v225 offset:53248
	ds_read_b128 v[238:241], v225 offset:54272
	ds_read_b128 v[242:245], v225 offset:55296
	ds_read_b128 v[246:249], v225 offset:56320
	global_load_lds_dwordx4 v[78:79], off
	s_add_i32 m0, s14, 0x2000
	s_add_u32 s10, s10, 0x40080
	v_lshl_add_u64 v[78:79], v[198:199], 0, s[0:1]
	s_addc_u32 s11, s11, 0
	s_add_i32 s14, s31, s20
	global_load_lds_dwordx4 v[78:79], off
	v_lshl_add_u64 v[78:79], s[10:11], 0, v[156:157]
	s_mov_b32 m0, s14
	s_nop 0
	global_load_lds_dwordx4 v[78:79], off
	v_lshl_add_u64 v[78:79], s[10:11], 0, v[160:161]
	s_add_i32 m0, s14, 0x2000
	s_nop 0
	global_load_lds_dwordx4 v[78:79], off
	v_lshl_add_u64 v[78:79], v[200:201], 0, s[0:1]
	s_mov_b32 m0, s64
	s_nop 0
	global_load_lds_dwordx4 v[78:79], off
	v_lshl_add_u64 v[78:79], v[250:251], 0, s[0:1]
	s_mov_b32 m0, s65
	s_nop 0
	global_load_lds_dwordx4 v[78:79], off
	s_waitcnt vmcnt(8)
	s_waitcnt lgkmcnt(0)
	s_barrier
	s_waitcnt lgkmcnt(0)
	v_mfma_f32_16x16x32_bf16 v[78:81], v[46:49], v[74:77], v[86:89]
	v_mfma_f32_16x16x32_bf16 v[86:89], v[54:57], v[186:189], v[78:81]
	v_mfma_f32_16x16x32_bf16 v[78:81], v[58:61], v[74:77], v[82:85]
	v_mfma_f32_16x16x32_bf16 v[70:73], v[46:49], v[226:229], v[70:73]
	v_mfma_f32_16x16x32_bf16 v[66:69], v[58:61], v[226:229], v[66:69]
	v_mfma_f32_16x16x32_bf16 v[50:53], v[46:49], v[234:237], v[50:53]
	v_mfma_f32_16x16x32_bf16 v[42:45], v[58:61], v[234:237], v[42:45]
	v_mfma_f32_16x16x32_bf16 v[14:17], v[46:49], v[242:245], v[14:17]
	v_mfma_f32_16x16x32_bf16 v[10:13], v[58:61], v[242:245], v[10:13]
	v_mfma_f32_16x16x32_bf16 v[82:85], v[62:65], v[186:189], v[78:81]
	v_mfma_f32_16x16x32_bf16 v[70:73], v[54:57], v[230:233], v[70:73]
	v_mfma_f32_16x16x32_bf16 v[66:69], v[62:65], v[230:233], v[66:69]
	v_mfma_f32_16x16x32_bf16 v[50:53], v[54:57], v[238:241], v[50:53]
	v_mfma_f32_16x16x32_bf16 v[42:45], v[62:65], v[238:241], v[42:45]
	v_mfma_f32_16x16x32_bf16 v[14:17], v[54:57], v[246:249], v[14:17]
	v_mfma_f32_16x16x32_bf16 v[10:13], v[62:65], v[246:249], v[10:13]
	v_mfma_f32_16x16x32_bf16 v[18:21], v[170:173], v[74:77], v[18:21]
	v_mfma_f32_16x16x32_bf16 v[78:81], v[174:177], v[186:189], v[18:21]
	v_mfma_f32_16x16x32_bf16 v[18:21], v[178:181], v[74:77], v[22:25]
	v_mfma_f32_16x16x32_bf16 v[74:77], v[182:185], v[186:189], v[18:21]
	v_mfma_f32_16x16x32_bf16 v[18:21], v[170:173], v[226:229], v[26:29]
	v_mfma_f32_16x16x32_bf16 v[62:65], v[174:177], v[230:233], v[18:21]
	v_mfma_f32_16x16x32_bf16 v[18:21], v[178:181], v[226:229], v[30:33]
	v_mfma_f32_16x16x32_bf16 v[58:61], v[182:185], v[230:233], v[18:21]
	v_mfma_f32_16x16x32_bf16 v[18:21], v[170:173], v[234:237], v[38:41]
	v_mfma_f32_16x16x32_bf16 v[38:41], v[174:177], v[238:241], v[18:21]
	v_mfma_f32_16x16x32_bf16 v[18:21], v[178:181], v[234:237], v[34:37]
	v_mfma_f32_16x16x32_bf16 v[6:9], v[170:173], v[242:245], v[6:9]
	v_mfma_f32_16x16x32_bf16 v[2:5], v[178:181], v[242:245], v[2:5]
	v_mfma_f32_16x16x32_bf16 v[34:37], v[182:185], v[238:241], v[18:21]
	v_mfma_f32_16x16x32_bf16 v[6:9], v[174:177], v[246:249], v[6:9]
	v_mfma_f32_16x16x32_bf16 v[2:5], v[182:185], v[246:249], v[2:5]
	s_barrier
	s_add_i32 s43, s43, 2
	s_add_u32 s8, s8, 0x100
	s_addc_u32 s9, s9, 0
	s_add_u32 s41, s41, 0x100
	s_addc_u32 s42, s42, 0
	s_cmp_gt_u32 s43, 13
	s_cbranch_scc0 .LBB0_188
	s_branch .Lpeel_exit_p1
.LBB0_188:
	s_add_u32 s10, s8, 0xfffc0080
	s_addc_u32 s11, s9, -1
	s_add_i32 s30, 0, 0x10000
	s_cmp_eq_u32 s43, 12
	s_cselect_b32 s15, s33, s11
	s_cselect_b32 s14, s34, s10
	v_add_u32_e32 v0, s30, v204
	s_cselect_b32 s11, s35, s42
	s_cselect_b32 s10, s40, s41
	s_add_i32 s51, 0, 0x14000
	ds_read_b128 v[18:21], v0
	ds_read_b128 v[22:25], v0 offset:1024
	ds_read_b128 v[26:29], v0 offset:2048
	ds_read_b128 v[30:33], v0 offset:3072
	v_add_u32_e32 v0, s51, v204
	ds_read_b128 v[46:49], v0
	ds_read_b128 v[54:57], v0 offset:1024
	ds_read_b128 v[170:173], v0 offset:2048
	ds_read_b128 v[174:177], v0 offset:3072
	v_lshl_add_u64 v[190:191], s[8:9], 0, v[166:167]
	s_add_i32 m0, s21, 0xc000
	ds_read_b128 v[178:181], v225
	ds_read_b128 v[182:185], v225 offset:1024
	ds_read_b128 v[186:189], v225 offset:2048
	ds_read_b128 v[226:229], v225 offset:3072
	ds_read_b128 v[230:233], v225 offset:4096
	ds_read_b128 v[234:237], v225 offset:5120
	ds_read_b128 v[238:241], v225 offset:6144
	ds_read_b128 v[242:245], v225 offset:7168
	global_load_lds_dwordx4 v[190:191], off
	v_lshl_add_u64 v[190:191], s[8:9], 0, v[168:169]
	s_add_i32 m0, s21, 0xe000
	s_nop 0
	global_load_lds_dwordx4 v[190:191], off
	s_waitcnt vmcnt(8)
	s_waitcnt lgkmcnt(0)
	s_barrier
; #define PG8_STAGE(bufoff, gbase, voff) do { _Pragma("unroll") for (int _i = 0; _i < 2; ++_i) \
;         __builtin_amdgcn_global_load_lds((const unsigned*)((const char*)(gbase) + (voff)[_i]), (PG8_LAS unsigned*)(lds + (bufoff) + ldsw + _i * 8192), 16, 0, 0); } while (0)
; #define PG8_LDA(dst, b, h) do { _Pragma("unroll") for (int m = 0; m < 4; ++m) _Pragma("unroll") for (int k = 0; k < 2; ++k) dst[m][k] = *(const PG8_LAS bf16x8*)(lds + PG8_SA(b, h) + aoff + m * 2048 + k * 1024); } while (0)
; #define PG8_MMA(ai, bj, At, Bt) do { __builtin_amdgcn_s_setprio(1); _Pragma("unroll") for (int m = 0; m < 4; ++m) _Pragma("unroll") for (int n = 0; n < 2; ++n) _Pragma("unroll") for (int k = 0; k < 2; ++k) \
;         acc[ai][bj][m][n] = __builtin_amdgcn_mfma_f32_16x16x32_bf16(Bt[n][k], At[m][k], acc[ai][bj][m][n], 0, 0, 0); __builtin_amdgcn_s_setprio(0); } while (0)
; #define PG8_WAIT_V(n) asm volatile("s_waitcnt vmcnt(" #n ")" ::: "memory")
; #define PG8_WAIT_L(n) asm volatile("s_waitcnt lgkmcnt(" #n ")" ::: "memory")
; #define PG8_BAR __builtin_amdgcn_s_barrier()
; #define PG8_SCHED __builtin_amdgcn_sched_barrier(0)
; template <class Epi, class Sched, bool ALIGN_EPI = false, bool SP2 = false>
; __device__ __forceinline__ void gemm_phase(PG8_LAS unsigned char* lds, const Gemm g, const Sched& S, const Epi& E) {
;     ...
;             PG8_WAIT_V(8); PG8_WAIT_L(0); PG8_BAR; PG8_MMA(0, 0, At, B0); PG8_MMA(0, 1, At, B1); PG8_BAR; PG8_SCHED;
;             PG8_LDA(At, 0, 1); PG8_STAGE(PG8_SB(0, 0), b2, voffB); PG8_STAGE(PG8_SB(0, 1), b2 + hstep, voffB); PG8_STAGE(PG8_SA(0, 0), a2, voffA);
;             PG8_WAIT_V(8); PG8_WAIT_L(0); PG8_BAR; PG8_MMA(1, 0, At, B0); PG8_MMA(1, 1, At, B1); PG8_BAR; PG8_SCHED;
	s_waitcnt lgkmcnt(0)
	v_mfma_f32_16x16x32_bf16 v[150:153], v[18:21], v[178:181], v[150:153]
	v_mfma_f32_16x16x32_bf16 v[146:149], v[26:29], v[178:181], v[146:149]
	v_mfma_f32_16x16x32_bf16 v[134:137], v[18:21], v[186:189], v[134:137]
	v_mfma_f32_16x16x32_bf16 v[130:133], v[26:29], v[186:189], v[130:133]
	v_mfma_f32_16x16x32_bf16 v[118:121], v[18:21], v[230:233], v[118:121]
	v_mfma_f32_16x16x32_bf16 v[114:117], v[26:29], v[230:233], v[114:117]
	v_mfma_f32_16x16x32_bf16 v[102:105], v[18:21], v[238:241], v[102:105]
	v_mfma_f32_16x16x32_bf16 v[98:101], v[26:29], v[238:241], v[98:101]
	v_mfma_f32_16x16x32_bf16 v[150:153], v[22:25], v[182:185], v[150:153]
	v_mfma_f32_16x16x32_bf16 v[146:149], v[30:33], v[182:185], v[146:149]
	v_mfma_f32_16x16x32_bf16 v[134:137], v[22:25], v[226:229], v[134:137]
	v_mfma_f32_16x16x32_bf16 v[130:133], v[30:33], v[226:229], v[130:133]
	v_mfma_f32_16x16x32_bf16 v[118:121], v[22:25], v[234:237], v[118:121]
	v_mfma_f32_16x16x32_bf16 v[114:117], v[30:33], v[234:237], v[114:117]
	v_mfma_f32_16x16x32_bf16 v[102:105], v[22:25], v[242:245], v[102:105]
	v_mfma_f32_16x16x32_bf16 v[98:101], v[30:33], v[242:245], v[98:101]
	v_mfma_f32_16x16x32_bf16 v[142:145], v[46:49], v[178:181], v[142:145]
	v_mfma_f32_16x16x32_bf16 v[138:141], v[170:173], v[178:181], v[138:141]
	v_mfma_f32_16x16x32_bf16 v[126:129], v[46:49], v[186:189], v[126:129]
	v_mfma_f32_16x16x32_bf16 v[122:125], v[170:173], v[186:189], v[122:125]
	v_mfma_f32_16x16x32_bf16 v[110:113], v[46:49], v[230:233], v[110:113]
	v_mfma_f32_16x16x32_bf16 v[106:109], v[170:173], v[230:233], v[106:109]
	v_mfma_f32_16x16x32_bf16 v[94:97], v[46:49], v[238:241], v[94:97]
	v_mfma_f32_16x16x32_bf16 v[90:93], v[170:173], v[238:241], v[90:93]
	v_mfma_f32_16x16x32_bf16 v[142:145], v[54:57], v[182:185], v[142:145]
	v_mfma_f32_16x16x32_bf16 v[138:141], v[174:177], v[182:185], v[138:141]
	v_mfma_f32_16x16x32_bf16 v[126:129], v[54:57], v[226:229], v[126:129]
	v_mfma_f32_16x16x32_bf16 v[122:125], v[174:177], v[226:229], v[122:125]
	v_mfma_f32_16x16x32_bf16 v[110:113], v[54:57], v[234:237], v[110:113]
	v_mfma_f32_16x16x32_bf16 v[106:109], v[174:177], v[234:237], v[106:109]
	v_mfma_f32_16x16x32_bf16 v[94:97], v[54:57], v[242:245], v[94:97]
	v_mfma_f32_16x16x32_bf16 v[90:93], v[174:177], v[242:245], v[90:93]
	s_barrier
	s_add_i32 s30, s30, s20
	v_lshl_add_u64 v[190:191], s[10:11], 0, v[156:157]
	s_mov_b32 m0, s30
	ds_read_b128 v[178:181], v225 offset:16384
	ds_read_b128 v[182:185], v225 offset:17408
	ds_read_b128 v[186:189], v225 offset:18432
	ds_read_b128 v[226:229], v225 offset:19456
	ds_read_b128 v[230:233], v225 offset:20480
	ds_read_b128 v[234:237], v225 offset:21504
	ds_read_b128 v[238:241], v225 offset:22528
	ds_read_b128 v[242:245], v225 offset:23552
	global_load_lds_dwordx4 v[190:191], off
	s_add_i32 m0, s30, 0x2000
	s_add_u32 s30, s10, 0x40000
	v_lshl_add_u64 v[198:199], s[10:11], 0, v[160:161]
	s_addc_u32 s31, s11, 0
	s_add_i32 s51, s51, s20
	global_load_lds_dwordx4 v[198:199], off
	v_lshl_add_u64 v[200:201], s[30:31], 0, v[156:157]
	s_mov_b32 m0, s51
	v_lshl_add_u64 v[250:251], s[14:15], 0, v[158:159]
	global_load_lds_dwordx4 v[200:201], off
	v_lshl_add_u64 v[200:201], s[30:31], 0, v[160:161]
	s_add_i32 m0, s51, 0x2000
	s_nop 0
	global_load_lds_dwordx4 v[200:201], off
	v_lshl_add_u64 v[200:201], s[14:15], 0, v[154:155]
	s_mov_b32 m0, s21
	s_nop 0
	global_load_lds_dwordx4 v[200:201], off
	s_mov_b32 m0, s45
	s_nop 0
	global_load_lds_dwordx4 v[250:251], off
	s_waitcnt vmcnt(8)
	s_waitcnt lgkmcnt(0)
	s_barrier
	s_waitcnt lgkmcnt(0)
	v_mfma_f32_16x16x32_bf16 v[86:89], v[18:21], v[178:181], v[86:89]
	v_mfma_f32_16x16x32_bf16 v[82:85], v[26:29], v[178:181], v[82:85]
	v_mfma_f32_16x16x32_bf16 v[70:73], v[18:21], v[186:189], v[70:73]
	v_mfma_f32_16x16x32_bf16 v[66:69], v[26:29], v[186:189], v[66:69]
	v_mfma_f32_16x16x32_bf16 v[50:53], v[18:21], v[230:233], v[50:53]
	v_mfma_f32_16x16x32_bf16 v[42:45], v[26:29], v[230:233], v[42:45]
	v_mfma_f32_16x16x32_bf16 v[14:17], v[18:21], v[238:241], v[14:17]
	v_mfma_f32_16x16x32_bf16 v[10:13], v[26:29], v[238:241], v[10:13]
	v_mfma_f32_16x16x32_bf16 v[86:89], v[22:25], v[182:185], v[86:89]
	v_mfma_f32_16x16x32_bf16 v[82:85], v[30:33], v[182:185], v[82:85]
	v_mfma_f32_16x16x32_bf16 v[70:73], v[22:25], v[226:229], v[70:73]
	v_mfma_f32_16x16x32_bf16 v[66:69], v[30:33], v[226:229], v[66:69]
	v_mfma_f32_16x16x32_bf16 v[50:53], v[22:25], v[234:237], v[50:53]
	v_mfma_f32_16x16x32_bf16 v[42:45], v[30:33], v[234:237], v[42:45]
	v_mfma_f32_16x16x32_bf16 v[14:17], v[22:25], v[242:245], v[14:17]
	v_mfma_f32_16x16x32_bf16 v[10:13], v[30:33], v[242:245], v[10:13]
	v_mfma_f32_16x16x32_bf16 v[38:41], v[46:49], v[230:233], v[38:41]
	v_mfma_f32_16x16x32_bf16 v[34:37], v[170:173], v[230:233], v[34:37]
	v_mfma_f32_16x16x32_bf16 v[6:9], v[46:49], v[238:241], v[6:9]
	v_mfma_f32_16x16x32_bf16 v[2:5], v[170:173], v[238:241], v[2:5]
	v_mfma_f32_16x16x32_bf16 v[18:21], v[46:49], v[178:181], v[78:81]
	v_mfma_f32_16x16x32_bf16 v[22:25], v[170:173], v[178:181], v[74:77]
	v_mfma_f32_16x16x32_bf16 v[26:29], v[46:49], v[186:189], v[62:65]
	v_mfma_f32_16x16x32_bf16 v[30:33], v[170:173], v[186:189], v[58:61]
	v_mfma_f32_16x16x32_bf16 v[38:41], v[54:57], v[234:237], v[38:41]
	v_mfma_f32_16x16x32_bf16 v[34:37], v[174:177], v[234:237], v[34:37]
	v_mfma_f32_16x16x32_bf16 v[6:9], v[54:57], v[242:245], v[6:9]
	v_mfma_f32_16x16x32_bf16 v[2:5], v[174:177], v[242:245], v[2:5]
	v_mfma_f32_16x16x32_bf16 v[18:21], v[54:57], v[182:185], v[18:21]
	v_mfma_f32_16x16x32_bf16 v[22:25], v[174:177], v[182:185], v[22:25]
	v_mfma_f32_16x16x32_bf16 v[26:29], v[54:57], v[226:229], v[26:29]
	v_mfma_f32_16x16x32_bf16 v[30:33], v[174:177], v[226:229], v[30:33]
	s_barrier
; #define PG8_STAGE(bufoff, gbase, voff) do { _Pragma("unroll") for (int _i = 0; _i < 2; ++_i) \
;         __builtin_amdgcn_global_load_lds((const unsigned*)((const char*)(gbase) + (voff)[_i]), (PG8_LAS unsigned*)(lds + (bufoff) + ldsw + _i * 8192), 16, 0, 0); } while (0)
; #define PG8_LDA(dst, b, h) do { _Pragma("unroll") for (int m = 0; m < 4; ++m) _Pragma("unroll") for (int k = 0; k < 2; ++k) dst[m][k] = *(const PG8_LAS bf16x8*)(lds + PG8_SA(b, h) + aoff + m * 2048 + k * 1024); } while (0)
; #define PG8_LDB(dst, b, h) do { _Pragma("unroll") for (int n = 0; n < 2; ++n) _Pragma("unroll") for (int k = 0; k < 2; ++k) dst[n][k] = *(const PG8_LAS bf16x8*)(lds + PG8_SB(b, h) + boff + n * 2048 + k * 1024); } while (0)
; #define PG8_MMA(ai, bj, At, Bt) do { __builtin_amdgcn_s_setprio(1); _Pragma("unroll") for (int m = 0; m < 4; ++m) _Pragma("unroll") for (int n = 0; n < 2; ++n) _Pragma("unroll") for (int k = 0; k < 2; ++k) \
;         acc[ai][bj][m][n] = __builtin_amdgcn_mfma_f32_16x16x32_bf16(Bt[n][k], At[m][k], acc[ai][bj][m][n], 0, 0, 0); __builtin_amdgcn_s_setprio(0); } while (0)
; #define PG8_WAIT_V(n) asm volatile("s_waitcnt vmcnt(" #n ")" ::: "memory")
; #define PG8_WAIT_L(n) asm volatile("s_waitcnt lgkmcnt(" #n ")" ::: "memory")
; #define PG8_BAR __builtin_amdgcn_s_barrier()
; template <class Epi, class Sched, bool ALIGN_EPI = false, bool SP2 = false>
; __device__ __forceinline__ void gemm_phase(PG8_LAS unsigned char* lds, const Gemm g, const Sched& S, const Epi& E) {
;     ...
;         for (int t = 0; t < nt; t += 2) {
;             const bool last = (t == nt - 2);
;             const char* a1 = cA + (size_t)(t + 1) * kstep;
;             const char* a2 = last ? nA : cA + (size_t)(t + 2) * kstep; const char* b2 = last ? nB : cB + (size_t)(t + 2) * kstep;
;             const char* a3 = a2 + kstep; const char* b3 = b2 + kstep;
;     ...
;             PG8_LDB(B0, 1, 0); PG8_LDB(B1, 1, 1); PG8_SCHED; PG8_LDA(At, 1, 0); PG8_STAGE(PG8_SA(0, 1), a2 + hstep, voffA);
;             PG8_WAIT_V(8); PG8_WAIT_L(0); PG8_BAR; PG8_MMA(0, 0, At, B0); PG8_MMA(0, 1, At, B1); PG8_BAR; PG8_SCHED;
;             PG8_LDA(At, 1, 1); PG8_STAGE(PG8_SB(1, 0), b3, voffB); PG8_STAGE(PG8_SB(1, 1), b3 + hstep, voffB); PG8_STAGE(PG8_SA(1, 0), a3, voffA);
;             PG8_WAIT_V(8); PG8_WAIT_L(0); PG8_BAR; PG8_MMA(1, 0, At, B0); PG8_MMA(1, 1, At, B1); PG8_BAR; PG8_SCHED;
	s_add_i32 s30, 0, 0x18000
	v_add_u32_e32 v0, s30, v204
	s_add_i32 s31, 0, 0x1c000
	ds_read_b128 v[46:49], v0
	ds_read_b128 v[54:57], v0 offset:1024
	ds_read_b128 v[58:61], v0 offset:2048
	ds_read_b128 v[62:65], v0 offset:3072
	v_add_u32_e32 v0, s31, v204
	ds_read_b128 v[170:173], v0
	ds_read_b128 v[174:177], v0 offset:1024
	ds_read_b128 v[178:181], v0 offset:2048
	ds_read_b128 v[182:185], v0 offset:3072
	s_add_u32 s14, s14, 0x40000
	s_addc_u32 s15, s15, 0
	s_mov_b32 m0, s62
	v_lshl_add_u64 v[246:247], s[14:15], 0, v[154:155]
	ds_read_b128 v[74:77], v225 offset:32768
	ds_read_b128 v[78:81], v225 offset:33792
	ds_read_b128 v[186:189], v225 offset:34816
	ds_read_b128 v[226:229], v225 offset:35840
	ds_read_b128 v[230:233], v225 offset:36864
	ds_read_b128 v[234:237], v225 offset:37888
	ds_read_b128 v[238:241], v225 offset:38912
	ds_read_b128 v[242:245], v225 offset:39936
	global_load_lds_dwordx4 v[246:247], off
	v_lshl_add_u64 v[246:247], s[14:15], 0, v[158:159]
	s_mov_b32 m0, s63
	s_nop 0
	global_load_lds_dwordx4 v[246:247], off
	s_waitcnt vmcnt(8)
	s_waitcnt lgkmcnt(0)
	s_barrier
	s_waitcnt lgkmcnt(0)
	v_mfma_f32_16x16x32_bf16 v[150:153], v[46:49], v[74:77], v[150:153]
	v_mfma_f32_16x16x32_bf16 v[146:149], v[58:61], v[74:77], v[146:149]
	v_mfma_f32_16x16x32_bf16 v[134:137], v[46:49], v[186:189], v[134:137]
	v_mfma_f32_16x16x32_bf16 v[130:133], v[58:61], v[186:189], v[130:133]
	v_mfma_f32_16x16x32_bf16 v[118:121], v[46:49], v[230:233], v[118:121]
	v_mfma_f32_16x16x32_bf16 v[114:117], v[58:61], v[230:233], v[114:117]
	v_mfma_f32_16x16x32_bf16 v[102:105], v[46:49], v[238:241], v[102:105]
	v_mfma_f32_16x16x32_bf16 v[98:101], v[58:61], v[238:241], v[98:101]
	v_mfma_f32_16x16x32_bf16 v[150:153], v[54:57], v[78:81], v[150:153]
	v_mfma_f32_16x16x32_bf16 v[146:149], v[62:65], v[78:81], v[146:149]
	v_mfma_f32_16x16x32_bf16 v[134:137], v[54:57], v[226:229], v[134:137]
	v_mfma_f32_16x16x32_bf16 v[130:133], v[62:65], v[226:229], v[130:133]
	v_mfma_f32_16x16x32_bf16 v[118:121], v[54:57], v[234:237], v[118:121]
	v_mfma_f32_16x16x32_bf16 v[114:117], v[62:65], v[234:237], v[114:117]
	v_mfma_f32_16x16x32_bf16 v[102:105], v[54:57], v[242:245], v[102:105]
	v_mfma_f32_16x16x32_bf16 v[98:101], v[62:65], v[242:245], v[98:101]
	v_mfma_f32_16x16x32_bf16 v[142:145], v[170:173], v[74:77], v[142:145]
	v_mfma_f32_16x16x32_bf16 v[74:77], v[178:181], v[74:77], v[138:141]
	v_mfma_f32_16x16x32_bf16 v[138:141], v[182:185], v[78:81], v[74:77]
	v_mfma_f32_16x16x32_bf16 v[74:77], v[170:173], v[186:189], v[126:129]
	v_mfma_f32_16x16x32_bf16 v[126:129], v[174:177], v[226:229], v[74:77]
	v_mfma_f32_16x16x32_bf16 v[74:77], v[178:181], v[186:189], v[122:125]
	v_mfma_f32_16x16x32_bf16 v[122:125], v[182:185], v[226:229], v[74:77]
	v_mfma_f32_16x16x32_bf16 v[74:77], v[170:173], v[230:233], v[110:113]
	v_mfma_f32_16x16x32_bf16 v[110:113], v[174:177], v[234:237], v[74:77]
	v_mfma_f32_16x16x32_bf16 v[74:77], v[178:181], v[230:233], v[106:109]
	v_mfma_f32_16x16x32_bf16 v[106:109], v[182:185], v[234:237], v[74:77]
	v_mfma_f32_16x16x32_bf16 v[74:77], v[170:173], v[238:241], v[94:97]
	v_mfma_f32_16x16x32_bf16 v[94:97], v[174:177], v[242:245], v[74:77]
	v_mfma_f32_16x16x32_bf16 v[74:77], v[178:181], v[238:241], v[90:93]
	v_mfma_f32_16x16x32_bf16 v[142:145], v[174:177], v[78:81], v[142:145]
	v_mfma_f32_16x16x32_bf16 v[90:93], v[182:185], v[242:245], v[74:77]
	s_barrier
	s_add_i32 s14, s30, s20
	v_lshl_add_u64 v[78:79], v[190:191], 0, s[0:1]
	s_mov_b32 m0, s14
	s_nop 0
	ds_read_b128 v[74:77], v225 offset:49152
	ds_read_b128 v[186:189], v225 offset:50176
	ds_read_b128 v[226:229], v225 offset:51200
	ds_read_b128 v[230:233], v225 offset:52224
	ds_read_b128 v[234:237], v225 offset:53248
	ds_read_b128 v[238:241], v225 offset:54272
	ds_read_b128 v[242:245], v225 offset:55296
	ds_read_b128 v[246:249], v225 offset:56320
	global_load_lds_dwordx4 v[78:79], off
	s_add_i32 m0, s14, 0x2000
	s_add_u32 s10, s10, 0x40080
	v_lshl_add_u64 v[78:79], v[198:199], 0, s[0:1]
	s_addc_u32 s11, s11, 0
	s_add_i32 s14, s31, s20
	global_load_lds_dwordx4 v[78:79], off
	v_lshl_add_u64 v[78:79], s[10:11], 0, v[156:157]
	s_mov_b32 m0, s14
	s_nop 0
	global_load_lds_dwordx4 v[78:79], off
	v_lshl_add_u64 v[78:79], s[10:11], 0, v[160:161]
	s_add_i32 m0, s14, 0x2000
	s_nop 0
	global_load_lds_dwordx4 v[78:79], off
	v_lshl_add_u64 v[78:79], v[200:201], 0, s[0:1]
	s_mov_b32 m0, s64
	s_nop 0
	global_load_lds_dwordx4 v[78:79], off
	v_lshl_add_u64 v[78:79], v[250:251], 0, s[0:1]
	s_mov_b32 m0, s65
	s_nop 0
	global_load_lds_dwordx4 v[78:79], off
	s_waitcnt vmcnt(8)
	s_waitcnt lgkmcnt(0)
	s_barrier
	s_waitcnt lgkmcnt(0)
	v_mfma_f32_16x16x32_bf16 v[78:81], v[46:49], v[74:77], v[86:89]
	v_mfma_f32_16x16x32_bf16 v[86:89], v[54:57], v[186:189], v[78:81]
	v_mfma_f32_16x16x32_bf16 v[78:81], v[58:61], v[74:77], v[82:85]
	v_mfma_f32_16x16x32_bf16 v[70:73], v[46:49], v[226:229], v[70:73]
	v_mfma_f32_16x16x32_bf16 v[66:69], v[58:61], v[226:229], v[66:69]
	v_mfma_f32_16x16x32_bf16 v[50:53], v[46:49], v[234:237], v[50:53]
	v_mfma_f32_16x16x32_bf16 v[42:45], v[58:61], v[234:237], v[42:45]
	v_mfma_f32_16x16x32_bf16 v[14:17], v[46:49], v[242:245], v[14:17]
	v_mfma_f32_16x16x32_bf16 v[10:13], v[58:61], v[242:245], v[10:13]
	v_mfma_f32_16x16x32_bf16 v[82:85], v[62:65], v[186:189], v[78:81]
	v_mfma_f32_16x16x32_bf16 v[70:73], v[54:57], v[230:233], v[70:73]
	v_mfma_f32_16x16x32_bf16 v[66:69], v[62:65], v[230:233], v[66:69]
	v_mfma_f32_16x16x32_bf16 v[50:53], v[54:57], v[238:241], v[50:53]
	v_mfma_f32_16x16x32_bf16 v[42:45], v[62:65], v[238:241], v[42:45]
	v_mfma_f32_16x16x32_bf16 v[14:17], v[54:57], v[246:249], v[14:17]
	v_mfma_f32_16x16x32_bf16 v[10:13], v[62:65], v[246:249], v[10:13]
	v_mfma_f32_16x16x32_bf16 v[18:21], v[170:173], v[74:77], v[18:21]
	v_mfma_f32_16x16x32_bf16 v[78:81], v[174:177], v[186:189], v[18:21]
	v_mfma_f32_16x16x32_bf16 v[18:21], v[178:181], v[74:77], v[22:25]
	v_mfma_f32_16x16x32_bf16 v[74:77], v[182:185], v[186:189], v[18:21]
	v_mfma_f32_16x16x32_bf16 v[18:21], v[170:173], v[226:229], v[26:29]
	v_mfma_f32_16x16x32_bf16 v[62:65], v[174:177], v[230:233], v[18:21]
	v_mfma_f32_16x16x32_bf16 v[18:21], v[178:181], v[226:229], v[30:33]
	v_mfma_f32_16x16x32_bf16 v[58:61], v[182:185], v[230:233], v[18:21]
	v_mfma_f32_16x16x32_bf16 v[18:21], v[170:173], v[234:237], v[38:41]
	v_mfma_f32_16x16x32_bf16 v[38:41], v[174:177], v[238:241], v[18:21]
	v_mfma_f32_16x16x32_bf16 v[18:21], v[178:181], v[234:237], v[34:37]
	v_mfma_f32_16x16x32_bf16 v[6:9], v[170:173], v[242:245], v[6:9]
	v_mfma_f32_16x16x32_bf16 v[2:5], v[178:181], v[242:245], v[2:5]
	v_mfma_f32_16x16x32_bf16 v[34:37], v[182:185], v[238:241], v[18:21]
	v_mfma_f32_16x16x32_bf16 v[6:9], v[174:177], v[246:249], v[6:9]
	v_mfma_f32_16x16x32_bf16 v[2:5], v[182:185], v[246:249], v[2:5]
	s_barrier
	s_add_i32 s43, s43, 2
	s_add_u32 s8, s8, 0x100
	s_addc_u32 s9, s9, 0
	s_add_u32 s41, s41, 0x100
	s_addc_u32 s42, s42, 0
	s_cmp_gt_u32 s43, 13
	s_cbranch_scc0 .LBB0_188

; #define PG8_STAGE(bufoff, gbase, voff) do { _Pragma("unroll") for (int _i = 0; _i < 2; ++_i) \
;         __builtin_amdgcn_global_load_lds((const unsigned*)((const char*)(gbase) + (voff)[_i]), (PG8_LAS unsigned*)(lds + (bufoff) + ldsw + _i * 8192), 16, 0, 0); } while (0)
; #define PG8_LDA(dst, b, h) do { _Pragma("unroll") for (int m = 0; m < 4; ++m) _Pragma("unroll") for (int k = 0; k < 2; ++k) dst[m][k] = *(const PG8_LAS bf16x8*)(lds + PG8_SA(b, h) + aoff + m * 2048 + k * 1024); } while (0)
; #define PG8_LDB(dst, b, h) do { _Pragma("unroll") for (int n = 0; n < 2; ++n) _Pragma("unroll") for (int k = 0; k < 2; ++k) dst[n][k] = *(const PG8_LAS bf16x8*)(lds + PG8_SB(b, h) + boff + n * 2048 + k * 1024); } while (0)
; #define PG8_MMA(ai, bj, At, Bt) do { __builtin_amdgcn_s_setprio(1); _Pragma("unroll") for (int m = 0; m < 4; ++m) _Pragma("unroll") for (int n = 0; n < 2; ++n) _Pragma("unroll") for (int k = 0; k < 2; ++k) \
;         acc[ai][bj][m][n] = __builtin_amdgcn_mfma_f32_16x16x32_bf16(Bt[n][k], At[m][k], acc[ai][bj][m][n], 0, 0, 0); __builtin_amdgcn_s_setprio(0); } while (0)
; #define PG8_WAIT_V(n) asm volatile("s_waitcnt vmcnt(" #n ")" ::: "memory")
; #define PG8_WAIT_L(n) asm volatile("s_waitcnt lgkmcnt(" #n ")" ::: "memory")
; #define PG8_BAR __builtin_amdgcn_s_barrier()
; #define PG8_SCHED __builtin_amdgcn_sched_barrier(0)
; template <class Epi, class Sched, bool ALIGN_EPI = false, bool SP2 = false>
; __device__ __forceinline__ void gemm_phase(PG8_LAS unsigned char* lds, const Gemm g, const Sched& S, const Epi& E) {
;     ...
;         for (int t = 0; t < nt; t += 2) {
;             const bool last = (t == nt - 2);
;             const char* a1 = cA + (size_t)(t + 1) * kstep;
;             const char* a2 = last ? nA : cA + (size_t)(t + 2) * kstep; const char* b2 = last ? nB : cB + (size_t)(t + 2) * kstep;
;             const char* a3 = a2 + kstep; const char* b3 = b2 + kstep;
;             if (last && has_next) S.a_ready(nxt);
;             if constexpr (SP2) {
;             PG8_LDB(B0, 0, 0); PG8_LDB(B1, 0, 1); PG8_SCHED; PG8_LDA(At, 0, 0); PG8_STAGE(PG8_SA(1, 1), a1 + hstep, voffA);
;             PG8_WAIT_V(8); PG8_WAIT_L(0); PG8_BAR; PG8_MMA(0, 0, At, B0); PG8_MMA(0, 1, At, B1); PG8_BAR; PG8_SCHED;
;             PG8_LDA(At, 0, 1); PG8_STAGE(PG8_SB(0, 0), b2, voffB); PG8_STAGE(PG8_SB(0, 1), b2 + hstep, voffB); PG8_STAGE(PG8_SA(0, 0), a2, voffA);
.Lpeel_p3:
	s_add_u32 s30, s44, 0xfffc0080
	s_addc_u32 s31, s45, -1
	s_add_i32 s62, 0, 0x10000
	s_cmp_eq_u32 s61, 12
	s_cselect_b32 s49, s15, s31
	s_cselect_b32 s48, s34, s30
	s_cselect_b32 s47, s11, s60
	s_cselect_b32 s46, s35, s59
	s_add_i32 s63, 0, 0x14000
	v_add_u32_e32 v134, s62, v185
	v_add_u32_e32 v168, s63, v185
	ds_read_b128 v[114:117], v134
	ds_read_b128 v[118:121], v134 offset:1024
	ds_read_b128 v[126:129], v134 offset:2048
	ds_read_b128 v[134:137], v134 offset:3072
	ds_read_b128 v[146:149], v168
	ds_read_b128 v[150:153], v168 offset:1024
	ds_read_b128 v[164:167], v168 offset:2048
	ds_read_b128 v[168:171], v168 offset:3072
	v_lshl_add_u64 v[210:211], s[44:45], 0, v[160:161]
	s_add_i32 m0, s50, 0xc000
	ds_read_b128 v[172:175], v187
	ds_read_b128 v[176:179], v187 offset:1024
	ds_read_b128 v[180:183], v187 offset:2048
	ds_read_b128 v[188:191], v187 offset:3072
	ds_read_b128 v[198:201], v187 offset:4096
	ds_read_b128 v[202:205], v187 offset:5120
	ds_read_b128 v[206:209], v187 offset:6144
	ds_read_b128 v[222:225], v187 offset:7168
	global_load_lds_dwordx4 v[210:211], off
	v_lshl_add_u64 v[210:211], s[44:45], 0, v[162:163]
	s_add_i32 m0, s50, 0xe000
	s_nop 0
	global_load_lds_dwordx4 v[210:211], off
	s_waitcnt vmcnt(8)
	s_waitcnt lgkmcnt(0)
	s_barrier
	s_waitcnt lgkmcnt(0)
	v_mfma_f32_16x16x32_bf16 v[142:145], v[114:117], v[172:175], 0
	v_mfma_f32_16x16x32_bf16 v[138:141], v[126:129], v[172:175], 0
	v_mfma_f32_16x16x32_bf16 v[110:113], v[114:117], v[180:183], 0
	v_mfma_f32_16x16x32_bf16 v[106:109], v[126:129], v[180:183], 0
	v_mfma_f32_16x16x32_bf16 v[94:97], v[114:117], v[198:201], 0
	v_mfma_f32_16x16x32_bf16 v[90:93], v[126:129], v[198:201], 0
	v_mfma_f32_16x16x32_bf16 v[78:81], v[114:117], v[206:209], 0
	v_mfma_f32_16x16x32_bf16 v[74:77], v[126:129], v[206:209], 0
	v_mfma_f32_16x16x32_bf16 v[142:145], v[118:121], v[176:179], v[142:145]
	v_mfma_f32_16x16x32_bf16 v[138:141], v[134:137], v[176:179], v[138:141]
	v_mfma_f32_16x16x32_bf16 v[110:113], v[118:121], v[188:191], v[110:113]
	v_mfma_f32_16x16x32_bf16 v[106:109], v[134:137], v[188:191], v[106:109]
	v_mfma_f32_16x16x32_bf16 v[94:97], v[118:121], v[202:205], v[94:97]
	v_mfma_f32_16x16x32_bf16 v[90:93], v[134:137], v[202:205], v[90:93]
	v_mfma_f32_16x16x32_bf16 v[78:81], v[118:121], v[222:225], v[78:81]
	v_mfma_f32_16x16x32_bf16 v[74:77], v[134:137], v[222:225], v[74:77]
	v_mfma_f32_16x16x32_bf16 v[130:133], v[146:149], v[172:175], 0
	v_mfma_f32_16x16x32_bf16 v[122:125], v[164:167], v[172:175], 0
	v_mfma_f32_16x16x32_bf16 v[102:105], v[146:149], v[180:183], 0
	v_mfma_f32_16x16x32_bf16 v[98:101], v[164:167], v[180:183], 0
	v_mfma_f32_16x16x32_bf16 v[86:89], v[146:149], v[198:201], 0
	v_mfma_f32_16x16x32_bf16 v[82:85], v[164:167], v[198:201], 0
	v_mfma_f32_16x16x32_bf16 v[70:73], v[146:149], v[206:209], 0
	v_mfma_f32_16x16x32_bf16 v[66:69], v[164:167], v[206:209], 0
	v_mfma_f32_16x16x32_bf16 v[130:133], v[150:153], v[176:179], v[130:133]
	v_mfma_f32_16x16x32_bf16 v[122:125], v[168:171], v[176:179], v[122:125]
	v_mfma_f32_16x16x32_bf16 v[102:105], v[150:153], v[188:191], v[102:105]
	v_mfma_f32_16x16x32_bf16 v[98:101], v[168:171], v[188:191], v[98:101]
	v_mfma_f32_16x16x32_bf16 v[86:89], v[150:153], v[202:205], v[86:89]
	v_mfma_f32_16x16x32_bf16 v[82:85], v[168:171], v[202:205], v[82:85]
	v_mfma_f32_16x16x32_bf16 v[70:73], v[150:153], v[222:225], v[70:73]
	v_mfma_f32_16x16x32_bf16 v[66:69], v[168:171], v[222:225], v[66:69]
	s_barrier
	s_add_i32 s30, s62, s33
	v_lshl_add_u64 v[210:211], s[46:47], 0, v[0:1]
	s_mov_b32 m0, s30
	ds_read_b128 v[172:175], v187 offset:16384
	ds_read_b128 v[176:179], v187 offset:17408
	ds_read_b128 v[180:183], v187 offset:18432
	ds_read_b128 v[188:191], v187 offset:19456
	ds_read_b128 v[198:201], v187 offset:20480
	ds_read_b128 v[202:205], v187 offset:21504
	ds_read_b128 v[206:209], v187 offset:22528
	ds_read_b128 v[222:225], v187 offset:23552
	global_load_lds_dwordx4 v[210:211], off
	s_add_i32 m0, s30, 0x2000
	s_add_u32 s30, s46, 0x40000
	v_lshl_add_u64 v[226:227], s[46:47], 0, v[154:155]
	s_addc_u32 s31, s47, 0
	s_add_i32 s62, s63, s33
	global_load_lds_dwordx4 v[226:227], off
	v_lshl_add_u64 v[228:229], s[30:31], 0, v[0:1]
	s_mov_b32 m0, s62
	v_lshl_add_u64 v[230:231], s[48:49], 0, v[156:157]
	global_load_lds_dwordx4 v[228:229], off
	v_lshl_add_u64 v[228:229], s[30:31], 0, v[154:155]
	s_add_i32 m0, s62, 0x2000
	s_nop 0
	global_load_lds_dwordx4 v[228:229], off
	v_lshl_add_u64 v[228:229], s[48:49], 0, v[158:159]
	s_mov_b32 m0, s50
	s_nop 0
	global_load_lds_dwordx4 v[228:229], off
	s_mov_b32 m0, s51
	s_nop 0
	global_load_lds_dwordx4 v[230:231], off
	s_waitcnt vmcnt(8)
	s_waitcnt lgkmcnt(0)
	s_barrier
; #define PG8_STAGE(bufoff, gbase, voff) do { _Pragma("unroll") for (int _i = 0; _i < 2; ++_i) \
;         __builtin_amdgcn_global_load_lds((const unsigned*)((const char*)(gbase) + (voff)[_i]), (PG8_LAS unsigned*)(lds + (bufoff) + ldsw + _i * 8192), 16, 0, 0); } while (0)
; #define PG8_LDA(dst, b, h) do { _Pragma("unroll") for (int m = 0; m < 4; ++m) _Pragma("unroll") for (int k = 0; k < 2; ++k) dst[m][k] = *(const PG8_LAS bf16x8*)(lds + PG8_SA(b, h) + aoff + m * 2048 + k * 1024); } while (0)
; #define PG8_LDB(dst, b, h) do { _Pragma("unroll") for (int n = 0; n < 2; ++n) _Pragma("unroll") for (int k = 0; k < 2; ++k) dst[n][k] = *(const PG8_LAS bf16x8*)(lds + PG8_SB(b, h) + boff + n * 2048 + k * 1024); } while (0)
; #define PG8_MMA(ai, bj, At, Bt) do { __builtin_amdgcn_s_setprio(1); _Pragma("unroll") for (int m = 0; m < 4; ++m) _Pragma("unroll") for (int n = 0; n < 2; ++n) _Pragma("unroll") for (int k = 0; k < 2; ++k) \
;         acc[ai][bj][m][n] = __builtin_amdgcn_mfma_f32_16x16x32_bf16(Bt[n][k], At[m][k], acc[ai][bj][m][n], 0, 0, 0); __builtin_amdgcn_s_setprio(0); } while (0)
; #define PG8_WAIT_V(n) asm volatile("s_waitcnt vmcnt(" #n ")" ::: "memory")
; #define PG8_WAIT_L(n) asm volatile("s_waitcnt lgkmcnt(" #n ")" ::: "memory")
; #define PG8_BAR __builtin_amdgcn_s_barrier()
; #define PG8_SCHED __builtin_amdgcn_sched_barrier(0)
; template <class Epi, class Sched, bool ALIGN_EPI = false, bool SP2 = false>
; __device__ __forceinline__ void gemm_phase(PG8_LAS unsigned char* lds, const Gemm g, const Sched& S, const Epi& E) {
;     ...
;             PG8_WAIT_V(8); PG8_WAIT_L(0); PG8_BAR; PG8_MMA(1, 0, At, B0); PG8_MMA(1, 1, At, B1); PG8_BAR; PG8_SCHED;
;             PG8_LDB(B0, 1, 0); PG8_LDB(B1, 1, 1); PG8_SCHED; PG8_LDA(At, 1, 0); PG8_STAGE(PG8_SA(0, 1), a2 + hstep, voffA);
;             PG8_WAIT_V(8); PG8_WAIT_L(0); PG8_BAR; PG8_MMA(0, 0, At, B0); PG8_MMA(0, 1, At, B1); PG8_BAR; PG8_SCHED;
	s_waitcnt lgkmcnt(0)
	v_mfma_f32_16x16x32_bf16 v[62:65], v[114:117], v[172:175], 0
	v_mfma_f32_16x16x32_bf16 v[58:61], v[126:129], v[172:175], 0
	v_mfma_f32_16x16x32_bf16 v[46:49], v[114:117], v[180:183], 0
	v_mfma_f32_16x16x32_bf16 v[42:45], v[126:129], v[180:183], 0
	v_mfma_f32_16x16x32_bf16 v[30:33], v[114:117], v[198:201], 0
	v_mfma_f32_16x16x32_bf16 v[26:29], v[126:129], v[198:201], 0
	v_mfma_f32_16x16x32_bf16 v[14:17], v[114:117], v[206:209], 0
	v_mfma_f32_16x16x32_bf16 v[10:13], v[126:129], v[206:209], 0
	v_mfma_f32_16x16x32_bf16 v[62:65], v[118:121], v[176:179], v[62:65]
	v_mfma_f32_16x16x32_bf16 v[58:61], v[134:137], v[176:179], v[58:61]
	v_mfma_f32_16x16x32_bf16 v[46:49], v[118:121], v[188:191], v[46:49]
	v_mfma_f32_16x16x32_bf16 v[42:45], v[134:137], v[188:191], v[42:45]
	v_mfma_f32_16x16x32_bf16 v[30:33], v[118:121], v[202:205], v[30:33]
	v_mfma_f32_16x16x32_bf16 v[26:29], v[134:137], v[202:205], v[26:29]
	v_mfma_f32_16x16x32_bf16 v[14:17], v[118:121], v[222:225], v[14:17]
	v_mfma_f32_16x16x32_bf16 v[10:13], v[134:137], v[222:225], v[10:13]
	v_mfma_f32_16x16x32_bf16 v[54:57], v[146:149], v[172:175], 0
	v_mfma_f32_16x16x32_bf16 v[50:53], v[164:167], v[172:175], 0
	v_mfma_f32_16x16x32_bf16 v[38:41], v[146:149], v[180:183], 0
	v_mfma_f32_16x16x32_bf16 v[34:37], v[164:167], v[180:183], 0
	v_mfma_f32_16x16x32_bf16 v[22:25], v[146:149], v[198:201], 0
	v_mfma_f32_16x16x32_bf16 v[18:21], v[164:167], v[198:201], 0
	v_mfma_f32_16x16x32_bf16 v[6:9], v[146:149], v[206:209], 0
	v_mfma_f32_16x16x32_bf16 v[2:5], v[164:167], v[206:209], 0
	v_mfma_f32_16x16x32_bf16 v[54:57], v[150:153], v[176:179], v[54:57]
	v_mfma_f32_16x16x32_bf16 v[50:53], v[168:171], v[176:179], v[50:53]
	v_mfma_f32_16x16x32_bf16 v[38:41], v[150:153], v[188:191], v[38:41]
	v_mfma_f32_16x16x32_bf16 v[34:37], v[168:171], v[188:191], v[34:37]
	v_mfma_f32_16x16x32_bf16 v[22:25], v[150:153], v[202:205], v[22:25]
	v_mfma_f32_16x16x32_bf16 v[18:21], v[168:171], v[202:205], v[18:21]
	v_mfma_f32_16x16x32_bf16 v[6:9], v[150:153], v[222:225], v[6:9]
	v_mfma_f32_16x16x32_bf16 v[2:5], v[168:171], v[222:225], v[2:5]
	s_barrier
	s_add_i32 s62, 0, 0x18000
	s_add_i32 s63, 0, 0x1c000
	v_add_u32_e32 v134, s62, v185
	v_add_u32_e32 v168, s63, v185
	ds_read_b128 v[114:117], v134
	ds_read_b128 v[118:121], v134 offset:1024
	ds_read_b128 v[126:129], v134 offset:2048
	ds_read_b128 v[134:137], v134 offset:3072
	ds_read_b128 v[146:149], v168
	ds_read_b128 v[150:153], v168 offset:1024
	ds_read_b128 v[164:167], v168 offset:2048
	ds_read_b128 v[168:171], v168 offset:3072
	s_add_u32 s30, s48, 0x40000
	s_addc_u32 s31, s49, 0
	s_mov_b32 m0, s52
	v_lshl_add_u64 v[232:233], s[30:31], 0, v[158:159]
	ds_read_b128 v[172:175], v187 offset:32768
	ds_read_b128 v[176:179], v187 offset:33792
	ds_read_b128 v[180:183], v187 offset:34816
	ds_read_b128 v[188:191], v187 offset:35840
	ds_read_b128 v[198:201], v187 offset:36864
	ds_read_b128 v[202:205], v187 offset:37888
	ds_read_b128 v[206:209], v187 offset:38912
	ds_read_b128 v[222:225], v187 offset:39936
	global_load_lds_dwordx4 v[232:233], off
	v_lshl_add_u64 v[232:233], s[30:31], 0, v[156:157]
	s_mov_b32 m0, s53
	s_nop 0
	global_load_lds_dwordx4 v[232:233], off
	s_waitcnt vmcnt(8)
	s_waitcnt lgkmcnt(0)
	s_barrier
	s_waitcnt lgkmcnt(0)
	v_mfma_f32_16x16x32_bf16 v[142:145], v[114:117], v[172:175], v[142:145]
	v_mfma_f32_16x16x32_bf16 v[138:141], v[126:129], v[172:175], v[138:141]
	v_mfma_f32_16x16x32_bf16 v[110:113], v[114:117], v[180:183], v[110:113]
	v_mfma_f32_16x16x32_bf16 v[106:109], v[126:129], v[180:183], v[106:109]
	v_mfma_f32_16x16x32_bf16 v[94:97], v[114:117], v[198:201], v[94:97]
	v_mfma_f32_16x16x32_bf16 v[90:93], v[126:129], v[198:201], v[90:93]
	v_mfma_f32_16x16x32_bf16 v[78:81], v[114:117], v[206:209], v[78:81]
	v_mfma_f32_16x16x32_bf16 v[74:77], v[126:129], v[206:209], v[74:77]
	v_mfma_f32_16x16x32_bf16 v[142:145], v[118:121], v[176:179], v[142:145]
	v_mfma_f32_16x16x32_bf16 v[138:141], v[134:137], v[176:179], v[138:141]
	v_mfma_f32_16x16x32_bf16 v[110:113], v[118:121], v[188:191], v[110:113]
	v_mfma_f32_16x16x32_bf16 v[106:109], v[134:137], v[188:191], v[106:109]
	v_mfma_f32_16x16x32_bf16 v[94:97], v[118:121], v[202:205], v[94:97]
	v_mfma_f32_16x16x32_bf16 v[90:93], v[134:137], v[202:205], v[90:93]
	v_mfma_f32_16x16x32_bf16 v[78:81], v[118:121], v[222:225], v[78:81]
	v_mfma_f32_16x16x32_bf16 v[74:77], v[134:137], v[222:225], v[74:77]
	v_mfma_f32_16x16x32_bf16 v[130:133], v[146:149], v[172:175], v[130:133]
	v_mfma_f32_16x16x32_bf16 v[122:125], v[164:167], v[172:175], v[122:125]
	v_mfma_f32_16x16x32_bf16 v[102:105], v[146:149], v[180:183], v[102:105]
	v_mfma_f32_16x16x32_bf16 v[98:101], v[164:167], v[180:183], v[98:101]
	v_mfma_f32_16x16x32_bf16 v[86:89], v[146:149], v[198:201], v[86:89]
	v_mfma_f32_16x16x32_bf16 v[82:85], v[164:167], v[198:201], v[82:85]
	v_mfma_f32_16x16x32_bf16 v[70:73], v[146:149], v[206:209], v[70:73]
	v_mfma_f32_16x16x32_bf16 v[66:69], v[164:167], v[206:209], v[66:69]
	v_mfma_f32_16x16x32_bf16 v[130:133], v[150:153], v[176:179], v[130:133]
	v_mfma_f32_16x16x32_bf16 v[122:125], v[168:171], v[176:179], v[122:125]
	v_mfma_f32_16x16x32_bf16 v[102:105], v[150:153], v[188:191], v[102:105]
	v_mfma_f32_16x16x32_bf16 v[98:101], v[168:171], v[188:191], v[98:101]
	v_mfma_f32_16x16x32_bf16 v[86:89], v[150:153], v[202:205], v[86:89]
	v_mfma_f32_16x16x32_bf16 v[82:85], v[168:171], v[202:205], v[82:85]
	v_mfma_f32_16x16x32_bf16 v[70:73], v[150:153], v[222:225], v[70:73]
	v_mfma_f32_16x16x32_bf16 v[66:69], v[168:171], v[222:225], v[66:69]
	s_barrier
; #define PG8_STAGE(bufoff, gbase, voff) do { _Pragma("unroll") for (int _i = 0; _i < 2; ++_i) \
;         __builtin_amdgcn_global_load_lds((const unsigned*)((const char*)(gbase) + (voff)[_i]), (PG8_LAS unsigned*)(lds + (bufoff) + ldsw + _i * 8192), 16, 0, 0); } while (0)
; #define PG8_LDA(dst, b, h) do { _Pragma("unroll") for (int m = 0; m < 4; ++m) _Pragma("unroll") for (int k = 0; k < 2; ++k) dst[m][k] = *(const PG8_LAS bf16x8*)(lds + PG8_SA(b, h) + aoff + m * 2048 + k * 1024); } while (0)
; #define PG8_LDB(dst, b, h) do { _Pragma("unroll") for (int n = 0; n < 2; ++n) _Pragma("unroll") for (int k = 0; k < 2; ++k) dst[n][k] = *(const PG8_LAS bf16x8*)(lds + PG8_SB(b, h) + boff + n * 2048 + k * 1024); } while (0)
; template <class Epi, class Sched, bool ALIGN_EPI = false, bool SP2 = false>
; __device__ __forceinline__ void gemm_phase(PG8_LAS unsigned char* lds, const Gemm g, const Sched& S, const Epi& E) {
;     ...
;         for (int t = 0; t < nt; t += 2) {
;             const bool last = (t == nt - 2);
;             const char* a1 = cA + (size_t)(t + 1) * kstep;
;             const char* a2 = last ? nA : cA + (size_t)(t + 2) * kstep; const char* b2 = last ? nB : cB + (size_t)(t + 2) * kstep;
;             const char* a3 = a2 + kstep; const char* b3 = b2 + kstep;
;             if (last && has_next) S.a_ready(nxt);
;             if constexpr (SP2) {
;             PG8_LDB(B0, 0, 0); PG8_LDB(B1, 0, 1); PG8_SCHED; PG8_LDA(At, 0, 0); PG8_STAGE(PG8_SA(1, 1), a1 + hstep, voffA);
;             PG8_WAIT_V(8); PG8_WAIT_L(0); PG8_BAR; PG8_MMA(0, 0, At, B0); PG8_MMA(0, 1, At, B1); PG8_BAR; PG8_SCHED;
;             PG8_LDA(At, 0, 1); PG8_STAGE(PG8_SB(0, 0), b2, voffB); PG8_STAGE(PG8_SB(0, 1), b2 + hstep, voffB); PG8_STAGE(PG8_SA(0, 0), a2, voffA);
;             PG8_WAIT_V(8); PG8_WAIT_L(0); PG8_BAR; PG8_MMA(1, 0, At, B0); PG8_MMA(1, 1, At, B1); PG8_BAR; PG8_SCHED;
;             PG8_LDB(B0, 1, 0); PG8_LDB(B1, 1, 1); PG8_SCHED; PG8_LDA(At, 1, 0); PG8_STAGE(PG8_SA(0, 1), a2 + hstep, voffA);
;             PG8_WAIT_V(8); PG8_WAIT_L(0); PG8_BAR; PG8_MMA(0, 0, At, B0); PG8_MMA(0, 1, At, B1); PG8_BAR; PG8_SCHED;
;             PG8_LDA(At, 1, 1); PG8_STAGE(PG8_SB(1, 0), b3, voffB); PG8_STAGE(PG8_SB(1, 1), b3 + hstep, voffB); PG8_STAGE(PG8_SA(1, 0), a3, voffA);
;             PG8_WAIT_V(8); PG8_WAIT_L(0); PG8_BAR; PG8_MMA(1, 0, At, B0); PG8_MMA(1, 1, At, B1); PG8_BAR; PG8_SCHED;
	s_add_i32 s30, s62, s33
	v_lshl_add_u64 v[210:211], v[210:211], 0, s[0:1]
	s_mov_b32 m0, s30
	ds_read_b128 v[172:175], v187 offset:49152
	ds_read_b128 v[176:179], v187 offset:50176
	ds_read_b128 v[180:183], v187 offset:51200
	ds_read_b128 v[188:191], v187 offset:52224
	ds_read_b128 v[198:201], v187 offset:53248
	ds_read_b128 v[202:205], v187 offset:54272
	ds_read_b128 v[206:209], v187 offset:55296
	ds_read_b128 v[222:225], v187 offset:56320
	global_load_lds_dwordx4 v[210:211], off
	s_add_i32 m0, s30, 0x2000
	s_add_u32 s30, s46, 0x40080
	v_lshl_add_u64 v[210:211], v[226:227], 0, s[0:1]
	s_addc_u32 s31, s47, 0
	s_add_i32 s46, s63, s33
	global_load_lds_dwordx4 v[210:211], off
	v_lshl_add_u64 v[210:211], s[30:31], 0, v[0:1]
	s_mov_b32 m0, s46
	s_nop 0
	global_load_lds_dwordx4 v[210:211], off
	v_lshl_add_u64 v[210:211], s[30:31], 0, v[154:155]
	s_add_i32 m0, s46, 0x2000
	s_nop 0
	global_load_lds_dwordx4 v[210:211], off
	v_lshl_add_u64 v[210:211], v[228:229], 0, s[0:1]
	s_mov_b32 m0, s56
	s_nop 0
	global_load_lds_dwordx4 v[210:211], off
	v_lshl_add_u64 v[210:211], v[230:231], 0, s[0:1]
	s_mov_b32 m0, s57
	s_nop 0
	global_load_lds_dwordx4 v[210:211], off
	s_waitcnt vmcnt(8)
	s_waitcnt lgkmcnt(0)
	s_barrier
	s_waitcnt lgkmcnt(0)
	v_mfma_f32_16x16x32_bf16 v[62:65], v[114:117], v[172:175], v[62:65]
	v_mfma_f32_16x16x32_bf16 v[58:61], v[126:129], v[172:175], v[58:61]
	v_mfma_f32_16x16x32_bf16 v[46:49], v[114:117], v[180:183], v[46:49]
	v_mfma_f32_16x16x32_bf16 v[42:45], v[126:129], v[180:183], v[42:45]
	v_mfma_f32_16x16x32_bf16 v[30:33], v[114:117], v[198:201], v[30:33]
	v_mfma_f32_16x16x32_bf16 v[26:29], v[126:129], v[198:201], v[26:29]
	v_mfma_f32_16x16x32_bf16 v[14:17], v[114:117], v[206:209], v[14:17]
	v_mfma_f32_16x16x32_bf16 v[10:13], v[126:129], v[206:209], v[10:13]
	v_mfma_f32_16x16x32_bf16 v[62:65], v[118:121], v[176:179], v[62:65]
	v_mfma_f32_16x16x32_bf16 v[58:61], v[134:137], v[176:179], v[58:61]
	v_mfma_f32_16x16x32_bf16 v[46:49], v[118:121], v[188:191], v[46:49]
	v_mfma_f32_16x16x32_bf16 v[42:45], v[134:137], v[188:191], v[42:45]
	v_mfma_f32_16x16x32_bf16 v[30:33], v[118:121], v[202:205], v[30:33]
	v_mfma_f32_16x16x32_bf16 v[26:29], v[134:137], v[202:205], v[26:29]
	v_mfma_f32_16x16x32_bf16 v[14:17], v[118:121], v[222:225], v[14:17]
	v_mfma_f32_16x16x32_bf16 v[10:13], v[134:137], v[222:225], v[10:13]
	v_mfma_f32_16x16x32_bf16 v[54:57], v[146:149], v[172:175], v[54:57]
	v_mfma_f32_16x16x32_bf16 v[50:53], v[164:167], v[172:175], v[50:53]
	v_mfma_f32_16x16x32_bf16 v[38:41], v[146:149], v[180:183], v[38:41]
	v_mfma_f32_16x16x32_bf16 v[34:37], v[164:167], v[180:183], v[34:37]
	v_mfma_f32_16x16x32_bf16 v[22:25], v[146:149], v[198:201], v[22:25]
	v_mfma_f32_16x16x32_bf16 v[18:21], v[164:167], v[198:201], v[18:21]
	v_mfma_f32_16x16x32_bf16 v[6:9], v[146:149], v[206:209], v[6:9]
	v_mfma_f32_16x16x32_bf16 v[2:5], v[164:167], v[206:209], v[2:5]
	v_mfma_f32_16x16x32_bf16 v[54:57], v[150:153], v[176:179], v[54:57]
	v_mfma_f32_16x16x32_bf16 v[50:53], v[168:171], v[176:179], v[50:53]
	v_mfma_f32_16x16x32_bf16 v[38:41], v[150:153], v[188:191], v[38:41]
	v_mfma_f32_16x16x32_bf16 v[34:37], v[168:171], v[188:191], v[34:37]
	v_mfma_f32_16x16x32_bf16 v[22:25], v[150:153], v[202:205], v[22:25]
	v_mfma_f32_16x16x32_bf16 v[18:21], v[168:171], v[202:205], v[18:21]
	v_mfma_f32_16x16x32_bf16 v[6:9], v[150:153], v[222:225], v[6:9]
	v_mfma_f32_16x16x32_bf16 v[2:5], v[168:171], v[222:225], v[2:5]
	s_barrier
	s_add_i32 s61, s61, 2
	s_add_u32 s44, s44, 0x100
	s_addc_u32 s45, s45, 0
	s_add_u32 s59, s59, 0x100
	s_addc_u32 s60, s60, 0
	s_cmp_gt_u32 s61, 13
	s_cbranch_scc0 .LBB0_676
	s_branch .Lpeel_exit_p3
.LBB0_676:
	s_add_u32 s30, s44, 0xfffc0080
	s_addc_u32 s31, s45, -1
	s_add_i32 s62, 0, 0x10000
	s_cmp_eq_u32 s61, 12
	s_cselect_b32 s49, s15, s31
	s_cselect_b32 s48, s34, s30
	s_cselect_b32 s47, s11, s60
	s_cselect_b32 s46, s35, s59
	s_add_i32 s63, 0, 0x14000
	v_add_u32_e32 v134, s62, v185
	v_add_u32_e32 v168, s63, v185
	ds_read_b128 v[114:117], v134
	ds_read_b128 v[118:121], v134 offset:1024
	ds_read_b128 v[126:129], v134 offset:2048
	ds_read_b128 v[134:137], v134 offset:3072
	ds_read_b128 v[146:149], v168
	ds_read_b128 v[150:153], v168 offset:1024
	ds_read_b128 v[164:167], v168 offset:2048
	ds_read_b128 v[168:171], v168 offset:3072
	v_lshl_add_u64 v[210:211], s[44:45], 0, v[160:161]
	s_add_i32 m0, s50, 0xc000
	ds_read_b128 v[172:175], v187
	ds_read_b128 v[176:179], v187 offset:1024
	ds_read_b128 v[180:183], v187 offset:2048
	ds_read_b128 v[188:191], v187 offset:3072
	ds_read_b128 v[198:201], v187 offset:4096
	ds_read_b128 v[202:205], v187 offset:5120
	ds_read_b128 v[206:209], v187 offset:6144
	ds_read_b128 v[222:225], v187 offset:7168
	global_load_lds_dwordx4 v[210:211], off
	v_lshl_add_u64 v[210:211], s[44:45], 0, v[162:163]
	s_add_i32 m0, s50, 0xe000
	s_nop 0
	global_load_lds_dwordx4 v[210:211], off
	s_waitcnt vmcnt(8)
	s_waitcnt lgkmcnt(0)
	s_barrier
; #define PG8_STAGE(bufoff, gbase, voff) do { _Pragma("unroll") for (int _i = 0; _i < 2; ++_i) \
;         __builtin_amdgcn_global_load_lds((const unsigned*)((const char*)(gbase) + (voff)[_i]), (PG8_LAS unsigned*)(lds + (bufoff) + ldsw + _i * 8192), 16, 0, 0); } while (0)
; #define PG8_LDA(dst, b, h) do { _Pragma("unroll") for (int m = 0; m < 4; ++m) _Pragma("unroll") for (int k = 0; k < 2; ++k) dst[m][k] = *(const PG8_LAS bf16x8*)(lds + PG8_SA(b, h) + aoff + m * 2048 + k * 1024); } while (0)
; #define PG8_LDB(dst, b, h) do { _Pragma("unroll") for (int n = 0; n < 2; ++n) _Pragma("unroll") for (int k = 0; k < 2; ++k) dst[n][k] = *(const PG8_LAS bf16x8*)(lds + PG8_SB(b, h) + boff + n * 2048 + k * 1024); } while (0)
; #define PG8_MMA(ai, bj, At, Bt) do { __builtin_amdgcn_s_setprio(1); _Pragma("unroll") for (int m = 0; m < 4; ++m) _Pragma("unroll") for (int n = 0; n < 2; ++n) _Pragma("unroll") for (int k = 0; k < 2; ++k) \
;         acc[ai][bj][m][n] = __builtin_amdgcn_mfma_f32_16x16x32_bf16(Bt[n][k], At[m][k], acc[ai][bj][m][n], 0, 0, 0); __builtin_amdgcn_s_setprio(0); } while (0)
; #define PG8_WAIT_V(n) asm volatile("s_waitcnt vmcnt(" #n ")" ::: "memory")
; #define PG8_WAIT_L(n) asm volatile("s_waitcnt lgkmcnt(" #n ")" ::: "memory")
; #define PG8_BAR __builtin_amdgcn_s_barrier()
; #define PG8_SCHED __builtin_amdgcn_sched_barrier(0)
; template <class Epi, class Sched, bool ALIGN_EPI = false, bool SP2 = false>
; __device__ __forceinline__ void gemm_phase(PG8_LAS unsigned char* lds, const Gemm g, const Sched& S, const Epi& E) {
;     ...
;             PG8_LDB(B0, 0, 0); PG8_LDB(B1, 0, 1); PG8_SCHED; PG8_LDA(At, 0, 0); PG8_STAGE(PG8_SA(1, 1), a1 + hstep, voffA);
;             PG8_WAIT_V(8); PG8_WAIT_L(0); PG8_BAR; PG8_MMA(0, 0, At, B0); PG8_MMA(0, 1, At, B1); PG8_BAR; PG8_SCHED;
;             PG8_LDA(At, 0, 1); PG8_STAGE(PG8_SB(0, 0), b2, voffB); PG8_STAGE(PG8_SB(0, 1), b2 + hstep, voffB); PG8_STAGE(PG8_SA(0, 0), a2, voffA);
;             PG8_WAIT_V(8); PG8_WAIT_L(0); PG8_BAR; PG8_MMA(1, 0, At, B0); PG8_MMA(1, 1, At, B1); PG8_BAR; PG8_SCHED;
	s_waitcnt lgkmcnt(0)
	v_mfma_f32_16x16x32_bf16 v[142:145], v[114:117], v[172:175], v[142:145]
	v_mfma_f32_16x16x32_bf16 v[138:141], v[126:129], v[172:175], v[138:141]
	v_mfma_f32_16x16x32_bf16 v[110:113], v[114:117], v[180:183], v[110:113]
	v_mfma_f32_16x16x32_bf16 v[106:109], v[126:129], v[180:183], v[106:109]
	v_mfma_f32_16x16x32_bf16 v[94:97], v[114:117], v[198:201], v[94:97]
	v_mfma_f32_16x16x32_bf16 v[90:93], v[126:129], v[198:201], v[90:93]
	v_mfma_f32_16x16x32_bf16 v[78:81], v[114:117], v[206:209], v[78:81]
	v_mfma_f32_16x16x32_bf16 v[74:77], v[126:129], v[206:209], v[74:77]
	v_mfma_f32_16x16x32_bf16 v[142:145], v[118:121], v[176:179], v[142:145]
	v_mfma_f32_16x16x32_bf16 v[138:141], v[134:137], v[176:179], v[138:141]
	v_mfma_f32_16x16x32_bf16 v[110:113], v[118:121], v[188:191], v[110:113]
	v_mfma_f32_16x16x32_bf16 v[106:109], v[134:137], v[188:191], v[106:109]
	v_mfma_f32_16x16x32_bf16 v[94:97], v[118:121], v[202:205], v[94:97]
	v_mfma_f32_16x16x32_bf16 v[90:93], v[134:137], v[202:205], v[90:93]
	v_mfma_f32_16x16x32_bf16 v[78:81], v[118:121], v[222:225], v[78:81]
	v_mfma_f32_16x16x32_bf16 v[74:77], v[134:137], v[222:225], v[74:77]
	v_mfma_f32_16x16x32_bf16 v[130:133], v[146:149], v[172:175], v[130:133]
	v_mfma_f32_16x16x32_bf16 v[122:125], v[164:167], v[172:175], v[122:125]
	v_mfma_f32_16x16x32_bf16 v[102:105], v[146:149], v[180:183], v[102:105]
	v_mfma_f32_16x16x32_bf16 v[98:101], v[164:167], v[180:183], v[98:101]
	v_mfma_f32_16x16x32_bf16 v[86:89], v[146:149], v[198:201], v[86:89]
	v_mfma_f32_16x16x32_bf16 v[82:85], v[164:167], v[198:201], v[82:85]
	v_mfma_f32_16x16x32_bf16 v[70:73], v[146:149], v[206:209], v[70:73]
	v_mfma_f32_16x16x32_bf16 v[66:69], v[164:167], v[206:209], v[66:69]
	v_mfma_f32_16x16x32_bf16 v[130:133], v[150:153], v[176:179], v[130:133]
	v_mfma_f32_16x16x32_bf16 v[122:125], v[168:171], v[176:179], v[122:125]
	v_mfma_f32_16x16x32_bf16 v[102:105], v[150:153], v[188:191], v[102:105]
	v_mfma_f32_16x16x32_bf16 v[98:101], v[168:171], v[188:191], v[98:101]
	v_mfma_f32_16x16x32_bf16 v[86:89], v[150:153], v[202:205], v[86:89]
	v_mfma_f32_16x16x32_bf16 v[82:85], v[168:171], v[202:205], v[82:85]
	v_mfma_f32_16x16x32_bf16 v[70:73], v[150:153], v[222:225], v[70:73]
	v_mfma_f32_16x16x32_bf16 v[66:69], v[168:171], v[222:225], v[66:69]
	s_barrier
	s_add_i32 s30, s62, s33
	v_lshl_add_u64 v[210:211], s[46:47], 0, v[0:1]
	s_mov_b32 m0, s30
	ds_read_b128 v[172:175], v187 offset:16384
	ds_read_b128 v[176:179], v187 offset:17408
	ds_read_b128 v[180:183], v187 offset:18432
	ds_read_b128 v[188:191], v187 offset:19456
	ds_read_b128 v[198:201], v187 offset:20480
	ds_read_b128 v[202:205], v187 offset:21504
	ds_read_b128 v[206:209], v187 offset:22528
	ds_read_b128 v[222:225], v187 offset:23552
	global_load_lds_dwordx4 v[210:211], off
	s_add_i32 m0, s30, 0x2000
	s_add_u32 s30, s46, 0x40000
	v_lshl_add_u64 v[226:227], s[46:47], 0, v[154:155]
	s_addc_u32 s31, s47, 0
	s_add_i32 s62, s63, s33
	global_load_lds_dwordx4 v[226:227], off
	v_lshl_add_u64 v[228:229], s[30:31], 0, v[0:1]
	s_mov_b32 m0, s62
	v_lshl_add_u64 v[230:231], s[48:49], 0, v[156:157]
	global_load_lds_dwordx4 v[228:229], off
	v_lshl_add_u64 v[228:229], s[30:31], 0, v[154:155]
	s_add_i32 m0, s62, 0x2000
	s_nop 0
	global_load_lds_dwordx4 v[228:229], off
	v_lshl_add_u64 v[228:229], s[48:49], 0, v[158:159]
	s_mov_b32 m0, s50
	s_nop 0
	global_load_lds_dwordx4 v[228:229], off
	s_mov_b32 m0, s51
	s_nop 0
	global_load_lds_dwordx4 v[230:231], off
	s_waitcnt vmcnt(8)
	s_waitcnt lgkmcnt(0)
	s_barrier
	s_waitcnt lgkmcnt(0)
	v_mfma_f32_16x16x32_bf16 v[62:65], v[114:117], v[172:175], v[62:65]
	v_mfma_f32_16x16x32_bf16 v[58:61], v[126:129], v[172:175], v[58:61]
	v_mfma_f32_16x16x32_bf16 v[46:49], v[114:117], v[180:183], v[46:49]
	v_mfma_f32_16x16x32_bf16 v[42:45], v[126:129], v[180:183], v[42:45]
	v_mfma_f32_16x16x32_bf16 v[30:33], v[114:117], v[198:201], v[30:33]
	v_mfma_f32_16x16x32_bf16 v[26:29], v[126:129], v[198:201], v[26:29]
	v_mfma_f32_16x16x32_bf16 v[14:17], v[114:117], v[206:209], v[14:17]
	v_mfma_f32_16x16x32_bf16 v[10:13], v[126:129], v[206:209], v[10:13]
	v_mfma_f32_16x16x32_bf16 v[62:65], v[118:121], v[176:179], v[62:65]
	v_mfma_f32_16x16x32_bf16 v[58:61], v[134:137], v[176:179], v[58:61]
	v_mfma_f32_16x16x32_bf16 v[46:49], v[118:121], v[188:191], v[46:49]
	v_mfma_f32_16x16x32_bf16 v[42:45], v[134:137], v[188:191], v[42:45]
	v_mfma_f32_16x16x32_bf16 v[30:33], v[118:121], v[202:205], v[30:33]
	v_mfma_f32_16x16x32_bf16 v[26:29], v[134:137], v[202:205], v[26:29]
	v_mfma_f32_16x16x32_bf16 v[14:17], v[118:121], v[222:225], v[14:17]
	v_mfma_f32_16x16x32_bf16 v[10:13], v[134:137], v[222:225], v[10:13]
	v_mfma_f32_16x16x32_bf16 v[54:57], v[146:149], v[172:175], v[54:57]
	v_mfma_f32_16x16x32_bf16 v[50:53], v[164:167], v[172:175], v[50:53]
	v_mfma_f32_16x16x32_bf16 v[38:41], v[146:149], v[180:183], v[38:41]
	v_mfma_f32_16x16x32_bf16 v[34:37], v[164:167], v[180:183], v[34:37]
	v_mfma_f32_16x16x32_bf16 v[22:25], v[146:149], v[198:201], v[22:25]
	v_mfma_f32_16x16x32_bf16 v[18:21], v[164:167], v[198:201], v[18:21]
	v_mfma_f32_16x16x32_bf16 v[6:9], v[146:149], v[206:209], v[6:9]
	v_mfma_f32_16x16x32_bf16 v[2:5], v[164:167], v[206:209], v[2:5]
	v_mfma_f32_16x16x32_bf16 v[54:57], v[150:153], v[176:179], v[54:57]
	v_mfma_f32_16x16x32_bf16 v[50:53], v[168:171], v[176:179], v[50:53]
	v_mfma_f32_16x16x32_bf16 v[38:41], v[150:153], v[188:191], v[38:41]
	v_mfma_f32_16x16x32_bf16 v[34:37], v[168:171], v[188:191], v[34:37]
	v_mfma_f32_16x16x32_bf16 v[22:25], v[150:153], v[202:205], v[22:25]
	v_mfma_f32_16x16x32_bf16 v[18:21], v[168:171], v[202:205], v[18:21]
	v_mfma_f32_16x16x32_bf16 v[6:9], v[150:153], v[222:225], v[6:9]
	v_mfma_f32_16x16x32_bf16 v[2:5], v[168:171], v[222:225], v[2:5]
	s_barrier
; #define PG8_STAGE(bufoff, gbase, voff) do { _Pragma("unroll") for (int _i = 0; _i < 2; ++_i) \
;         __builtin_amdgcn_global_load_lds((const unsigned*)((const char*)(gbase) + (voff)[_i]), (PG8_LAS unsigned*)(lds + (bufoff) + ldsw + _i * 8192), 16, 0, 0); } while (0)
; #define PG8_LDA(dst, b, h) do { _Pragma("unroll") for (int m = 0; m < 4; ++m) _Pragma("unroll") for (int k = 0; k < 2; ++k) dst[m][k] = *(const PG8_LAS bf16x8*)(lds + PG8_SA(b, h) + aoff + m * 2048 + k * 1024); } while (0)
; #define PG8_LDB(dst, b, h) do { _Pragma("unroll") for (int n = 0; n < 2; ++n) _Pragma("unroll") for (int k = 0; k < 2; ++k) dst[n][k] = *(const PG8_LAS bf16x8*)(lds + PG8_SB(b, h) + boff + n * 2048 + k * 1024); } while (0)
; #define PG8_MMA(ai, bj, At, Bt) do { __builtin_amdgcn_s_setprio(1); _Pragma("unroll") for (int m = 0; m < 4; ++m) _Pragma("unroll") for (int n = 0; n < 2; ++n) _Pragma("unroll") for (int k = 0; k < 2; ++k) \
;         acc[ai][bj][m][n] = __builtin_amdgcn_mfma_f32_16x16x32_bf16(Bt[n][k], At[m][k], acc[ai][bj][m][n], 0, 0, 0); __builtin_amdgcn_s_setprio(0); } while (0)
; #define PG8_WAIT_V(n) asm volatile("s_waitcnt vmcnt(" #n ")" ::: "memory")
; #define PG8_WAIT_L(n) asm volatile("s_waitcnt lgkmcnt(" #n ")" ::: "memory")
; #define PG8_BAR __builtin_amdgcn_s_barrier()
; template <class Epi, class Sched, bool ALIGN_EPI = false, bool SP2 = false>
; __device__ __forceinline__ void gemm_phase(PG8_LAS unsigned char* lds, const Gemm g, const Sched& S, const Epi& E) {
;     ...
;         for (int t = 0; t < nt; t += 2) {
;             const bool last = (t == nt - 2);
;             const char* a1 = cA + (size_t)(t + 1) * kstep;
;             const char* a2 = last ? nA : cA + (size_t)(t + 2) * kstep; const char* b2 = last ? nB : cB + (size_t)(t + 2) * kstep;
;             const char* a3 = a2 + kstep; const char* b3 = b2 + kstep;
;     ...
;             PG8_LDB(B0, 1, 0); PG8_LDB(B1, 1, 1); PG8_SCHED; PG8_LDA(At, 1, 0); PG8_STAGE(PG8_SA(0, 1), a2 + hstep, voffA);
;             PG8_WAIT_V(8); PG8_WAIT_L(0); PG8_BAR; PG8_MMA(0, 0, At, B0); PG8_MMA(0, 1, At, B1); PG8_BAR; PG8_SCHED;
;             PG8_LDA(At, 1, 1); PG8_STAGE(PG8_SB(1, 0), b3, voffB); PG8_STAGE(PG8_SB(1, 1), b3 + hstep, voffB); PG8_STAGE(PG8_SA(1, 0), a3, voffA);
;             PG8_WAIT_V(8); PG8_WAIT_L(0); PG8_BAR; PG8_MMA(1, 0, At, B0); PG8_MMA(1, 1, At, B1); PG8_BAR; PG8_SCHED;
	s_add_i32 s62, 0, 0x18000
	s_add_i32 s63, 0, 0x1c000
	v_add_u32_e32 v134, s62, v185
	v_add_u32_e32 v168, s63, v185
	ds_read_b128 v[114:117], v134
	ds_read_b128 v[118:121], v134 offset:1024
	ds_read_b128 v[126:129], v134 offset:2048
	ds_read_b128 v[134:137], v134 offset:3072
	ds_read_b128 v[146:149], v168
	ds_read_b128 v[150:153], v168 offset:1024
	ds_read_b128 v[164:167], v168 offset:2048
	ds_read_b128 v[168:171], v168 offset:3072
	s_add_u32 s30, s48, 0x40000
	s_addc_u32 s31, s49, 0
	s_mov_b32 m0, s52
	v_lshl_add_u64 v[232:233], s[30:31], 0, v[158:159]
	ds_read_b128 v[172:175], v187 offset:32768
	ds_read_b128 v[176:179], v187 offset:33792
	ds_read_b128 v[180:183], v187 offset:34816
	ds_read_b128 v[188:191], v187 offset:35840
	ds_read_b128 v[198:201], v187 offset:36864
	ds_read_b128 v[202:205], v187 offset:37888
	ds_read_b128 v[206:209], v187 offset:38912
	ds_read_b128 v[222:225], v187 offset:39936
	global_load_lds_dwordx4 v[232:233], off
	v_lshl_add_u64 v[232:233], s[30:31], 0, v[156:157]
	s_mov_b32 m0, s53
	s_nop 0
	global_load_lds_dwordx4 v[232:233], off
	s_waitcnt vmcnt(8)
	s_waitcnt lgkmcnt(0)
	s_barrier
	s_waitcnt lgkmcnt(0)
	v_mfma_f32_16x16x32_bf16 v[142:145], v[114:117], v[172:175], v[142:145]
	v_mfma_f32_16x16x32_bf16 v[138:141], v[126:129], v[172:175], v[138:141]
	v_mfma_f32_16x16x32_bf16 v[110:113], v[114:117], v[180:183], v[110:113]
	v_mfma_f32_16x16x32_bf16 v[106:109], v[126:129], v[180:183], v[106:109]
	v_mfma_f32_16x16x32_bf16 v[94:97], v[114:117], v[198:201], v[94:97]
	v_mfma_f32_16x16x32_bf16 v[90:93], v[126:129], v[198:201], v[90:93]
	v_mfma_f32_16x16x32_bf16 v[78:81], v[114:117], v[206:209], v[78:81]
	v_mfma_f32_16x16x32_bf16 v[74:77], v[126:129], v[206:209], v[74:77]
	v_mfma_f32_16x16x32_bf16 v[142:145], v[118:121], v[176:179], v[142:145]
	v_mfma_f32_16x16x32_bf16 v[138:141], v[134:137], v[176:179], v[138:141]
	v_mfma_f32_16x16x32_bf16 v[110:113], v[118:121], v[188:191], v[110:113]
	v_mfma_f32_16x16x32_bf16 v[106:109], v[134:137], v[188:191], v[106:109]
	v_mfma_f32_16x16x32_bf16 v[94:97], v[118:121], v[202:205], v[94:97]
	v_mfma_f32_16x16x32_bf16 v[90:93], v[134:137], v[202:205], v[90:93]
	v_mfma_f32_16x16x32_bf16 v[78:81], v[118:121], v[222:225], v[78:81]
	v_mfma_f32_16x16x32_bf16 v[74:77], v[134:137], v[222:225], v[74:77]
	v_mfma_f32_16x16x32_bf16 v[130:133], v[146:149], v[172:175], v[130:133]
	v_mfma_f32_16x16x32_bf16 v[122:125], v[164:167], v[172:175], v[122:125]
	v_mfma_f32_16x16x32_bf16 v[102:105], v[146:149], v[180:183], v[102:105]
	v_mfma_f32_16x16x32_bf16 v[98:101], v[164:167], v[180:183], v[98:101]
	v_mfma_f32_16x16x32_bf16 v[86:89], v[146:149], v[198:201], v[86:89]
	v_mfma_f32_16x16x32_bf16 v[82:85], v[164:167], v[198:201], v[82:85]
	v_mfma_f32_16x16x32_bf16 v[70:73], v[146:149], v[206:209], v[70:73]
	v_mfma_f32_16x16x32_bf16 v[66:69], v[164:167], v[206:209], v[66:69]
	v_mfma_f32_16x16x32_bf16 v[130:133], v[150:153], v[176:179], v[130:133]
	v_mfma_f32_16x16x32_bf16 v[122:125], v[168:171], v[176:179], v[122:125]
	v_mfma_f32_16x16x32_bf16 v[102:105], v[150:153], v[188:191], v[102:105]
	v_mfma_f32_16x16x32_bf16 v[98:101], v[168:171], v[188:191], v[98:101]
	v_mfma_f32_16x16x32_bf16 v[86:89], v[150:153], v[202:205], v[86:89]
	v_mfma_f32_16x16x32_bf16 v[82:85], v[168:171], v[202:205], v[82:85]
	v_mfma_f32_16x16x32_bf16 v[70:73], v[150:153], v[222:225], v[70:73]
	v_mfma_f32_16x16x32_bf16 v[66:69], v[168:171], v[222:225], v[66:69]
	s_barrier
	s_add_i32 s30, s62, s33
	v_lshl_add_u64 v[210:211], v[210:211], 0, s[0:1]
	s_mov_b32 m0, s30
	ds_read_b128 v[172:175], v187 offset:49152
	ds_read_b128 v[176:179], v187 offset:50176
	ds_read_b128 v[180:183], v187 offset:51200
	ds_read_b128 v[188:191], v187 offset:52224
	ds_read_b128 v[198:201], v187 offset:53248
	ds_read_b128 v[202:205], v187 offset:54272
	ds_read_b128 v[206:209], v187 offset:55296
	ds_read_b128 v[222:225], v187 offset:56320
	global_load_lds_dwordx4 v[210:211], off
	s_add_i32 m0, s30, 0x2000
	s_add_u32 s30, s46, 0x40080
	v_lshl_add_u64 v[210:211], v[226:227], 0, s[0:1]
	s_addc_u32 s31, s47, 0
	s_add_i32 s46, s63, s33
	global_load_lds_dwordx4 v[210:211], off
	v_lshl_add_u64 v[210:211], s[30:31], 0, v[0:1]
	s_mov_b32 m0, s46
	s_nop 0
	global_load_lds_dwordx4 v[210:211], off
	v_lshl_add_u64 v[210:211], s[30:31], 0, v[154:155]
	s_add_i32 m0, s46, 0x2000
	s_nop 0
	global_load_lds_dwordx4 v[210:211], off
	v_lshl_add_u64 v[210:211], v[228:229], 0, s[0:1]
	s_mov_b32 m0, s56
	s_nop 0
	global_load_lds_dwordx4 v[210:211], off
	v_lshl_add_u64 v[210:211], v[230:231], 0, s[0:1]
	s_mov_b32 m0, s57
	s_nop 0
	global_load_lds_dwordx4 v[210:211], off
	s_waitcnt vmcnt(8)
	s_waitcnt lgkmcnt(0)
	s_barrier
	s_waitcnt lgkmcnt(0)
	v_mfma_f32_16x16x32_bf16 v[62:65], v[114:117], v[172:175], v[62:65]
	v_mfma_f32_16x16x32_bf16 v[58:61], v[126:129], v[172:175], v[58:61]
	v_mfma_f32_16x16x32_bf16 v[46:49], v[114:117], v[180:183], v[46:49]
	v_mfma_f32_16x16x32_bf16 v[42:45], v[126:129], v[180:183], v[42:45]
	v_mfma_f32_16x16x32_bf16 v[30:33], v[114:117], v[198:201], v[30:33]
	v_mfma_f32_16x16x32_bf16 v[26:29], v[126:129], v[198:201], v[26:29]
	v_mfma_f32_16x16x32_bf16 v[14:17], v[114:117], v[206:209], v[14:17]
	v_mfma_f32_16x16x32_bf16 v[10:13], v[126:129], v[206:209], v[10:13]
	v_mfma_f32_16x16x32_bf16 v[62:65], v[118:121], v[176:179], v[62:65]
	v_mfma_f32_16x16x32_bf16 v[58:61], v[134:137], v[176:179], v[58:61]
	v_mfma_f32_16x16x32_bf16 v[46:49], v[118:121], v[188:191], v[46:49]
	v_mfma_f32_16x16x32_bf16 v[42:45], v[134:137], v[188:191], v[42:45]
	v_mfma_f32_16x16x32_bf16 v[30:33], v[118:121], v[202:205], v[30:33]
	v_mfma_f32_16x16x32_bf16 v[26:29], v[134:137], v[202:205], v[26:29]
	v_mfma_f32_16x16x32_bf16 v[14:17], v[118:121], v[222:225], v[14:17]
	v_mfma_f32_16x16x32_bf16 v[10:13], v[134:137], v[222:225], v[10:13]
	v_mfma_f32_16x16x32_bf16 v[54:57], v[146:149], v[172:175], v[54:57]
	v_mfma_f32_16x16x32_bf16 v[50:53], v[164:167], v[172:175], v[50:53]
	v_mfma_f32_16x16x32_bf16 v[38:41], v[146:149], v[180:183], v[38:41]
	v_mfma_f32_16x16x32_bf16 v[34:37], v[164:167], v[180:183], v[34:37]
	v_mfma_f32_16x16x32_bf16 v[22:25], v[146:149], v[198:201], v[22:25]
	v_mfma_f32_16x16x32_bf16 v[18:21], v[164:167], v[198:201], v[18:21]
	v_mfma_f32_16x16x32_bf16 v[6:9], v[146:149], v[206:209], v[6:9]
	v_mfma_f32_16x16x32_bf16 v[2:5], v[164:167], v[206:209], v[2:5]
	v_mfma_f32_16x16x32_bf16 v[54:57], v[150:153], v[176:179], v[54:57]
	v_mfma_f32_16x16x32_bf16 v[50:53], v[168:171], v[176:179], v[50:53]
	v_mfma_f32_16x16x32_bf16 v[38:41], v[150:153], v[188:191], v[38:41]
	v_mfma_f32_16x16x32_bf16 v[34:37], v[168:171], v[188:191], v[34:37]
	v_mfma_f32_16x16x32_bf16 v[22:25], v[150:153], v[202:205], v[22:25]
	v_mfma_f32_16x16x32_bf16 v[18:21], v[168:171], v[202:205], v[18:21]
	v_mfma_f32_16x16x32_bf16 v[6:9], v[150:153], v[222:225], v[6:9]
	v_mfma_f32_16x16x32_bf16 v[2:5], v[168:171], v[222:225], v[2:5]
	s_barrier
	s_add_i32 s61, s61, 2
	s_add_u32 s44, s44, 0x100
	s_addc_u32 s45, s45, 0
	s_add_u32 s59, s59, 0x100
	s_addc_u32 s60, s60, 0
	s_cmp_gt_u32 s61, 13
	s_cbranch_scc0 .LBB0_676

; #define PG8_STAGE(bufoff, gbase, voff) do { _Pragma("unroll") for (int _i = 0; _i < 2; ++_i) \
;         __builtin_amdgcn_global_load_lds((const unsigned*)((const char*)(gbase) + (voff)[_i]), (PG8_LAS unsigned*)(lds + (bufoff) + ldsw + _i * 8192), 16, 0, 0); } while (0)
; #define PG8_LDA(dst, b, h) do { _Pragma("unroll") for (int m = 0; m < 4; ++m) _Pragma("unroll") for (int k = 0; k < 2; ++k) dst[m][k] = *(const PG8_LAS bf16x8*)(lds + PG8_SA(b, h) + aoff + m * 2048 + k * 1024); } while (0)
; #define PG8_LDB(dst, b, h) do { _Pragma("unroll") for (int n = 0; n < 2; ++n) _Pragma("unroll") for (int k = 0; k < 2; ++k) dst[n][k] = *(const PG8_LAS bf16x8*)(lds + PG8_SB(b, h) + boff + n * 2048 + k * 1024); } while (0)
; #define PG8_MMA(ai, bj, At, Bt) do { __builtin_amdgcn_s_setprio(1); _Pragma("unroll") for (int m = 0; m < 4; ++m) _Pragma("unroll") for (int n = 0; n < 2; ++n) _Pragma("unroll") for (int k = 0; k < 2; ++k) \
;         acc[ai][bj][m][n] = __builtin_amdgcn_mfma_f32_16x16x32_bf16(Bt[n][k], At[m][k], acc[ai][bj][m][n], 0, 0, 0); __builtin_amdgcn_s_setprio(0); } while (0)
; #define PG8_WAIT_V(n) asm volatile("s_waitcnt vmcnt(" #n ")" ::: "memory")
; template <class Epi, class Sched, bool ALIGN_EPI = false, bool SP2 = false>
; __device__ __forceinline__ void gemm_phase(PG8_LAS unsigned char* lds, const Gemm g, const Sched& S, const Epi& E) {
;     ...
;         const char* nA = has_next ? (const char*)g.A + (size_t)nxt.pm * tstep : cA; const char* nB = has_next ? (const char*)g.Bt + (size_t)nxt.pn * tstep : cB;
;         for (int t = 0; t < nt; t += 2) {
;             const bool last = (t == nt - 2);
;             const char* a1 = cA + (size_t)(t + 1) * kstep;
;             const char* a2 = last ? nA : cA + (size_t)(t + 2) * kstep; const char* b2 = last ? nB : cB + (size_t)(t + 2) * kstep;
;             const char* a3 = a2 + kstep; const char* b3 = b2 + kstep;
;             if (last && has_next) S.a_ready(nxt);
;             if constexpr (SP2) {
;             PG8_LDB(B0, 0, 0); PG8_LDB(B1, 0, 1); PG8_SCHED; PG8_LDA(At, 0, 0); PG8_STAGE(PG8_SA(1, 1), a1 + hstep, voffA);
;             PG8_WAIT_V(8); PG8_WAIT_L(0); PG8_BAR; PG8_MMA(0, 0, At, B0); PG8_MMA(0, 1, At, B1); PG8_BAR; PG8_SCHED;
;             PG8_LDA(At, 0, 1); PG8_STAGE(PG8_SB(0, 0), b2, voffB); PG8_STAGE(PG8_SB(0, 1), b2 + hstep, voffB); PG8_STAGE(PG8_SA(0, 0), a2, voffA);
.Lpeel_p4:
	s_add_u32 s30, s46, 0xfffc0080
	s_addc_u32 s31, s47, -1
	s_add_i32 s65, 0, 0x10000
	s_cmp_eq_u32 s64, 12
	s_cselect_b32 s51, s15, s31
	s_cselect_b32 s50, s60, s30
	v_add_u32_e32 v152, s65, v157
	s_cselect_b32 s49, s11, s63
	s_cselect_b32 s48, s61, s62
	s_add_i32 s66, 0, 0x14000
	ds_read_b128 v[50:53], v152
	ds_read_b128 v[54:57], v152 offset:1024
	ds_read_b128 v[162:165], v152 offset:2048
	ds_read_b128 v[166:169], v152 offset:3072
	v_add_u32_e32 v152, s66, v157
	ds_read_b128 v[170:173], v152
	ds_read_b128 v[174:177], v152 offset:1024
	ds_read_b128 v[178:181], v152 offset:2048
	ds_read_b128 v[182:185], v152 offset:3072
	v_lshl_add_u64 v[152:153], s[46:47], 0, v[148:149]
	s_add_i32 m0, s52, 0xc000
	ds_read_b128 v[186:189], v160
	ds_read_b128 v[198:201], v160 offset:1024
	ds_read_b128 v[202:205], v160 offset:2048
	ds_read_b128 v[206:209], v160 offset:3072
	ds_read_b128 v[222:225], v160 offset:4096
	ds_read_b128 v[226:229], v160 offset:5120
	ds_read_b128 v[230:233], v160 offset:6144
	ds_read_b128 v[234:237], v160 offset:7168
	global_load_lds_dwordx4 v[152:153], off
	v_lshl_add_u64 v[152:153], s[46:47], 0, v[150:151]
	s_add_i32 m0, s52, 0xe000
	s_nop 0
	global_load_lds_dwordx4 v[152:153], off
	s_waitcnt vmcnt(8)
	s_waitcnt lgkmcnt(0)
	s_barrier
	s_waitcnt lgkmcnt(0)
	v_mfma_f32_16x16x32_bf16 v[134:137], v[50:53], v[186:189], 0
	v_mfma_f32_16x16x32_bf16 v[126:129], v[162:165], v[186:189], 0
	v_mfma_f32_16x16x32_bf16 v[118:121], v[50:53], v[202:205], 0
	v_mfma_f32_16x16x32_bf16 v[110:113], v[162:165], v[202:205], 0
	v_mfma_f32_16x16x32_bf16 v[102:105], v[50:53], v[222:225], 0
	v_mfma_f32_16x16x32_bf16 v[94:97], v[162:165], v[222:225], 0
	v_mfma_f32_16x16x32_bf16 v[86:89], v[50:53], v[230:233], 0
	v_mfma_f32_16x16x32_bf16 v[78:81], v[162:165], v[230:233], 0
	v_mfma_f32_16x16x32_bf16 v[134:137], v[54:57], v[198:201], v[134:137]
	v_mfma_f32_16x16x32_bf16 v[126:129], v[166:169], v[198:201], v[126:129]
	v_mfma_f32_16x16x32_bf16 v[118:121], v[54:57], v[206:209], v[118:121]
	v_mfma_f32_16x16x32_bf16 v[110:113], v[166:169], v[206:209], v[110:113]
	v_mfma_f32_16x16x32_bf16 v[102:105], v[54:57], v[226:229], v[102:105]
	v_mfma_f32_16x16x32_bf16 v[94:97], v[166:169], v[226:229], v[94:97]
	v_mfma_f32_16x16x32_bf16 v[86:89], v[54:57], v[234:237], v[86:89]
	v_mfma_f32_16x16x32_bf16 v[78:81], v[166:169], v[234:237], v[78:81]
	v_mfma_f32_16x16x32_bf16 v[130:133], v[170:173], v[186:189], 0
	v_mfma_f32_16x16x32_bf16 v[122:125], v[178:181], v[186:189], 0
	v_mfma_f32_16x16x32_bf16 v[114:117], v[170:173], v[202:205], 0
	v_mfma_f32_16x16x32_bf16 v[106:109], v[178:181], v[202:205], 0
	v_mfma_f32_16x16x32_bf16 v[98:101], v[170:173], v[222:225], 0
	v_mfma_f32_16x16x32_bf16 v[90:93], v[178:181], v[222:225], 0
	v_mfma_f32_16x16x32_bf16 v[82:85], v[170:173], v[230:233], 0
	v_mfma_f32_16x16x32_bf16 v[74:77], v[178:181], v[230:233], 0
	v_mfma_f32_16x16x32_bf16 v[130:133], v[174:177], v[198:201], v[130:133]
	v_mfma_f32_16x16x32_bf16 v[122:125], v[182:185], v[198:201], v[122:125]
	v_mfma_f32_16x16x32_bf16 v[114:117], v[174:177], v[206:209], v[114:117]
	v_mfma_f32_16x16x32_bf16 v[106:109], v[182:185], v[206:209], v[106:109]
	v_mfma_f32_16x16x32_bf16 v[98:101], v[174:177], v[226:229], v[98:101]
	v_mfma_f32_16x16x32_bf16 v[90:93], v[182:185], v[226:229], v[90:93]
	v_mfma_f32_16x16x32_bf16 v[82:85], v[174:177], v[234:237], v[82:85]
	v_mfma_f32_16x16x32_bf16 v[74:77], v[182:185], v[234:237], v[74:77]
	s_barrier
	s_add_i32 s30, s65, s33
	v_lshl_add_u64 v[152:153], s[48:49], 0, v[140:141]
	s_mov_b32 m0, s30
	ds_read_b128 v[186:189], v160 offset:16384
	ds_read_b128 v[198:201], v160 offset:17408
	ds_read_b128 v[202:205], v160 offset:18432
	ds_read_b128 v[206:209], v160 offset:19456
	ds_read_b128 v[222:225], v160 offset:20480
	ds_read_b128 v[226:229], v160 offset:21504
	ds_read_b128 v[230:233], v160 offset:22528
	ds_read_b128 v[234:237], v160 offset:23552
	global_load_lds_dwordx4 v[152:153], off
	s_add_i32 m0, s30, 0x2000
	s_add_u32 s30, s48, 0x40000
	v_lshl_add_u64 v[190:191], s[48:49], 0, v[144:145]
	s_addc_u32 s31, s49, 0
	s_add_i32 s65, s66, s33
	global_load_lds_dwordx4 v[190:191], off
	v_lshl_add_u64 v[210:211], s[30:31], 0, v[140:141]
	s_mov_b32 m0, s65
	v_lshl_add_u64 v[238:239], s[50:51], 0, v[142:143]
	global_load_lds_dwordx4 v[210:211], off
	v_lshl_add_u64 v[210:211], s[30:31], 0, v[144:145]
	s_add_i32 m0, s65, 0x2000
	s_nop 0
	global_load_lds_dwordx4 v[210:211], off
	v_lshl_add_u64 v[210:211], s[50:51], 0, v[138:139]
	s_mov_b32 m0, s52
	s_nop 0
	global_load_lds_dwordx4 v[210:211], off
	s_mov_b32 m0, s53
	s_nop 0
	global_load_lds_dwordx4 v[238:239], off
	s_waitcnt vmcnt(8)
	s_waitcnt lgkmcnt(0)
	s_barrier
; #define PG8_STAGE(bufoff, gbase, voff) do { _Pragma("unroll") for (int _i = 0; _i < 2; ++_i) \
;         __builtin_amdgcn_global_load_lds((const unsigned*)((const char*)(gbase) + (voff)[_i]), (PG8_LAS unsigned*)(lds + (bufoff) + ldsw + _i * 8192), 16, 0, 0); } while (0)
; #define PG8_LDA(dst, b, h) do { _Pragma("unroll") for (int m = 0; m < 4; ++m) _Pragma("unroll") for (int k = 0; k < 2; ++k) dst[m][k] = *(const PG8_LAS bf16x8*)(lds + PG8_SA(b, h) + aoff + m * 2048 + k * 1024); } while (0)
; #define PG8_LDB(dst, b, h) do { _Pragma("unroll") for (int n = 0; n < 2; ++n) _Pragma("unroll") for (int k = 0; k < 2; ++k) dst[n][k] = *(const PG8_LAS bf16x8*)(lds + PG8_SB(b, h) + boff + n * 2048 + k * 1024); } while (0)
; #define PG8_MMA(ai, bj, At, Bt) do { __builtin_amdgcn_s_setprio(1); _Pragma("unroll") for (int m = 0; m < 4; ++m) _Pragma("unroll") for (int n = 0; n < 2; ++n) _Pragma("unroll") for (int k = 0; k < 2; ++k) \
;         acc[ai][bj][m][n] = __builtin_amdgcn_mfma_f32_16x16x32_bf16(Bt[n][k], At[m][k], acc[ai][bj][m][n], 0, 0, 0); __builtin_amdgcn_s_setprio(0); } while (0)
; #define PG8_WAIT_V(n) asm volatile("s_waitcnt vmcnt(" #n ")" ::: "memory")
; #define PG8_WAIT_L(n) asm volatile("s_waitcnt lgkmcnt(" #n ")" ::: "memory")
; #define PG8_BAR __builtin_amdgcn_s_barrier()
; #define PG8_SCHED __builtin_amdgcn_sched_barrier(0)
; template <class Epi, class Sched, bool ALIGN_EPI = false, bool SP2 = false>
; __device__ __forceinline__ void gemm_phase(PG8_LAS unsigned char* lds, const Gemm g, const Sched& S, const Epi& E) {
;     ...
;             PG8_WAIT_V(8); PG8_WAIT_L(0); PG8_BAR; PG8_MMA(0, 0, At, B0); PG8_MMA(0, 1, At, B1); PG8_BAR; PG8_SCHED;
;             PG8_LDA(At, 0, 1); PG8_STAGE(PG8_SB(0, 0), b2, voffB); PG8_STAGE(PG8_SB(0, 1), b2 + hstep, voffB); PG8_STAGE(PG8_SA(0, 0), a2, voffA);
;             PG8_WAIT_V(8); PG8_WAIT_L(0); PG8_BAR; PG8_MMA(1, 0, At, B0); PG8_MMA(1, 1, At, B1); PG8_BAR; PG8_SCHED;
;             PG8_LDB(B0, 1, 0); PG8_LDB(B1, 1, 1); PG8_SCHED; PG8_LDA(At, 1, 0); PG8_STAGE(PG8_SA(0, 1), a2 + hstep, voffA);
;             PG8_WAIT_V(8); PG8_WAIT_L(0); PG8_BAR; PG8_MMA(0, 0, At, B0); PG8_MMA(0, 1, At, B1); PG8_BAR; PG8_SCHED;
	s_waitcnt lgkmcnt(0)
	v_mfma_f32_16x16x32_bf16 v[70:73], v[50:53], v[186:189], 0
	v_mfma_f32_16x16x32_bf16 v[62:65], v[162:165], v[186:189], 0
	v_mfma_f32_16x16x32_bf16 v[46:49], v[50:53], v[202:205], 0
	v_mfma_f32_16x16x32_bf16 v[38:41], v[162:165], v[202:205], 0
	v_mfma_f32_16x16x32_bf16 v[30:33], v[50:53], v[222:225], 0
	v_mfma_f32_16x16x32_bf16 v[22:25], v[162:165], v[222:225], 0
	v_mfma_f32_16x16x32_bf16 v[14:17], v[50:53], v[230:233], 0
	v_mfma_f32_16x16x32_bf16 v[6:9], v[162:165], v[230:233], 0
	v_mfma_f32_16x16x32_bf16 v[70:73], v[54:57], v[198:201], v[70:73]
	v_mfma_f32_16x16x32_bf16 v[62:65], v[166:169], v[198:201], v[62:65]
	v_mfma_f32_16x16x32_bf16 v[46:49], v[54:57], v[206:209], v[46:49]
	v_mfma_f32_16x16x32_bf16 v[38:41], v[166:169], v[206:209], v[38:41]
	v_mfma_f32_16x16x32_bf16 v[30:33], v[54:57], v[226:229], v[30:33]
	v_mfma_f32_16x16x32_bf16 v[22:25], v[166:169], v[226:229], v[22:25]
	v_mfma_f32_16x16x32_bf16 v[14:17], v[54:57], v[234:237], v[14:17]
	v_mfma_f32_16x16x32_bf16 v[6:9], v[166:169], v[234:237], v[6:9]
	v_mfma_f32_16x16x32_bf16 v[42:45], v[170:173], v[202:205], 0
	v_mfma_f32_16x16x32_bf16 v[34:37], v[178:181], v[202:205], 0
	v_mfma_f32_16x16x32_bf16 v[26:29], v[170:173], v[222:225], 0
	v_mfma_f32_16x16x32_bf16 v[18:21], v[178:181], v[222:225], 0
	v_mfma_f32_16x16x32_bf16 v[10:13], v[170:173], v[230:233], 0
	v_mfma_f32_16x16x32_bf16 v[2:5], v[178:181], v[230:233], 0
	v_mfma_f32_16x16x32_bf16 v[50:53], v[170:173], v[186:189], 0
	v_mfma_f32_16x16x32_bf16 v[54:57], v[178:181], v[186:189], 0
	v_mfma_f32_16x16x32_bf16 v[42:45], v[174:177], v[206:209], v[42:45]
	v_mfma_f32_16x16x32_bf16 v[34:37], v[182:185], v[206:209], v[34:37]
	v_mfma_f32_16x16x32_bf16 v[26:29], v[174:177], v[226:229], v[26:29]
	v_mfma_f32_16x16x32_bf16 v[18:21], v[182:185], v[226:229], v[18:21]
	v_mfma_f32_16x16x32_bf16 v[10:13], v[174:177], v[234:237], v[10:13]
	v_mfma_f32_16x16x32_bf16 v[2:5], v[182:185], v[234:237], v[2:5]
	v_mfma_f32_16x16x32_bf16 v[50:53], v[174:177], v[198:201], v[50:53]
	v_mfma_f32_16x16x32_bf16 v[54:57], v[182:185], v[198:201], v[54:57]
	s_barrier
	s_add_i32 s65, 0, 0x18000
	v_add_u32_e32 v161, s65, v157
	s_add_i32 s66, 0, 0x1c000
	ds_read_b128 v[58:61], v161
	ds_read_b128 v[66:69], v161 offset:1024
	ds_read_b128 v[162:165], v161 offset:2048
	ds_read_b128 v[166:169], v161 offset:3072
	v_add_u32_e32 v161, s66, v157
	ds_read_b128 v[170:173], v161
	ds_read_b128 v[174:177], v161 offset:1024
	ds_read_b128 v[178:181], v161 offset:2048
	ds_read_b128 v[182:185], v161 offset:3072
	s_add_u32 s30, s50, 0x40000
	s_addc_u32 s31, s51, 0
	s_mov_b32 m0, s54
	v_lshl_add_u64 v[240:241], s[30:31], 0, v[138:139]
	ds_read_b128 v[186:189], v160 offset:32768
	ds_read_b128 v[198:201], v160 offset:33792
	ds_read_b128 v[202:205], v160 offset:34816
	ds_read_b128 v[206:209], v160 offset:35840
	ds_read_b128 v[222:225], v160 offset:36864
	ds_read_b128 v[226:229], v160 offset:37888
	ds_read_b128 v[230:233], v160 offset:38912
	ds_read_b128 v[234:237], v160 offset:39936
	global_load_lds_dwordx4 v[240:241], off
	v_lshl_add_u64 v[240:241], s[30:31], 0, v[142:143]
	s_mov_b32 m0, s55
	s_nop 0
	global_load_lds_dwordx4 v[240:241], off
	s_waitcnt vmcnt(8)
	s_waitcnt lgkmcnt(0)
	s_barrier
	s_waitcnt lgkmcnt(0)
	v_mfma_f32_16x16x32_bf16 v[134:137], v[58:61], v[186:189], v[134:137]
	v_mfma_f32_16x16x32_bf16 v[126:129], v[162:165], v[186:189], v[126:129]
	v_mfma_f32_16x16x32_bf16 v[118:121], v[58:61], v[202:205], v[118:121]
	v_mfma_f32_16x16x32_bf16 v[110:113], v[162:165], v[202:205], v[110:113]
	v_mfma_f32_16x16x32_bf16 v[102:105], v[58:61], v[222:225], v[102:105]
	v_mfma_f32_16x16x32_bf16 v[94:97], v[162:165], v[222:225], v[94:97]
	v_mfma_f32_16x16x32_bf16 v[86:89], v[58:61], v[230:233], v[86:89]
	v_mfma_f32_16x16x32_bf16 v[78:81], v[162:165], v[230:233], v[78:81]
	v_mfma_f32_16x16x32_bf16 v[134:137], v[66:69], v[198:201], v[134:137]
	v_mfma_f32_16x16x32_bf16 v[126:129], v[166:169], v[198:201], v[126:129]
	v_mfma_f32_16x16x32_bf16 v[118:121], v[66:69], v[206:209], v[118:121]
	v_mfma_f32_16x16x32_bf16 v[110:113], v[166:169], v[206:209], v[110:113]
	v_mfma_f32_16x16x32_bf16 v[102:105], v[66:69], v[226:229], v[102:105]
	v_mfma_f32_16x16x32_bf16 v[94:97], v[166:169], v[226:229], v[94:97]
	v_mfma_f32_16x16x32_bf16 v[86:89], v[66:69], v[234:237], v[86:89]
	v_mfma_f32_16x16x32_bf16 v[78:81], v[166:169], v[234:237], v[78:81]
	v_mfma_f32_16x16x32_bf16 v[130:133], v[170:173], v[186:189], v[130:133]
	v_mfma_f32_16x16x32_bf16 v[122:125], v[178:181], v[186:189], v[122:125]
	v_mfma_f32_16x16x32_bf16 v[114:117], v[170:173], v[202:205], v[114:117]
	v_mfma_f32_16x16x32_bf16 v[106:109], v[178:181], v[202:205], v[106:109]
	v_mfma_f32_16x16x32_bf16 v[98:101], v[170:173], v[222:225], v[98:101]
	v_mfma_f32_16x16x32_bf16 v[90:93], v[178:181], v[222:225], v[90:93]
	v_mfma_f32_16x16x32_bf16 v[82:85], v[170:173], v[230:233], v[82:85]
	v_mfma_f32_16x16x32_bf16 v[74:77], v[178:181], v[230:233], v[74:77]
	v_mfma_f32_16x16x32_bf16 v[130:133], v[174:177], v[198:201], v[130:133]
	v_mfma_f32_16x16x32_bf16 v[122:125], v[182:185], v[198:201], v[122:125]
	v_mfma_f32_16x16x32_bf16 v[114:117], v[174:177], v[206:209], v[114:117]
	v_mfma_f32_16x16x32_bf16 v[106:109], v[182:185], v[206:209], v[106:109]
	v_mfma_f32_16x16x32_bf16 v[98:101], v[174:177], v[226:229], v[98:101]
	v_mfma_f32_16x16x32_bf16 v[90:93], v[182:185], v[226:229], v[90:93]
	v_mfma_f32_16x16x32_bf16 v[82:85], v[174:177], v[234:237], v[82:85]
	v_mfma_f32_16x16x32_bf16 v[74:77], v[182:185], v[234:237], v[74:77]
	s_barrier
; #define PG8_STAGE(bufoff, gbase, voff) do { _Pragma("unroll") for (int _i = 0; _i < 2; ++_i) \
;         __builtin_amdgcn_global_load_lds((const unsigned*)((const char*)(gbase) + (voff)[_i]), (PG8_LAS unsigned*)(lds + (bufoff) + ldsw + _i * 8192), 16, 0, 0); } while (0)
; #define PG8_LDA(dst, b, h) do { _Pragma("unroll") for (int m = 0; m < 4; ++m) _Pragma("unroll") for (int k = 0; k < 2; ++k) dst[m][k] = *(const PG8_LAS bf16x8*)(lds + PG8_SA(b, h) + aoff + m * 2048 + k * 1024); } while (0)
; #define PG8_LDB(dst, b, h) do { _Pragma("unroll") for (int n = 0; n < 2; ++n) _Pragma("unroll") for (int k = 0; k < 2; ++k) dst[n][k] = *(const PG8_LAS bf16x8*)(lds + PG8_SB(b, h) + boff + n * 2048 + k * 1024); } while (0)
; template <class Epi, class Sched, bool ALIGN_EPI = false, bool SP2 = false>
; __device__ __forceinline__ void gemm_phase(PG8_LAS unsigned char* lds, const Gemm g, const Sched& S, const Epi& E) {
;     ...
;         for (int t = 0; t < nt; t += 2) {
;             const bool last = (t == nt - 2);
;             const char* a1 = cA + (size_t)(t + 1) * kstep;
;             const char* a2 = last ? nA : cA + (size_t)(t + 2) * kstep; const char* b2 = last ? nB : cB + (size_t)(t + 2) * kstep;
;             const char* a3 = a2 + kstep; const char* b3 = b2 + kstep;
;             if (last && has_next) S.a_ready(nxt);
;             if constexpr (SP2) {
;             PG8_LDB(B0, 0, 0); PG8_LDB(B1, 0, 1); PG8_SCHED; PG8_LDA(At, 0, 0); PG8_STAGE(PG8_SA(1, 1), a1 + hstep, voffA);
;             PG8_WAIT_V(8); PG8_WAIT_L(0); PG8_BAR; PG8_MMA(0, 0, At, B0); PG8_MMA(0, 1, At, B1); PG8_BAR; PG8_SCHED;
;             PG8_LDA(At, 0, 1); PG8_STAGE(PG8_SB(0, 0), b2, voffB); PG8_STAGE(PG8_SB(0, 1), b2 + hstep, voffB); PG8_STAGE(PG8_SA(0, 0), a2, voffA);
;             PG8_WAIT_V(8); PG8_WAIT_L(0); PG8_BAR; PG8_MMA(1, 0, At, B0); PG8_MMA(1, 1, At, B1); PG8_BAR; PG8_SCHED;
;             PG8_LDB(B0, 1, 0); PG8_LDB(B1, 1, 1); PG8_SCHED; PG8_LDA(At, 1, 0); PG8_STAGE(PG8_SA(0, 1), a2 + hstep, voffA);
;             PG8_WAIT_V(8); PG8_WAIT_L(0); PG8_BAR; PG8_MMA(0, 0, At, B0); PG8_MMA(0, 1, At, B1); PG8_BAR; PG8_SCHED;
;             PG8_LDA(At, 1, 1); PG8_STAGE(PG8_SB(1, 0), b3, voffB); PG8_STAGE(PG8_SB(1, 1), b3 + hstep, voffB); PG8_STAGE(PG8_SA(1, 0), a3, voffA);
;             PG8_WAIT_V(8); PG8_WAIT_L(0); PG8_BAR; PG8_MMA(1, 0, At, B0); PG8_MMA(1, 1, At, B1); PG8_BAR; PG8_SCHED;
	s_add_i32 s30, s65, s33
	v_lshl_add_u64 v[152:153], v[152:153], 0, s[0:1]
	s_mov_b32 m0, s30
	ds_read_b128 v[186:189], v160 offset:49152
	ds_read_b128 v[198:201], v160 offset:50176
	ds_read_b128 v[202:205], v160 offset:51200
	ds_read_b128 v[206:209], v160 offset:52224
	ds_read_b128 v[222:225], v160 offset:53248
	ds_read_b128 v[226:229], v160 offset:54272
	ds_read_b128 v[230:233], v160 offset:55296
	ds_read_b128 v[234:237], v160 offset:56320
	global_load_lds_dwordx4 v[152:153], off
	s_add_i32 m0, s30, 0x2000
	s_add_u32 s30, s48, 0x40080
	v_lshl_add_u64 v[152:153], v[190:191], 0, s[0:1]
	s_addc_u32 s31, s49, 0
	s_add_i32 s48, s66, s33
	global_load_lds_dwordx4 v[152:153], off
	v_lshl_add_u64 v[152:153], s[30:31], 0, v[140:141]
	s_mov_b32 m0, s48
	s_nop 0
	global_load_lds_dwordx4 v[152:153], off
	v_lshl_add_u64 v[152:153], s[30:31], 0, v[144:145]
	s_add_i32 m0, s48, 0x2000
	s_nop 0
	global_load_lds_dwordx4 v[152:153], off
	v_lshl_add_u64 v[152:153], v[210:211], 0, s[0:1]
	s_mov_b32 m0, s56
	s_nop 0
	global_load_lds_dwordx4 v[152:153], off
	v_lshl_add_u64 v[152:153], v[238:239], 0, s[0:1]
	s_mov_b32 m0, s57
	s_nop 0
	global_load_lds_dwordx4 v[152:153], off
	s_waitcnt vmcnt(8)
	s_waitcnt lgkmcnt(0)
	s_barrier
	s_waitcnt lgkmcnt(0)
	v_mfma_f32_16x16x32_bf16 v[70:73], v[58:61], v[186:189], v[70:73]
	v_mfma_f32_16x16x32_bf16 v[62:65], v[162:165], v[186:189], v[62:65]
	v_mfma_f32_16x16x32_bf16 v[46:49], v[58:61], v[202:205], v[46:49]
	v_mfma_f32_16x16x32_bf16 v[38:41], v[162:165], v[202:205], v[38:41]
	v_mfma_f32_16x16x32_bf16 v[30:33], v[58:61], v[222:225], v[30:33]
	v_mfma_f32_16x16x32_bf16 v[22:25], v[162:165], v[222:225], v[22:25]
	v_mfma_f32_16x16x32_bf16 v[14:17], v[58:61], v[230:233], v[14:17]
	v_mfma_f32_16x16x32_bf16 v[6:9], v[162:165], v[230:233], v[6:9]
	v_mfma_f32_16x16x32_bf16 v[70:73], v[66:69], v[198:201], v[70:73]
	v_mfma_f32_16x16x32_bf16 v[62:65], v[166:169], v[198:201], v[62:65]
	v_mfma_f32_16x16x32_bf16 v[46:49], v[66:69], v[206:209], v[46:49]
	v_mfma_f32_16x16x32_bf16 v[38:41], v[166:169], v[206:209], v[38:41]
	v_mfma_f32_16x16x32_bf16 v[30:33], v[66:69], v[226:229], v[30:33]
	v_mfma_f32_16x16x32_bf16 v[22:25], v[166:169], v[226:229], v[22:25]
	v_mfma_f32_16x16x32_bf16 v[14:17], v[66:69], v[234:237], v[14:17]
	v_mfma_f32_16x16x32_bf16 v[6:9], v[166:169], v[234:237], v[6:9]
	v_mfma_f32_16x16x32_bf16 v[50:53], v[170:173], v[186:189], v[50:53]
	v_mfma_f32_16x16x32_bf16 v[66:69], v[174:177], v[198:201], v[50:53]
	v_mfma_f32_16x16x32_bf16 v[50:53], v[178:181], v[186:189], v[54:57]
	v_mfma_f32_16x16x32_bf16 v[42:45], v[170:173], v[202:205], v[42:45]
	v_mfma_f32_16x16x32_bf16 v[34:37], v[178:181], v[202:205], v[34:37]
	v_mfma_f32_16x16x32_bf16 v[26:29], v[170:173], v[222:225], v[26:29]
	v_mfma_f32_16x16x32_bf16 v[18:21], v[178:181], v[222:225], v[18:21]
	v_mfma_f32_16x16x32_bf16 v[10:13], v[170:173], v[230:233], v[10:13]
	v_mfma_f32_16x16x32_bf16 v[2:5], v[178:181], v[230:233], v[2:5]
	v_mfma_f32_16x16x32_bf16 v[58:61], v[182:185], v[198:201], v[50:53]
	v_mfma_f32_16x16x32_bf16 v[42:45], v[174:177], v[206:209], v[42:45]
	v_mfma_f32_16x16x32_bf16 v[34:37], v[182:185], v[206:209], v[34:37]
	v_mfma_f32_16x16x32_bf16 v[26:29], v[174:177], v[226:229], v[26:29]
	v_mfma_f32_16x16x32_bf16 v[18:21], v[182:185], v[226:229], v[18:21]
	v_mfma_f32_16x16x32_bf16 v[10:13], v[174:177], v[234:237], v[10:13]
	v_mfma_f32_16x16x32_bf16 v[2:5], v[182:185], v[234:237], v[2:5]
	s_barrier
	s_add_i32 s64, s64, 2
	s_add_u32 s46, s46, 0x100
	s_addc_u32 s47, s47, 0
	s_add_u32 s62, s62, 0x100
	s_addc_u32 s63, s63, 0
	s_cmp_gt_u32 s64, 13
	s_cbranch_scc0 .LBB0_781
	s_branch .Lpeel_exit_p4
.LBB0_781:
	s_add_u32 s30, s46, 0xfffc0080
	s_addc_u32 s31, s47, -1
	s_add_i32 s65, 0, 0x10000
	s_cmp_eq_u32 s64, 12
	s_cselect_b32 s51, s15, s31
	s_cselect_b32 s50, s60, s30
	v_add_u32_e32 v152, s65, v157
	s_cselect_b32 s49, s11, s63
	s_cselect_b32 s48, s61, s62
	s_add_i32 s66, 0, 0x14000
	ds_read_b128 v[50:53], v152
	ds_read_b128 v[54:57], v152 offset:1024
	ds_read_b128 v[162:165], v152 offset:2048
	ds_read_b128 v[166:169], v152 offset:3072
	v_add_u32_e32 v152, s66, v157
	ds_read_b128 v[170:173], v152
	ds_read_b128 v[174:177], v152 offset:1024
	ds_read_b128 v[178:181], v152 offset:2048
	ds_read_b128 v[182:185], v152 offset:3072
	v_lshl_add_u64 v[152:153], s[46:47], 0, v[148:149]
	s_add_i32 m0, s52, 0xc000
	ds_read_b128 v[186:189], v160
	ds_read_b128 v[198:201], v160 offset:1024
	ds_read_b128 v[202:205], v160 offset:2048
	ds_read_b128 v[206:209], v160 offset:3072
	ds_read_b128 v[222:225], v160 offset:4096
	ds_read_b128 v[226:229], v160 offset:5120
	ds_read_b128 v[230:233], v160 offset:6144
	ds_read_b128 v[234:237], v160 offset:7168
	global_load_lds_dwordx4 v[152:153], off
	v_lshl_add_u64 v[152:153], s[46:47], 0, v[150:151]
	s_add_i32 m0, s52, 0xe000
	s_nop 0
	global_load_lds_dwordx4 v[152:153], off
	s_waitcnt vmcnt(8)
	s_waitcnt lgkmcnt(0)
	s_barrier
; #define PG8_STAGE(bufoff, gbase, voff) do { _Pragma("unroll") for (int _i = 0; _i < 2; ++_i) \
;         __builtin_amdgcn_global_load_lds((const unsigned*)((const char*)(gbase) + (voff)[_i]), (PG8_LAS unsigned*)(lds + (bufoff) + ldsw + _i * 8192), 16, 0, 0); } while (0)
; #define PG8_LDA(dst, b, h) do { _Pragma("unroll") for (int m = 0; m < 4; ++m) _Pragma("unroll") for (int k = 0; k < 2; ++k) dst[m][k] = *(const PG8_LAS bf16x8*)(lds + PG8_SA(b, h) + aoff + m * 2048 + k * 1024); } while (0)
; #define PG8_LDB(dst, b, h) do { _Pragma("unroll") for (int n = 0; n < 2; ++n) _Pragma("unroll") for (int k = 0; k < 2; ++k) dst[n][k] = *(const PG8_LAS bf16x8*)(lds + PG8_SB(b, h) + boff + n * 2048 + k * 1024); } while (0)
; #define PG8_MMA(ai, bj, At, Bt) do { __builtin_amdgcn_s_setprio(1); _Pragma("unroll") for (int m = 0; m < 4; ++m) _Pragma("unroll") for (int n = 0; n < 2; ++n) _Pragma("unroll") for (int k = 0; k < 2; ++k) \
;         acc[ai][bj][m][n] = __builtin_amdgcn_mfma_f32_16x16x32_bf16(Bt[n][k], At[m][k], acc[ai][bj][m][n], 0, 0, 0); __builtin_amdgcn_s_setprio(0); } while (0)
; #define PG8_WAIT_V(n) asm volatile("s_waitcnt vmcnt(" #n ")" ::: "memory")
; #define PG8_WAIT_L(n) asm volatile("s_waitcnt lgkmcnt(" #n ")" ::: "memory")
; #define PG8_BAR __builtin_amdgcn_s_barrier()
; #define PG8_SCHED __builtin_amdgcn_sched_barrier(0)
; template <class Epi, class Sched, bool ALIGN_EPI = false, bool SP2 = false>
; __device__ __forceinline__ void gemm_phase(PG8_LAS unsigned char* lds, const Gemm g, const Sched& S, const Epi& E) {
;     ...
;             PG8_LDB(B0, 0, 0); PG8_LDB(B1, 0, 1); PG8_SCHED; PG8_LDA(At, 0, 0); PG8_STAGE(PG8_SA(1, 1), a1 + hstep, voffA);
;             PG8_WAIT_V(8); PG8_WAIT_L(0); PG8_BAR; PG8_MMA(0, 0, At, B0); PG8_MMA(0, 1, At, B1); PG8_BAR; PG8_SCHED;
;             PG8_LDA(At, 0, 1); PG8_STAGE(PG8_SB(0, 0), b2, voffB); PG8_STAGE(PG8_SB(0, 1), b2 + hstep, voffB); PG8_STAGE(PG8_SA(0, 0), a2, voffA);
;             PG8_WAIT_V(8); PG8_WAIT_L(0); PG8_BAR; PG8_MMA(1, 0, At, B0); PG8_MMA(1, 1, At, B1); PG8_BAR; PG8_SCHED;
	s_waitcnt lgkmcnt(0)
	v_mfma_f32_16x16x32_bf16 v[134:137], v[50:53], v[186:189], v[134:137]
	v_mfma_f32_16x16x32_bf16 v[126:129], v[162:165], v[186:189], v[126:129]
	v_mfma_f32_16x16x32_bf16 v[118:121], v[50:53], v[202:205], v[118:121]
	v_mfma_f32_16x16x32_bf16 v[110:113], v[162:165], v[202:205], v[110:113]
	v_mfma_f32_16x16x32_bf16 v[102:105], v[50:53], v[222:225], v[102:105]
	v_mfma_f32_16x16x32_bf16 v[94:97], v[162:165], v[222:225], v[94:97]
	v_mfma_f32_16x16x32_bf16 v[86:89], v[50:53], v[230:233], v[86:89]
	v_mfma_f32_16x16x32_bf16 v[78:81], v[162:165], v[230:233], v[78:81]
	v_mfma_f32_16x16x32_bf16 v[134:137], v[54:57], v[198:201], v[134:137]
	v_mfma_f32_16x16x32_bf16 v[126:129], v[166:169], v[198:201], v[126:129]
	v_mfma_f32_16x16x32_bf16 v[118:121], v[54:57], v[206:209], v[118:121]
	v_mfma_f32_16x16x32_bf16 v[110:113], v[166:169], v[206:209], v[110:113]
	v_mfma_f32_16x16x32_bf16 v[102:105], v[54:57], v[226:229], v[102:105]
	v_mfma_f32_16x16x32_bf16 v[94:97], v[166:169], v[226:229], v[94:97]
	v_mfma_f32_16x16x32_bf16 v[86:89], v[54:57], v[234:237], v[86:89]
	v_mfma_f32_16x16x32_bf16 v[78:81], v[166:169], v[234:237], v[78:81]
	v_mfma_f32_16x16x32_bf16 v[130:133], v[170:173], v[186:189], v[130:133]
	v_mfma_f32_16x16x32_bf16 v[122:125], v[178:181], v[186:189], v[122:125]
	v_mfma_f32_16x16x32_bf16 v[114:117], v[170:173], v[202:205], v[114:117]
	v_mfma_f32_16x16x32_bf16 v[106:109], v[178:181], v[202:205], v[106:109]
	v_mfma_f32_16x16x32_bf16 v[98:101], v[170:173], v[222:225], v[98:101]
	v_mfma_f32_16x16x32_bf16 v[90:93], v[178:181], v[222:225], v[90:93]
	v_mfma_f32_16x16x32_bf16 v[82:85], v[170:173], v[230:233], v[82:85]
	v_mfma_f32_16x16x32_bf16 v[74:77], v[178:181], v[230:233], v[74:77]
	v_mfma_f32_16x16x32_bf16 v[130:133], v[174:177], v[198:201], v[130:133]
	v_mfma_f32_16x16x32_bf16 v[122:125], v[182:185], v[198:201], v[122:125]
	v_mfma_f32_16x16x32_bf16 v[114:117], v[174:177], v[206:209], v[114:117]
	v_mfma_f32_16x16x32_bf16 v[106:109], v[182:185], v[206:209], v[106:109]
	v_mfma_f32_16x16x32_bf16 v[98:101], v[174:177], v[226:229], v[98:101]
	v_mfma_f32_16x16x32_bf16 v[90:93], v[182:185], v[226:229], v[90:93]
	v_mfma_f32_16x16x32_bf16 v[82:85], v[174:177], v[234:237], v[82:85]
	v_mfma_f32_16x16x32_bf16 v[74:77], v[182:185], v[234:237], v[74:77]
	s_barrier
	s_add_i32 s30, s65, s33
	v_lshl_add_u64 v[152:153], s[48:49], 0, v[140:141]
	s_mov_b32 m0, s30
	ds_read_b128 v[186:189], v160 offset:16384
	ds_read_b128 v[198:201], v160 offset:17408
	ds_read_b128 v[202:205], v160 offset:18432
	ds_read_b128 v[206:209], v160 offset:19456
	ds_read_b128 v[222:225], v160 offset:20480
	ds_read_b128 v[226:229], v160 offset:21504
	ds_read_b128 v[230:233], v160 offset:22528
	ds_read_b128 v[234:237], v160 offset:23552
	global_load_lds_dwordx4 v[152:153], off
	s_add_i32 m0, s30, 0x2000
	s_add_u32 s30, s48, 0x40000
	v_lshl_add_u64 v[190:191], s[48:49], 0, v[144:145]
	s_addc_u32 s31, s49, 0
	s_add_i32 s65, s66, s33
	global_load_lds_dwordx4 v[190:191], off
	v_lshl_add_u64 v[210:211], s[30:31], 0, v[140:141]
	s_mov_b32 m0, s65
	v_lshl_add_u64 v[238:239], s[50:51], 0, v[142:143]
	global_load_lds_dwordx4 v[210:211], off
	v_lshl_add_u64 v[210:211], s[30:31], 0, v[144:145]
	s_add_i32 m0, s65, 0x2000
	s_nop 0
	global_load_lds_dwordx4 v[210:211], off
	v_lshl_add_u64 v[210:211], s[50:51], 0, v[138:139]
	s_mov_b32 m0, s52
	s_nop 0
	global_load_lds_dwordx4 v[210:211], off
	s_mov_b32 m0, s53
	s_nop 0
	global_load_lds_dwordx4 v[238:239], off
	s_waitcnt vmcnt(8)
	s_waitcnt lgkmcnt(0)
	s_barrier
	s_waitcnt lgkmcnt(0)
	v_mfma_f32_16x16x32_bf16 v[70:73], v[50:53], v[186:189], v[70:73]
	v_mfma_f32_16x16x32_bf16 v[62:65], v[162:165], v[186:189], v[62:65]
	v_mfma_f32_16x16x32_bf16 v[46:49], v[50:53], v[202:205], v[46:49]
	v_mfma_f32_16x16x32_bf16 v[38:41], v[162:165], v[202:205], v[38:41]
	v_mfma_f32_16x16x32_bf16 v[30:33], v[50:53], v[222:225], v[30:33]
	v_mfma_f32_16x16x32_bf16 v[22:25], v[162:165], v[222:225], v[22:25]
	v_mfma_f32_16x16x32_bf16 v[14:17], v[50:53], v[230:233], v[14:17]
	v_mfma_f32_16x16x32_bf16 v[6:9], v[162:165], v[230:233], v[6:9]
	v_mfma_f32_16x16x32_bf16 v[70:73], v[54:57], v[198:201], v[70:73]
	v_mfma_f32_16x16x32_bf16 v[62:65], v[166:169], v[198:201], v[62:65]
	v_mfma_f32_16x16x32_bf16 v[46:49], v[54:57], v[206:209], v[46:49]
	v_mfma_f32_16x16x32_bf16 v[38:41], v[166:169], v[206:209], v[38:41]
	v_mfma_f32_16x16x32_bf16 v[30:33], v[54:57], v[226:229], v[30:33]
	v_mfma_f32_16x16x32_bf16 v[22:25], v[166:169], v[226:229], v[22:25]
	v_mfma_f32_16x16x32_bf16 v[14:17], v[54:57], v[234:237], v[14:17]
	v_mfma_f32_16x16x32_bf16 v[6:9], v[166:169], v[234:237], v[6:9]
	v_mfma_f32_16x16x32_bf16 v[42:45], v[170:173], v[202:205], v[42:45]
	v_mfma_f32_16x16x32_bf16 v[34:37], v[178:181], v[202:205], v[34:37]
	v_mfma_f32_16x16x32_bf16 v[26:29], v[170:173], v[222:225], v[26:29]
	v_mfma_f32_16x16x32_bf16 v[18:21], v[178:181], v[222:225], v[18:21]
	v_mfma_f32_16x16x32_bf16 v[10:13], v[170:173], v[230:233], v[10:13]
	v_mfma_f32_16x16x32_bf16 v[2:5], v[178:181], v[230:233], v[2:5]
	v_mfma_f32_16x16x32_bf16 v[50:53], v[170:173], v[186:189], v[66:69]
	v_mfma_f32_16x16x32_bf16 v[54:57], v[178:181], v[186:189], v[58:61]
	v_mfma_f32_16x16x32_bf16 v[42:45], v[174:177], v[206:209], v[42:45]
	v_mfma_f32_16x16x32_bf16 v[34:37], v[182:185], v[206:209], v[34:37]
	v_mfma_f32_16x16x32_bf16 v[26:29], v[174:177], v[226:229], v[26:29]
	v_mfma_f32_16x16x32_bf16 v[18:21], v[182:185], v[226:229], v[18:21]
	v_mfma_f32_16x16x32_bf16 v[10:13], v[174:177], v[234:237], v[10:13]
	v_mfma_f32_16x16x32_bf16 v[2:5], v[182:185], v[234:237], v[2:5]
	v_mfma_f32_16x16x32_bf16 v[50:53], v[174:177], v[198:201], v[50:53]
	v_mfma_f32_16x16x32_bf16 v[54:57], v[182:185], v[198:201], v[54:57]
	s_barrier
; #define PG8_STAGE(bufoff, gbase, voff) do { _Pragma("unroll") for (int _i = 0; _i < 2; ++_i) \
;         __builtin_amdgcn_global_load_lds((const unsigned*)((const char*)(gbase) + (voff)[_i]), (PG8_LAS unsigned*)(lds + (bufoff) + ldsw + _i * 8192), 16, 0, 0); } while (0)
; #define PG8_LDA(dst, b, h) do { _Pragma("unroll") for (int m = 0; m < 4; ++m) _Pragma("unroll") for (int k = 0; k < 2; ++k) dst[m][k] = *(const PG8_LAS bf16x8*)(lds + PG8_SA(b, h) + aoff + m * 2048 + k * 1024); } while (0)
; #define PG8_LDB(dst, b, h) do { _Pragma("unroll") for (int n = 0; n < 2; ++n) _Pragma("unroll") for (int k = 0; k < 2; ++k) dst[n][k] = *(const PG8_LAS bf16x8*)(lds + PG8_SB(b, h) + boff + n * 2048 + k * 1024); } while (0)
; #define PG8_MMA(ai, bj, At, Bt) do { __builtin_amdgcn_s_setprio(1); _Pragma("unroll") for (int m = 0; m < 4; ++m) _Pragma("unroll") for (int n = 0; n < 2; ++n) _Pragma("unroll") for (int k = 0; k < 2; ++k) \
;         acc[ai][bj][m][n] = __builtin_amdgcn_mfma_f32_16x16x32_bf16(Bt[n][k], At[m][k], acc[ai][bj][m][n], 0, 0, 0); __builtin_amdgcn_s_setprio(0); } while (0)
; #define PG8_WAIT_V(n) asm volatile("s_waitcnt vmcnt(" #n ")" ::: "memory")
; #define PG8_WAIT_L(n) asm volatile("s_waitcnt lgkmcnt(" #n ")" ::: "memory")
; #define PG8_BAR __builtin_amdgcn_s_barrier()
; template <class Epi, class Sched, bool ALIGN_EPI = false, bool SP2 = false>
; __device__ __forceinline__ void gemm_phase(PG8_LAS unsigned char* lds, const Gemm g, const Sched& S, const Epi& E) {
;     ...
;         for (int t = 0; t < nt; t += 2) {
;             const bool last = (t == nt - 2);
;             const char* a1 = cA + (size_t)(t + 1) * kstep;
;             const char* a2 = last ? nA : cA + (size_t)(t + 2) * kstep; const char* b2 = last ? nB : cB + (size_t)(t + 2) * kstep;
;             const char* a3 = a2 + kstep; const char* b3 = b2 + kstep;
;     ...
;             PG8_LDB(B0, 1, 0); PG8_LDB(B1, 1, 1); PG8_SCHED; PG8_LDA(At, 1, 0); PG8_STAGE(PG8_SA(0, 1), a2 + hstep, voffA);
;             PG8_WAIT_V(8); PG8_WAIT_L(0); PG8_BAR; PG8_MMA(0, 0, At, B0); PG8_MMA(0, 1, At, B1); PG8_BAR; PG8_SCHED;
;             PG8_LDA(At, 1, 1); PG8_STAGE(PG8_SB(1, 0), b3, voffB); PG8_STAGE(PG8_SB(1, 1), b3 + hstep, voffB); PG8_STAGE(PG8_SA(1, 0), a3, voffA);
;             PG8_WAIT_V(8); PG8_WAIT_L(0); PG8_BAR; PG8_MMA(1, 0, At, B0); PG8_MMA(1, 1, At, B1); PG8_BAR; PG8_SCHED;
	s_add_i32 s65, 0, 0x18000
	v_add_u32_e32 v161, s65, v157
	s_add_i32 s66, 0, 0x1c000
	ds_read_b128 v[58:61], v161
	ds_read_b128 v[66:69], v161 offset:1024
	ds_read_b128 v[162:165], v161 offset:2048
	ds_read_b128 v[166:169], v161 offset:3072
	v_add_u32_e32 v161, s66, v157
	ds_read_b128 v[170:173], v161
	ds_read_b128 v[174:177], v161 offset:1024
	ds_read_b128 v[178:181], v161 offset:2048
	ds_read_b128 v[182:185], v161 offset:3072
	s_add_u32 s30, s50, 0x40000
	s_addc_u32 s31, s51, 0
	s_mov_b32 m0, s54
	v_lshl_add_u64 v[240:241], s[30:31], 0, v[138:139]
	ds_read_b128 v[186:189], v160 offset:32768
	ds_read_b128 v[198:201], v160 offset:33792
	ds_read_b128 v[202:205], v160 offset:34816
	ds_read_b128 v[206:209], v160 offset:35840
	ds_read_b128 v[222:225], v160 offset:36864
	ds_read_b128 v[226:229], v160 offset:37888
	ds_read_b128 v[230:233], v160 offset:38912
	ds_read_b128 v[234:237], v160 offset:39936
	global_load_lds_dwordx4 v[240:241], off
	v_lshl_add_u64 v[240:241], s[30:31], 0, v[142:143]
	s_mov_b32 m0, s55
	s_nop 0
	global_load_lds_dwordx4 v[240:241], off
	s_waitcnt vmcnt(8)
	s_waitcnt lgkmcnt(0)
	s_barrier
	s_waitcnt lgkmcnt(0)
	v_mfma_f32_16x16x32_bf16 v[134:137], v[58:61], v[186:189], v[134:137]
	v_mfma_f32_16x16x32_bf16 v[126:129], v[162:165], v[186:189], v[126:129]
	v_mfma_f32_16x16x32_bf16 v[118:121], v[58:61], v[202:205], v[118:121]
	v_mfma_f32_16x16x32_bf16 v[110:113], v[162:165], v[202:205], v[110:113]
	v_mfma_f32_16x16x32_bf16 v[102:105], v[58:61], v[222:225], v[102:105]
	v_mfma_f32_16x16x32_bf16 v[94:97], v[162:165], v[222:225], v[94:97]
	v_mfma_f32_16x16x32_bf16 v[86:89], v[58:61], v[230:233], v[86:89]
	v_mfma_f32_16x16x32_bf16 v[78:81], v[162:165], v[230:233], v[78:81]
	v_mfma_f32_16x16x32_bf16 v[134:137], v[66:69], v[198:201], v[134:137]
	v_mfma_f32_16x16x32_bf16 v[126:129], v[166:169], v[198:201], v[126:129]
	v_mfma_f32_16x16x32_bf16 v[118:121], v[66:69], v[206:209], v[118:121]
	v_mfma_f32_16x16x32_bf16 v[110:113], v[166:169], v[206:209], v[110:113]
	v_mfma_f32_16x16x32_bf16 v[102:105], v[66:69], v[226:229], v[102:105]
	v_mfma_f32_16x16x32_bf16 v[94:97], v[166:169], v[226:229], v[94:97]
	v_mfma_f32_16x16x32_bf16 v[86:89], v[66:69], v[234:237], v[86:89]
	v_mfma_f32_16x16x32_bf16 v[78:81], v[166:169], v[234:237], v[78:81]
	v_mfma_f32_16x16x32_bf16 v[130:133], v[170:173], v[186:189], v[130:133]
	v_mfma_f32_16x16x32_bf16 v[122:125], v[178:181], v[186:189], v[122:125]
	v_mfma_f32_16x16x32_bf16 v[114:117], v[170:173], v[202:205], v[114:117]
	v_mfma_f32_16x16x32_bf16 v[106:109], v[178:181], v[202:205], v[106:109]
	v_mfma_f32_16x16x32_bf16 v[98:101], v[170:173], v[222:225], v[98:101]
	v_mfma_f32_16x16x32_bf16 v[90:93], v[178:181], v[222:225], v[90:93]
	v_mfma_f32_16x16x32_bf16 v[82:85], v[170:173], v[230:233], v[82:85]
	v_mfma_f32_16x16x32_bf16 v[74:77], v[178:181], v[230:233], v[74:77]
	v_mfma_f32_16x16x32_bf16 v[130:133], v[174:177], v[198:201], v[130:133]
	v_mfma_f32_16x16x32_bf16 v[122:125], v[182:185], v[198:201], v[122:125]
	v_mfma_f32_16x16x32_bf16 v[114:117], v[174:177], v[206:209], v[114:117]
	v_mfma_f32_16x16x32_bf16 v[106:109], v[182:185], v[206:209], v[106:109]
	v_mfma_f32_16x16x32_bf16 v[98:101], v[174:177], v[226:229], v[98:101]
	v_mfma_f32_16x16x32_bf16 v[90:93], v[182:185], v[226:229], v[90:93]
	v_mfma_f32_16x16x32_bf16 v[82:85], v[174:177], v[234:237], v[82:85]
	v_mfma_f32_16x16x32_bf16 v[74:77], v[182:185], v[234:237], v[74:77]
	s_barrier
	s_add_i32 s30, s65, s33
	v_lshl_add_u64 v[152:153], v[152:153], 0, s[0:1]
	s_mov_b32 m0, s30
	ds_read_b128 v[186:189], v160 offset:49152
	ds_read_b128 v[198:201], v160 offset:50176
	ds_read_b128 v[202:205], v160 offset:51200
	ds_read_b128 v[206:209], v160 offset:52224
	ds_read_b128 v[222:225], v160 offset:53248
	ds_read_b128 v[226:229], v160 offset:54272
	ds_read_b128 v[230:233], v160 offset:55296
	ds_read_b128 v[234:237], v160 offset:56320
	global_load_lds_dwordx4 v[152:153], off
	s_add_i32 m0, s30, 0x2000
	s_add_u32 s30, s48, 0x40080
	v_lshl_add_u64 v[152:153], v[190:191], 0, s[0:1]
	s_addc_u32 s31, s49, 0
	s_add_i32 s48, s66, s33
	global_load_lds_dwordx4 v[152:153], off
	v_lshl_add_u64 v[152:153], s[30:31], 0, v[140:141]
	s_mov_b32 m0, s48
	s_nop 0
	global_load_lds_dwordx4 v[152:153], off
	v_lshl_add_u64 v[152:153], s[30:31], 0, v[144:145]
	s_add_i32 m0, s48, 0x2000
	s_nop 0
	global_load_lds_dwordx4 v[152:153], off
	v_lshl_add_u64 v[152:153], v[210:211], 0, s[0:1]
	s_mov_b32 m0, s56
	s_nop 0
	global_load_lds_dwordx4 v[152:153], off
	v_lshl_add_u64 v[152:153], v[238:239], 0, s[0:1]
	s_mov_b32 m0, s57
	s_nop 0
	global_load_lds_dwordx4 v[152:153], off
	s_waitcnt vmcnt(8)
	s_waitcnt lgkmcnt(0)
	s_barrier
	s_waitcnt lgkmcnt(0)
	v_mfma_f32_16x16x32_bf16 v[70:73], v[58:61], v[186:189], v[70:73]
	v_mfma_f32_16x16x32_bf16 v[62:65], v[162:165], v[186:189], v[62:65]
	v_mfma_f32_16x16x32_bf16 v[46:49], v[58:61], v[202:205], v[46:49]
	v_mfma_f32_16x16x32_bf16 v[38:41], v[162:165], v[202:205], v[38:41]
	v_mfma_f32_16x16x32_bf16 v[30:33], v[58:61], v[222:225], v[30:33]
	v_mfma_f32_16x16x32_bf16 v[22:25], v[162:165], v[222:225], v[22:25]
	v_mfma_f32_16x16x32_bf16 v[14:17], v[58:61], v[230:233], v[14:17]
	v_mfma_f32_16x16x32_bf16 v[6:9], v[162:165], v[230:233], v[6:9]
	v_mfma_f32_16x16x32_bf16 v[70:73], v[66:69], v[198:201], v[70:73]
	v_mfma_f32_16x16x32_bf16 v[62:65], v[166:169], v[198:201], v[62:65]
	v_mfma_f32_16x16x32_bf16 v[46:49], v[66:69], v[206:209], v[46:49]
	v_mfma_f32_16x16x32_bf16 v[38:41], v[166:169], v[206:209], v[38:41]
	v_mfma_f32_16x16x32_bf16 v[30:33], v[66:69], v[226:229], v[30:33]
	v_mfma_f32_16x16x32_bf16 v[22:25], v[166:169], v[226:229], v[22:25]
	v_mfma_f32_16x16x32_bf16 v[14:17], v[66:69], v[234:237], v[14:17]
	v_mfma_f32_16x16x32_bf16 v[6:9], v[166:169], v[234:237], v[6:9]
	v_mfma_f32_16x16x32_bf16 v[50:53], v[170:173], v[186:189], v[50:53]
	v_mfma_f32_16x16x32_bf16 v[66:69], v[174:177], v[198:201], v[50:53]
	v_mfma_f32_16x16x32_bf16 v[50:53], v[178:181], v[186:189], v[54:57]
	v_mfma_f32_16x16x32_bf16 v[42:45], v[170:173], v[202:205], v[42:45]
	v_mfma_f32_16x16x32_bf16 v[34:37], v[178:181], v[202:205], v[34:37]
	v_mfma_f32_16x16x32_bf16 v[26:29], v[170:173], v[222:225], v[26:29]
	v_mfma_f32_16x16x32_bf16 v[18:21], v[178:181], v[222:225], v[18:21]
	v_mfma_f32_16x16x32_bf16 v[10:13], v[170:173], v[230:233], v[10:13]
	v_mfma_f32_16x16x32_bf16 v[2:5], v[178:181], v[230:233], v[2:5]
	v_mfma_f32_16x16x32_bf16 v[58:61], v[182:185], v[198:201], v[50:53]
	v_mfma_f32_16x16x32_bf16 v[42:45], v[174:177], v[206:209], v[42:45]
	v_mfma_f32_16x16x32_bf16 v[34:37], v[182:185], v[206:209], v[34:37]
	v_mfma_f32_16x16x32_bf16 v[26:29], v[174:177], v[226:229], v[26:29]
	v_mfma_f32_16x16x32_bf16 v[18:21], v[182:185], v[226:229], v[18:21]
	v_mfma_f32_16x16x32_bf16 v[10:13], v[174:177], v[234:237], v[10:13]
	v_mfma_f32_16x16x32_bf16 v[2:5], v[182:185], v[234:237], v[2:5]
	s_barrier
	s_add_i32 s64, s64, 2
	s_add_u32 s46, s46, 0x100
	s_addc_u32 s47, s47, 0
	s_add_u32 s62, s62, 0x100
	s_addc_u32 s63, s63, 0
	s_cmp_gt_u32 s64, 13
	s_cbranch_scc0 .LBB0_781

; #define PG8_STAGE(bufoff, gbase, voff) do { _Pragma("unroll") for (int _i = 0; _i < 2; ++_i) \
;         __builtin_amdgcn_global_load_lds((const unsigned*)((const char*)(gbase) + (voff)[_i]), (PG8_LAS unsigned*)(lds + (bufoff) + ldsw + _i * 8192), 16, 0, 0); } while (0)
; #define PG8_LDA(dst, b, h) do { _Pragma("unroll") for (int m = 0; m < 4; ++m) _Pragma("unroll") for (int k = 0; k < 2; ++k) dst[m][k] = *(const PG8_LAS bf16x8*)(lds + PG8_SA(b, h) + aoff + m * 2048 + k * 1024); } while (0)
; #define PG8_LDB(dst, b, h) do { _Pragma("unroll") for (int n = 0; n < 2; ++n) _Pragma("unroll") for (int k = 0; k < 2; ++k) dst[n][k] = *(const PG8_LAS bf16x8*)(lds + PG8_SB(b, h) + boff + n * 2048 + k * 1024); } while (0)
; #define PG8_MMA(ai, bj, At, Bt) do { __builtin_amdgcn_s_setprio(1); _Pragma("unroll") for (int m = 0; m < 4; ++m) _Pragma("unroll") for (int n = 0; n < 2; ++n) _Pragma("unroll") for (int k = 0; k < 2; ++k) \
;         acc[ai][bj][m][n] = __builtin_amdgcn_mfma_f32_16x16x32_bf16(Bt[n][k], At[m][k], acc[ai][bj][m][n], 0, 0, 0); __builtin_amdgcn_s_setprio(0); } while (0)
; #define PG8_WAIT_V(n) asm volatile("s_waitcnt vmcnt(" #n ")" ::: "memory")
; template <class Epi, class Sched, bool ALIGN_EPI = false, bool SP2 = false>
; __device__ __forceinline__ void gemm_phase(PG8_LAS unsigned char* lds, const Gemm g, const Sched& S, const Epi& E) {
;     ...
;         const char* nA = has_next ? (const char*)g.A + (size_t)nxt.pm * tstep : cA; const char* nB = has_next ? (const char*)g.Bt + (size_t)nxt.pn * tstep : cB;
;         for (int t = 0; t < nt; t += 2) {
;             const bool last = (t == nt - 2);
;             const char* a1 = cA + (size_t)(t + 1) * kstep;
;             const char* a2 = last ? nA : cA + (size_t)(t + 2) * kstep; const char* b2 = last ? nB : cB + (size_t)(t + 2) * kstep;
;             const char* a3 = a2 + kstep; const char* b3 = b2 + kstep;
;             if (last && has_next) S.a_ready(nxt);
;             if constexpr (SP2) {
;             PG8_LDB(B0, 0, 0); PG8_LDB(B1, 0, 1); PG8_SCHED; PG8_LDA(At, 0, 0); PG8_STAGE(PG8_SA(1, 1), a1 + hstep, voffA);
;             PG8_WAIT_V(8); PG8_WAIT_L(0); PG8_BAR; PG8_MMA(0, 0, At, B0); PG8_MMA(0, 1, At, B1); PG8_BAR; PG8_SCHED;
;             PG8_LDA(At, 0, 1); PG8_STAGE(PG8_SB(0, 0), b2, voffB); PG8_STAGE(PG8_SB(0, 1), b2 + hstep, voffB); PG8_STAGE(PG8_SA(0, 0), a2, voffA);
.Lpeel_p5:
	s_add_u32 s42, s20, 0x100
	s_addc_u32 s43, s21, 0
	s_add_i32 s30, 0, 0x10000
	s_cmp_eq_u32 s59, 40
	s_cselect_b32 s47, s11, s43
	s_cselect_b32 s46, s10, s42
	s_cselect_b32 s45, s15, s35
	s_cselect_b32 s44, s14, s34
	s_add_i32 s31, 0, 0x14000
	v_add_u32_e32 v134, s30, v191
	v_add_u32_e32 v168, s31, v191
	ds_read_b128 v[114:117], v134
	ds_read_b128 v[126:129], v134 offset:1024
	ds_read_b128 v[130:133], v134 offset:2048
	ds_read_b128 v[134:137], v134 offset:3072
	ds_read_b128 v[146:149], v168
	ds_read_b128 v[150:153], v168 offset:1024
	ds_read_b128 v[154:157], v168 offset:2048
	ds_read_b128 v[168:171], v168 offset:3072
	v_lshl_add_u64 v[188:189], s[20:21], 0, v[164:165]
	s_add_i32 m0, s48, 0xc000
	ds_read_b128 v[172:175], v202
	ds_read_b128 v[176:179], v202 offset:1024
	ds_read_b128 v[180:183], v202 offset:2048
	ds_read_b128 v[184:187], v202 offset:3072
	ds_read_b128 v[198:201], v202 offset:4096
	ds_read_b128 v[204:207], v202 offset:5120
	ds_read_b128 v[208:211], v202 offset:6144
	ds_read_b128 v[222:225], v202 offset:7168
	global_load_lds_dwordx4 v[188:189], off
	v_lshl_add_u64 v[188:189], s[20:21], 0, v[166:167]
	s_add_i32 m0, s48, 0xe000
	s_nop 0
	global_load_lds_dwordx4 v[188:189], off
	s_waitcnt vmcnt(8)
	s_waitcnt lgkmcnt(0)
	s_barrier
	s_waitcnt lgkmcnt(0)
	v_mfma_f32_16x16x32_bf16 v[142:145], v[114:117], v[172:175], 0
	v_mfma_f32_16x16x32_bf16 v[138:141], v[130:133], v[172:175], 0
	v_mfma_f32_16x16x32_bf16 v[110:113], v[114:117], v[180:183], 0
	v_mfma_f32_16x16x32_bf16 v[106:109], v[130:133], v[180:183], 0
	v_mfma_f32_16x16x32_bf16 v[94:97], v[114:117], v[198:201], 0
	v_mfma_f32_16x16x32_bf16 v[90:93], v[130:133], v[198:201], 0
	v_mfma_f32_16x16x32_bf16 v[78:81], v[114:117], v[208:211], 0
	v_mfma_f32_16x16x32_bf16 v[74:77], v[130:133], v[208:211], 0
	v_mfma_f32_16x16x32_bf16 v[142:145], v[126:129], v[176:179], v[142:145]
	v_mfma_f32_16x16x32_bf16 v[138:141], v[134:137], v[176:179], v[138:141]
	v_mfma_f32_16x16x32_bf16 v[110:113], v[126:129], v[184:187], v[110:113]
	v_mfma_f32_16x16x32_bf16 v[106:109], v[134:137], v[184:187], v[106:109]
	v_mfma_f32_16x16x32_bf16 v[94:97], v[126:129], v[204:207], v[94:97]
	v_mfma_f32_16x16x32_bf16 v[90:93], v[134:137], v[204:207], v[90:93]
	v_mfma_f32_16x16x32_bf16 v[78:81], v[126:129], v[222:225], v[78:81]
	v_mfma_f32_16x16x32_bf16 v[74:77], v[134:137], v[222:225], v[74:77]
	v_mfma_f32_16x16x32_bf16 v[122:125], v[146:149], v[172:175], 0
	v_mfma_f32_16x16x32_bf16 v[118:121], v[154:157], v[172:175], 0
	v_mfma_f32_16x16x32_bf16 v[102:105], v[146:149], v[180:183], 0
	v_mfma_f32_16x16x32_bf16 v[98:101], v[154:157], v[180:183], 0
	v_mfma_f32_16x16x32_bf16 v[86:89], v[146:149], v[198:201], 0
	v_mfma_f32_16x16x32_bf16 v[82:85], v[154:157], v[198:201], 0
	v_mfma_f32_16x16x32_bf16 v[70:73], v[146:149], v[208:211], 0
	v_mfma_f32_16x16x32_bf16 v[66:69], v[154:157], v[208:211], 0
	v_mfma_f32_16x16x32_bf16 v[122:125], v[150:153], v[176:179], v[122:125]
	v_mfma_f32_16x16x32_bf16 v[118:121], v[168:171], v[176:179], v[118:121]
	v_mfma_f32_16x16x32_bf16 v[102:105], v[150:153], v[184:187], v[102:105]
	v_mfma_f32_16x16x32_bf16 v[98:101], v[168:171], v[184:187], v[98:101]
	v_mfma_f32_16x16x32_bf16 v[86:89], v[150:153], v[204:207], v[86:89]
	v_mfma_f32_16x16x32_bf16 v[82:85], v[168:171], v[204:207], v[82:85]
	v_mfma_f32_16x16x32_bf16 v[70:73], v[150:153], v[222:225], v[70:73]
	v_mfma_f32_16x16x32_bf16 v[66:69], v[168:171], v[222:225], v[66:69]
	s_barrier
	s_add_i32 s20, s30, s33
	v_lshl_add_u64 v[188:189], s[44:45], 0, v[0:1]
	s_mov_b32 m0, s20
	ds_read_b128 v[172:175], v202 offset:16384
	ds_read_b128 v[176:179], v202 offset:17408
	ds_read_b128 v[180:183], v202 offset:18432
	ds_read_b128 v[184:187], v202 offset:19456
	ds_read_b128 v[198:201], v202 offset:20480
	ds_read_b128 v[204:207], v202 offset:21504
	ds_read_b128 v[208:211], v202 offset:22528
	ds_read_b128 v[222:225], v202 offset:23552
	global_load_lds_dwordx4 v[188:189], off
	s_add_i32 m0, s20, 0x2000
	s_add_u32 s20, s44, 0xb0000
	v_lshl_add_u64 v[226:227], s[44:45], 0, v[158:159]
	s_addc_u32 s21, s45, 0
	s_add_i32 s30, s31, s33
	global_load_lds_dwordx4 v[226:227], off
	v_lshl_add_u64 v[228:229], s[20:21], 0, v[0:1]
	s_mov_b32 m0, s30
	v_lshl_add_u64 v[230:231], s[46:47], 0, v[160:161]
	global_load_lds_dwordx4 v[228:229], off
	v_lshl_add_u64 v[228:229], s[20:21], 0, v[158:159]
	s_add_i32 m0, s30, 0x2000
	s_nop 0
	global_load_lds_dwordx4 v[228:229], off
	v_lshl_add_u64 v[228:229], s[46:47], 0, v[162:163]
	s_mov_b32 m0, s48
	s_nop 0
	global_load_lds_dwordx4 v[228:229], off
	s_mov_b32 m0, s49
	s_nop 0
	global_load_lds_dwordx4 v[230:231], off
	s_waitcnt vmcnt(8)
	s_waitcnt lgkmcnt(0)
	s_barrier
; #define PG8_STAGE(bufoff, gbase, voff) do { _Pragma("unroll") for (int _i = 0; _i < 2; ++_i) \
;         __builtin_amdgcn_global_load_lds((const unsigned*)((const char*)(gbase) + (voff)[_i]), (PG8_LAS unsigned*)(lds + (bufoff) + ldsw + _i * 8192), 16, 0, 0); } while (0)
; #define PG8_LDA(dst, b, h) do { _Pragma("unroll") for (int m = 0; m < 4; ++m) _Pragma("unroll") for (int k = 0; k < 2; ++k) dst[m][k] = *(const PG8_LAS bf16x8*)(lds + PG8_SA(b, h) + aoff + m * 2048 + k * 1024); } while (0)
; #define PG8_LDB(dst, b, h) do { _Pragma("unroll") for (int n = 0; n < 2; ++n) _Pragma("unroll") for (int k = 0; k < 2; ++k) dst[n][k] = *(const PG8_LAS bf16x8*)(lds + PG8_SB(b, h) + boff + n * 2048 + k * 1024); } while (0)
; #define PG8_MMA(ai, bj, At, Bt) do { __builtin_amdgcn_s_setprio(1); _Pragma("unroll") for (int m = 0; m < 4; ++m) _Pragma("unroll") for (int n = 0; n < 2; ++n) _Pragma("unroll") for (int k = 0; k < 2; ++k) \
;         acc[ai][bj][m][n] = __builtin_amdgcn_mfma_f32_16x16x32_bf16(Bt[n][k], At[m][k], acc[ai][bj][m][n], 0, 0, 0); __builtin_amdgcn_s_setprio(0); } while (0)
; #define PG8_WAIT_V(n) asm volatile("s_waitcnt vmcnt(" #n ")" ::: "memory")
; #define PG8_WAIT_L(n) asm volatile("s_waitcnt lgkmcnt(" #n ")" ::: "memory")
; #define PG8_BAR __builtin_amdgcn_s_barrier()
; #define PG8_SCHED __builtin_amdgcn_sched_barrier(0)
; template <class Epi, class Sched, bool ALIGN_EPI = false, bool SP2 = false>
; __device__ __forceinline__ void gemm_phase(PG8_LAS unsigned char* lds, const Gemm g, const Sched& S, const Epi& E) {
;     ...
;             PG8_WAIT_V(8); PG8_WAIT_L(0); PG8_BAR; PG8_MMA(0, 0, At, B0); PG8_MMA(0, 1, At, B1); PG8_BAR; PG8_SCHED;
;             PG8_LDA(At, 0, 1); PG8_STAGE(PG8_SB(0, 0), b2, voffB); PG8_STAGE(PG8_SB(0, 1), b2 + hstep, voffB); PG8_STAGE(PG8_SA(0, 0), a2, voffA);
;             PG8_WAIT_V(8); PG8_WAIT_L(0); PG8_BAR; PG8_MMA(1, 0, At, B0); PG8_MMA(1, 1, At, B1); PG8_BAR; PG8_SCHED;
;             PG8_LDB(B0, 1, 0); PG8_LDB(B1, 1, 1); PG8_SCHED; PG8_LDA(At, 1, 0); PG8_STAGE(PG8_SA(0, 1), a2 + hstep, voffA);
;             PG8_WAIT_V(8); PG8_WAIT_L(0); PG8_BAR; PG8_MMA(0, 0, At, B0); PG8_MMA(0, 1, At, B1); PG8_BAR; PG8_SCHED;
	s_waitcnt lgkmcnt(0)
	v_mfma_f32_16x16x32_bf16 v[62:65], v[114:117], v[172:175], 0
	v_mfma_f32_16x16x32_bf16 v[58:61], v[130:133], v[172:175], 0
	v_mfma_f32_16x16x32_bf16 v[46:49], v[114:117], v[180:183], 0
	v_mfma_f32_16x16x32_bf16 v[42:45], v[130:133], v[180:183], 0
	v_mfma_f32_16x16x32_bf16 v[30:33], v[114:117], v[198:201], 0
	v_mfma_f32_16x16x32_bf16 v[26:29], v[130:133], v[198:201], 0
	v_mfma_f32_16x16x32_bf16 v[14:17], v[114:117], v[208:211], 0
	v_mfma_f32_16x16x32_bf16 v[10:13], v[130:133], v[208:211], 0
	v_mfma_f32_16x16x32_bf16 v[62:65], v[126:129], v[176:179], v[62:65]
	v_mfma_f32_16x16x32_bf16 v[58:61], v[134:137], v[176:179], v[58:61]
	v_mfma_f32_16x16x32_bf16 v[46:49], v[126:129], v[184:187], v[46:49]
	v_mfma_f32_16x16x32_bf16 v[42:45], v[134:137], v[184:187], v[42:45]
	v_mfma_f32_16x16x32_bf16 v[30:33], v[126:129], v[204:207], v[30:33]
	v_mfma_f32_16x16x32_bf16 v[26:29], v[134:137], v[204:207], v[26:29]
	v_mfma_f32_16x16x32_bf16 v[14:17], v[126:129], v[222:225], v[14:17]
	v_mfma_f32_16x16x32_bf16 v[10:13], v[134:137], v[222:225], v[10:13]
	v_mfma_f32_16x16x32_bf16 v[54:57], v[146:149], v[172:175], 0
	v_mfma_f32_16x16x32_bf16 v[50:53], v[154:157], v[172:175], 0
	v_mfma_f32_16x16x32_bf16 v[38:41], v[146:149], v[180:183], 0
	v_mfma_f32_16x16x32_bf16 v[34:37], v[154:157], v[180:183], 0
	v_mfma_f32_16x16x32_bf16 v[22:25], v[146:149], v[198:201], 0
	v_mfma_f32_16x16x32_bf16 v[18:21], v[154:157], v[198:201], 0
	v_mfma_f32_16x16x32_bf16 v[6:9], v[146:149], v[208:211], 0
	v_mfma_f32_16x16x32_bf16 v[2:5], v[154:157], v[208:211], 0
	v_mfma_f32_16x16x32_bf16 v[54:57], v[150:153], v[176:179], v[54:57]
	v_mfma_f32_16x16x32_bf16 v[50:53], v[168:171], v[176:179], v[50:53]
	v_mfma_f32_16x16x32_bf16 v[38:41], v[150:153], v[184:187], v[38:41]
	v_mfma_f32_16x16x32_bf16 v[34:37], v[168:171], v[184:187], v[34:37]
	v_mfma_f32_16x16x32_bf16 v[22:25], v[150:153], v[204:207], v[22:25]
	v_mfma_f32_16x16x32_bf16 v[18:21], v[168:171], v[204:207], v[18:21]
	v_mfma_f32_16x16x32_bf16 v[6:9], v[150:153], v[222:225], v[6:9]
	v_mfma_f32_16x16x32_bf16 v[2:5], v[168:171], v[222:225], v[2:5]
	s_barrier
	s_add_i32 s30, 0, 0x18000
	s_add_i32 s31, 0, 0x1c000
	v_add_u32_e32 v134, s30, v191
	v_add_u32_e32 v168, s31, v191
	ds_read_b128 v[114:117], v134
	ds_read_b128 v[126:129], v134 offset:1024
	ds_read_b128 v[130:133], v134 offset:2048
	ds_read_b128 v[134:137], v134 offset:3072
	ds_read_b128 v[146:149], v168
	ds_read_b128 v[150:153], v168 offset:1024
	ds_read_b128 v[154:157], v168 offset:2048
	ds_read_b128 v[168:171], v168 offset:3072
	s_add_u32 s20, s46, 0xb0000
	s_addc_u32 s21, s47, 0
	s_mov_b32 m0, s50
	v_lshl_add_u64 v[232:233], s[20:21], 0, v[162:163]
	ds_read_b128 v[172:175], v202 offset:32768
	ds_read_b128 v[176:179], v202 offset:33792
	ds_read_b128 v[180:183], v202 offset:34816
	ds_read_b128 v[184:187], v202 offset:35840
	ds_read_b128 v[198:201], v202 offset:36864
	ds_read_b128 v[204:207], v202 offset:37888
	ds_read_b128 v[208:211], v202 offset:38912
	ds_read_b128 v[222:225], v202 offset:39936
	global_load_lds_dwordx4 v[232:233], off
	v_lshl_add_u64 v[232:233], s[20:21], 0, v[160:161]
	s_mov_b32 m0, s51
	s_nop 0
	global_load_lds_dwordx4 v[232:233], off
	s_waitcnt vmcnt(8)
	s_waitcnt lgkmcnt(0)
	s_barrier
	s_waitcnt lgkmcnt(0)
	v_mfma_f32_16x16x32_bf16 v[142:145], v[114:117], v[172:175], v[142:145]
	v_mfma_f32_16x16x32_bf16 v[138:141], v[130:133], v[172:175], v[138:141]
	v_mfma_f32_16x16x32_bf16 v[110:113], v[114:117], v[180:183], v[110:113]
	v_mfma_f32_16x16x32_bf16 v[106:109], v[130:133], v[180:183], v[106:109]
	v_mfma_f32_16x16x32_bf16 v[94:97], v[114:117], v[198:201], v[94:97]
	v_mfma_f32_16x16x32_bf16 v[90:93], v[130:133], v[198:201], v[90:93]
	v_mfma_f32_16x16x32_bf16 v[78:81], v[114:117], v[208:211], v[78:81]
	v_mfma_f32_16x16x32_bf16 v[74:77], v[130:133], v[208:211], v[74:77]
	v_mfma_f32_16x16x32_bf16 v[142:145], v[126:129], v[176:179], v[142:145]
	v_mfma_f32_16x16x32_bf16 v[138:141], v[134:137], v[176:179], v[138:141]
	v_mfma_f32_16x16x32_bf16 v[110:113], v[126:129], v[184:187], v[110:113]
	v_mfma_f32_16x16x32_bf16 v[106:109], v[134:137], v[184:187], v[106:109]
	v_mfma_f32_16x16x32_bf16 v[94:97], v[126:129], v[204:207], v[94:97]
	v_mfma_f32_16x16x32_bf16 v[90:93], v[134:137], v[204:207], v[90:93]
	v_mfma_f32_16x16x32_bf16 v[78:81], v[126:129], v[222:225], v[78:81]
	v_mfma_f32_16x16x32_bf16 v[74:77], v[134:137], v[222:225], v[74:77]
	v_mfma_f32_16x16x32_bf16 v[122:125], v[146:149], v[172:175], v[122:125]
	v_mfma_f32_16x16x32_bf16 v[118:121], v[154:157], v[172:175], v[118:121]
	v_mfma_f32_16x16x32_bf16 v[102:105], v[146:149], v[180:183], v[102:105]
	v_mfma_f32_16x16x32_bf16 v[98:101], v[154:157], v[180:183], v[98:101]
	v_mfma_f32_16x16x32_bf16 v[86:89], v[146:149], v[198:201], v[86:89]
	v_mfma_f32_16x16x32_bf16 v[82:85], v[154:157], v[198:201], v[82:85]
	v_mfma_f32_16x16x32_bf16 v[70:73], v[146:149], v[208:211], v[70:73]
	v_mfma_f32_16x16x32_bf16 v[66:69], v[154:157], v[208:211], v[66:69]
	v_mfma_f32_16x16x32_bf16 v[122:125], v[150:153], v[176:179], v[122:125]
	v_mfma_f32_16x16x32_bf16 v[118:121], v[168:171], v[176:179], v[118:121]
	v_mfma_f32_16x16x32_bf16 v[102:105], v[150:153], v[184:187], v[102:105]
	v_mfma_f32_16x16x32_bf16 v[98:101], v[168:171], v[184:187], v[98:101]
	v_mfma_f32_16x16x32_bf16 v[86:89], v[150:153], v[204:207], v[86:89]
	v_mfma_f32_16x16x32_bf16 v[82:85], v[168:171], v[204:207], v[82:85]
	v_mfma_f32_16x16x32_bf16 v[70:73], v[150:153], v[222:225], v[70:73]
	v_mfma_f32_16x16x32_bf16 v[66:69], v[168:171], v[222:225], v[66:69]
	s_barrier
; #define PG8_STAGE(bufoff, gbase, voff) do { _Pragma("unroll") for (int _i = 0; _i < 2; ++_i) \
;         __builtin_amdgcn_global_load_lds((const unsigned*)((const char*)(gbase) + (voff)[_i]), (PG8_LAS unsigned*)(lds + (bufoff) + ldsw + _i * 8192), 16, 0, 0); } while (0)
; #define PG8_LDA(dst, b, h) do { _Pragma("unroll") for (int m = 0; m < 4; ++m) _Pragma("unroll") for (int k = 0; k < 2; ++k) dst[m][k] = *(const PG8_LAS bf16x8*)(lds + PG8_SA(b, h) + aoff + m * 2048 + k * 1024); } while (0)
; #define PG8_LDB(dst, b, h) do { _Pragma("unroll") for (int n = 0; n < 2; ++n) _Pragma("unroll") for (int k = 0; k < 2; ++k) dst[n][k] = *(const PG8_LAS bf16x8*)(lds + PG8_SB(b, h) + boff + n * 2048 + k * 1024); } while (0)
; template <class Epi, class Sched, bool ALIGN_EPI = false, bool SP2 = false>
; __device__ __forceinline__ void gemm_phase(PG8_LAS unsigned char* lds, const Gemm g, const Sched& S, const Epi& E) {
;     ...
;         for (int t = 0; t < nt; t += 2) {
;             const bool last = (t == nt - 2);
;             const char* a1 = cA + (size_t)(t + 1) * kstep;
;             const char* a2 = last ? nA : cA + (size_t)(t + 2) * kstep; const char* b2 = last ? nB : cB + (size_t)(t + 2) * kstep;
;             const char* a3 = a2 + kstep; const char* b3 = b2 + kstep;
;             if (last && has_next) S.a_ready(nxt);
;             if constexpr (SP2) {
;             PG8_LDB(B0, 0, 0); PG8_LDB(B1, 0, 1); PG8_SCHED; PG8_LDA(At, 0, 0); PG8_STAGE(PG8_SA(1, 1), a1 + hstep, voffA);
;             PG8_WAIT_V(8); PG8_WAIT_L(0); PG8_BAR; PG8_MMA(0, 0, At, B0); PG8_MMA(0, 1, At, B1); PG8_BAR; PG8_SCHED;
;             PG8_LDA(At, 0, 1); PG8_STAGE(PG8_SB(0, 0), b2, voffB); PG8_STAGE(PG8_SB(0, 1), b2 + hstep, voffB); PG8_STAGE(PG8_SA(0, 0), a2, voffA);
;             PG8_WAIT_V(8); PG8_WAIT_L(0); PG8_BAR; PG8_MMA(1, 0, At, B0); PG8_MMA(1, 1, At, B1); PG8_BAR; PG8_SCHED;
;             PG8_LDB(B0, 1, 0); PG8_LDB(B1, 1, 1); PG8_SCHED; PG8_LDA(At, 1, 0); PG8_STAGE(PG8_SA(0, 1), a2 + hstep, voffA);
;             PG8_WAIT_V(8); PG8_WAIT_L(0); PG8_BAR; PG8_MMA(0, 0, At, B0); PG8_MMA(0, 1, At, B1); PG8_BAR; PG8_SCHED;
;             PG8_LDA(At, 1, 1); PG8_STAGE(PG8_SB(1, 0), b3, voffB); PG8_STAGE(PG8_SB(1, 1), b3 + hstep, voffB); PG8_STAGE(PG8_SA(1, 0), a3, voffA);
;             PG8_WAIT_V(8); PG8_WAIT_L(0); PG8_BAR; PG8_MMA(1, 0, At, B0); PG8_MMA(1, 1, At, B1); PG8_BAR; PG8_SCHED;
	s_add_i32 s20, s30, s33
	v_lshl_add_u64 v[188:189], v[188:189], 0, s[0:1]
	s_mov_b32 m0, s20
	ds_read_b128 v[172:175], v202 offset:49152
	ds_read_b128 v[176:179], v202 offset:50176
	ds_read_b128 v[180:183], v202 offset:51200
	ds_read_b128 v[184:187], v202 offset:52224
	ds_read_b128 v[198:201], v202 offset:53248
	ds_read_b128 v[204:207], v202 offset:54272
	ds_read_b128 v[208:211], v202 offset:55296
	ds_read_b128 v[222:225], v202 offset:56320
	global_load_lds_dwordx4 v[188:189], off
	s_add_i32 m0, s20, 0x2000
	s_add_u32 s20, s44, 0xb0080
	v_lshl_add_u64 v[188:189], v[226:227], 0, s[0:1]
	s_addc_u32 s21, s45, 0
	s_add_i32 s30, s31, s33
	global_load_lds_dwordx4 v[188:189], off
	v_lshl_add_u64 v[188:189], s[20:21], 0, v[0:1]
	s_mov_b32 m0, s30
	s_nop 0
	global_load_lds_dwordx4 v[188:189], off
	v_lshl_add_u64 v[188:189], s[20:21], 0, v[158:159]
	s_add_i32 m0, s30, 0x2000
	s_nop 0
	global_load_lds_dwordx4 v[188:189], off
	v_lshl_add_u64 v[188:189], v[228:229], 0, s[0:1]
	s_mov_b32 m0, s54
	s_nop 0
	global_load_lds_dwordx4 v[188:189], off
	v_lshl_add_u64 v[188:189], v[230:231], 0, s[0:1]
	s_mov_b32 m0, s55
	s_nop 0
	global_load_lds_dwordx4 v[188:189], off
	s_waitcnt vmcnt(8)
	s_waitcnt lgkmcnt(0)
	s_barrier
	s_waitcnt lgkmcnt(0)
	v_mfma_f32_16x16x32_bf16 v[62:65], v[114:117], v[172:175], v[62:65]
	v_mfma_f32_16x16x32_bf16 v[58:61], v[130:133], v[172:175], v[58:61]
	v_mfma_f32_16x16x32_bf16 v[46:49], v[114:117], v[180:183], v[46:49]
	v_mfma_f32_16x16x32_bf16 v[42:45], v[130:133], v[180:183], v[42:45]
	v_mfma_f32_16x16x32_bf16 v[30:33], v[114:117], v[198:201], v[30:33]
	v_mfma_f32_16x16x32_bf16 v[26:29], v[130:133], v[198:201], v[26:29]
	v_mfma_f32_16x16x32_bf16 v[14:17], v[114:117], v[208:211], v[14:17]
	v_mfma_f32_16x16x32_bf16 v[10:13], v[130:133], v[208:211], v[10:13]
	v_mfma_f32_16x16x32_bf16 v[62:65], v[126:129], v[176:179], v[62:65]
	v_mfma_f32_16x16x32_bf16 v[58:61], v[134:137], v[176:179], v[58:61]
	v_mfma_f32_16x16x32_bf16 v[46:49], v[126:129], v[184:187], v[46:49]
	v_mfma_f32_16x16x32_bf16 v[42:45], v[134:137], v[184:187], v[42:45]
	v_mfma_f32_16x16x32_bf16 v[30:33], v[126:129], v[204:207], v[30:33]
	v_mfma_f32_16x16x32_bf16 v[26:29], v[134:137], v[204:207], v[26:29]
	v_mfma_f32_16x16x32_bf16 v[14:17], v[126:129], v[222:225], v[14:17]
	v_mfma_f32_16x16x32_bf16 v[10:13], v[134:137], v[222:225], v[10:13]
	v_mfma_f32_16x16x32_bf16 v[54:57], v[146:149], v[172:175], v[54:57]
	v_mfma_f32_16x16x32_bf16 v[50:53], v[154:157], v[172:175], v[50:53]
	v_mfma_f32_16x16x32_bf16 v[38:41], v[146:149], v[180:183], v[38:41]
	v_mfma_f32_16x16x32_bf16 v[34:37], v[154:157], v[180:183], v[34:37]
	v_mfma_f32_16x16x32_bf16 v[22:25], v[146:149], v[198:201], v[22:25]
	v_mfma_f32_16x16x32_bf16 v[18:21], v[154:157], v[198:201], v[18:21]
	v_mfma_f32_16x16x32_bf16 v[6:9], v[146:149], v[208:211], v[6:9]
	v_mfma_f32_16x16x32_bf16 v[2:5], v[154:157], v[208:211], v[2:5]
	v_mfma_f32_16x16x32_bf16 v[54:57], v[150:153], v[176:179], v[54:57]
	v_mfma_f32_16x16x32_bf16 v[50:53], v[168:171], v[176:179], v[50:53]
	v_mfma_f32_16x16x32_bf16 v[38:41], v[150:153], v[184:187], v[38:41]
	v_mfma_f32_16x16x32_bf16 v[34:37], v[168:171], v[184:187], v[34:37]
	v_mfma_f32_16x16x32_bf16 v[22:25], v[150:153], v[204:207], v[22:25]
	v_mfma_f32_16x16x32_bf16 v[18:21], v[168:171], v[204:207], v[18:21]
	v_mfma_f32_16x16x32_bf16 v[6:9], v[150:153], v[222:225], v[6:9]
	v_mfma_f32_16x16x32_bf16 v[2:5], v[168:171], v[222:225], v[2:5]
	s_barrier
	s_add_i32 s59, s59, 2
	s_add_u32 s34, s34, 0x100
	s_addc_u32 s35, s35, 0
	s_cmp_gt_u32 s59, 41
	s_mov_b64 s[20:21], s[42:43]
	s_cbranch_scc0 .LBB0_868
	s_branch .Lpeel_exit_p5
.LBB0_868:
	s_add_u32 s42, s20, 0x100
	s_addc_u32 s43, s21, 0
	s_add_i32 s30, 0, 0x10000
	s_cmp_eq_u32 s59, 40
	s_cselect_b32 s47, s11, s43
	s_cselect_b32 s46, s10, s42
	s_cselect_b32 s45, s15, s35
	s_cselect_b32 s44, s14, s34
	s_add_i32 s31, 0, 0x14000
	v_add_u32_e32 v134, s30, v191
	v_add_u32_e32 v168, s31, v191
	ds_read_b128 v[114:117], v134
	ds_read_b128 v[126:129], v134 offset:1024
	ds_read_b128 v[130:133], v134 offset:2048
	ds_read_b128 v[134:137], v134 offset:3072
	ds_read_b128 v[146:149], v168
	ds_read_b128 v[150:153], v168 offset:1024
	ds_read_b128 v[154:157], v168 offset:2048
	ds_read_b128 v[168:171], v168 offset:3072
	v_lshl_add_u64 v[188:189], s[20:21], 0, v[164:165]
	s_add_i32 m0, s48, 0xc000
	ds_read_b128 v[172:175], v202
	ds_read_b128 v[176:179], v202 offset:1024
	ds_read_b128 v[180:183], v202 offset:2048
	ds_read_b128 v[184:187], v202 offset:3072
	ds_read_b128 v[198:201], v202 offset:4096
	ds_read_b128 v[204:207], v202 offset:5120
	ds_read_b128 v[208:211], v202 offset:6144
	ds_read_b128 v[222:225], v202 offset:7168
	global_load_lds_dwordx4 v[188:189], off
	v_lshl_add_u64 v[188:189], s[20:21], 0, v[166:167]
	s_add_i32 m0, s48, 0xe000
	s_nop 0
	global_load_lds_dwordx4 v[188:189], off
	s_waitcnt vmcnt(8)
	s_waitcnt lgkmcnt(0)
	s_barrier
; #define PG8_STAGE(bufoff, gbase, voff) do { _Pragma("unroll") for (int _i = 0; _i < 2; ++_i) \
;         __builtin_amdgcn_global_load_lds((const unsigned*)((const char*)(gbase) + (voff)[_i]), (PG8_LAS unsigned*)(lds + (bufoff) + ldsw + _i * 8192), 16, 0, 0); } while (0)
; #define PG8_LDA(dst, b, h) do { _Pragma("unroll") for (int m = 0; m < 4; ++m) _Pragma("unroll") for (int k = 0; k < 2; ++k) dst[m][k] = *(const PG8_LAS bf16x8*)(lds + PG8_SA(b, h) + aoff + m * 2048 + k * 1024); } while (0)
; #define PG8_LDB(dst, b, h) do { _Pragma("unroll") for (int n = 0; n < 2; ++n) _Pragma("unroll") for (int k = 0; k < 2; ++k) dst[n][k] = *(const PG8_LAS bf16x8*)(lds + PG8_SB(b, h) + boff + n * 2048 + k * 1024); } while (0)
; #define PG8_MMA(ai, bj, At, Bt) do { __builtin_amdgcn_s_setprio(1); _Pragma("unroll") for (int m = 0; m < 4; ++m) _Pragma("unroll") for (int n = 0; n < 2; ++n) _Pragma("unroll") for (int k = 0; k < 2; ++k) \
;         acc[ai][bj][m][n] = __builtin_amdgcn_mfma_f32_16x16x32_bf16(Bt[n][k], At[m][k], acc[ai][bj][m][n], 0, 0, 0); __builtin_amdgcn_s_setprio(0); } while (0)
; #define PG8_WAIT_V(n) asm volatile("s_waitcnt vmcnt(" #n ")" ::: "memory")
; #define PG8_WAIT_L(n) asm volatile("s_waitcnt lgkmcnt(" #n ")" ::: "memory")
; #define PG8_BAR __builtin_amdgcn_s_barrier()
; #define PG8_SCHED __builtin_amdgcn_sched_barrier(0)
; template <class Epi, class Sched, bool ALIGN_EPI = false, bool SP2 = false>
; __device__ __forceinline__ void gemm_phase(PG8_LAS unsigned char* lds, const Gemm g, const Sched& S, const Epi& E) {
;     ...
;             PG8_LDB(B0, 0, 0); PG8_LDB(B1, 0, 1); PG8_SCHED; PG8_LDA(At, 0, 0); PG8_STAGE(PG8_SA(1, 1), a1 + hstep, voffA);
;             PG8_WAIT_V(8); PG8_WAIT_L(0); PG8_BAR; PG8_MMA(0, 0, At, B0); PG8_MMA(0, 1, At, B1); PG8_BAR; PG8_SCHED;
;             PG8_LDA(At, 0, 1); PG8_STAGE(PG8_SB(0, 0), b2, voffB); PG8_STAGE(PG8_SB(0, 1), b2 + hstep, voffB); PG8_STAGE(PG8_SA(0, 0), a2, voffA);
;             PG8_WAIT_V(8); PG8_WAIT_L(0); PG8_BAR; PG8_MMA(1, 0, At, B0); PG8_MMA(1, 1, At, B1); PG8_BAR; PG8_SCHED;
	s_waitcnt lgkmcnt(0)
	v_mfma_f32_16x16x32_bf16 v[142:145], v[114:117], v[172:175], v[142:145]
	v_mfma_f32_16x16x32_bf16 v[138:141], v[130:133], v[172:175], v[138:141]
	v_mfma_f32_16x16x32_bf16 v[110:113], v[114:117], v[180:183], v[110:113]
	v_mfma_f32_16x16x32_bf16 v[106:109], v[130:133], v[180:183], v[106:109]
	v_mfma_f32_16x16x32_bf16 v[94:97], v[114:117], v[198:201], v[94:97]
	v_mfma_f32_16x16x32_bf16 v[90:93], v[130:133], v[198:201], v[90:93]
	v_mfma_f32_16x16x32_bf16 v[78:81], v[114:117], v[208:211], v[78:81]
	v_mfma_f32_16x16x32_bf16 v[74:77], v[130:133], v[208:211], v[74:77]
	v_mfma_f32_16x16x32_bf16 v[142:145], v[126:129], v[176:179], v[142:145]
	v_mfma_f32_16x16x32_bf16 v[138:141], v[134:137], v[176:179], v[138:141]
	v_mfma_f32_16x16x32_bf16 v[110:113], v[126:129], v[184:187], v[110:113]
	v_mfma_f32_16x16x32_bf16 v[106:109], v[134:137], v[184:187], v[106:109]
	v_mfma_f32_16x16x32_bf16 v[94:97], v[126:129], v[204:207], v[94:97]
	v_mfma_f32_16x16x32_bf16 v[90:93], v[134:137], v[204:207], v[90:93]
	v_mfma_f32_16x16x32_bf16 v[78:81], v[126:129], v[222:225], v[78:81]
	v_mfma_f32_16x16x32_bf16 v[74:77], v[134:137], v[222:225], v[74:77]
	v_mfma_f32_16x16x32_bf16 v[122:125], v[146:149], v[172:175], v[122:125]
	v_mfma_f32_16x16x32_bf16 v[118:121], v[154:157], v[172:175], v[118:121]
	v_mfma_f32_16x16x32_bf16 v[102:105], v[146:149], v[180:183], v[102:105]
	v_mfma_f32_16x16x32_bf16 v[98:101], v[154:157], v[180:183], v[98:101]
	v_mfma_f32_16x16x32_bf16 v[86:89], v[146:149], v[198:201], v[86:89]
	v_mfma_f32_16x16x32_bf16 v[82:85], v[154:157], v[198:201], v[82:85]
	v_mfma_f32_16x16x32_bf16 v[70:73], v[146:149], v[208:211], v[70:73]
	v_mfma_f32_16x16x32_bf16 v[66:69], v[154:157], v[208:211], v[66:69]
	v_mfma_f32_16x16x32_bf16 v[122:125], v[150:153], v[176:179], v[122:125]
	v_mfma_f32_16x16x32_bf16 v[118:121], v[168:171], v[176:179], v[118:121]
	v_mfma_f32_16x16x32_bf16 v[102:105], v[150:153], v[184:187], v[102:105]
	v_mfma_f32_16x16x32_bf16 v[98:101], v[168:171], v[184:187], v[98:101]
	v_mfma_f32_16x16x32_bf16 v[86:89], v[150:153], v[204:207], v[86:89]
	v_mfma_f32_16x16x32_bf16 v[82:85], v[168:171], v[204:207], v[82:85]
	v_mfma_f32_16x16x32_bf16 v[70:73], v[150:153], v[222:225], v[70:73]
	v_mfma_f32_16x16x32_bf16 v[66:69], v[168:171], v[222:225], v[66:69]
	s_barrier
	s_add_i32 s20, s30, s33
	v_lshl_add_u64 v[188:189], s[44:45], 0, v[0:1]
	s_mov_b32 m0, s20
	ds_read_b128 v[172:175], v202 offset:16384
	ds_read_b128 v[176:179], v202 offset:17408
	ds_read_b128 v[180:183], v202 offset:18432
	ds_read_b128 v[184:187], v202 offset:19456
	ds_read_b128 v[198:201], v202 offset:20480
	ds_read_b128 v[204:207], v202 offset:21504
	ds_read_b128 v[208:211], v202 offset:22528
	ds_read_b128 v[222:225], v202 offset:23552
	global_load_lds_dwordx4 v[188:189], off
	s_add_i32 m0, s20, 0x2000
	s_add_u32 s20, s44, 0xb0000
	v_lshl_add_u64 v[226:227], s[44:45], 0, v[158:159]
	s_addc_u32 s21, s45, 0
	s_add_i32 s30, s31, s33
	global_load_lds_dwordx4 v[226:227], off
	v_lshl_add_u64 v[228:229], s[20:21], 0, v[0:1]
	s_mov_b32 m0, s30
	v_lshl_add_u64 v[230:231], s[46:47], 0, v[160:161]
	global_load_lds_dwordx4 v[228:229], off
	v_lshl_add_u64 v[228:229], s[20:21], 0, v[158:159]
	s_add_i32 m0, s30, 0x2000
	s_nop 0
	global_load_lds_dwordx4 v[228:229], off
	v_lshl_add_u64 v[228:229], s[46:47], 0, v[162:163]
	s_mov_b32 m0, s48
	s_nop 0
	global_load_lds_dwordx4 v[228:229], off
	s_mov_b32 m0, s49
	s_nop 0
	global_load_lds_dwordx4 v[230:231], off
	s_waitcnt vmcnt(8)
	s_waitcnt lgkmcnt(0)
	s_barrier
	s_waitcnt lgkmcnt(0)
	v_mfma_f32_16x16x32_bf16 v[62:65], v[114:117], v[172:175], v[62:65]
	v_mfma_f32_16x16x32_bf16 v[58:61], v[130:133], v[172:175], v[58:61]
	v_mfma_f32_16x16x32_bf16 v[46:49], v[114:117], v[180:183], v[46:49]
	v_mfma_f32_16x16x32_bf16 v[42:45], v[130:133], v[180:183], v[42:45]
	v_mfma_f32_16x16x32_bf16 v[30:33], v[114:117], v[198:201], v[30:33]
	v_mfma_f32_16x16x32_bf16 v[26:29], v[130:133], v[198:201], v[26:29]
	v_mfma_f32_16x16x32_bf16 v[14:17], v[114:117], v[208:211], v[14:17]
	v_mfma_f32_16x16x32_bf16 v[10:13], v[130:133], v[208:211], v[10:13]
	v_mfma_f32_16x16x32_bf16 v[62:65], v[126:129], v[176:179], v[62:65]
	v_mfma_f32_16x16x32_bf16 v[58:61], v[134:137], v[176:179], v[58:61]
	v_mfma_f32_16x16x32_bf16 v[46:49], v[126:129], v[184:187], v[46:49]
	v_mfma_f32_16x16x32_bf16 v[42:45], v[134:137], v[184:187], v[42:45]
	v_mfma_f32_16x16x32_bf16 v[30:33], v[126:129], v[204:207], v[30:33]
	v_mfma_f32_16x16x32_bf16 v[26:29], v[134:137], v[204:207], v[26:29]
	v_mfma_f32_16x16x32_bf16 v[14:17], v[126:129], v[222:225], v[14:17]
	v_mfma_f32_16x16x32_bf16 v[10:13], v[134:137], v[222:225], v[10:13]
	v_mfma_f32_16x16x32_bf16 v[54:57], v[146:149], v[172:175], v[54:57]
	v_mfma_f32_16x16x32_bf16 v[50:53], v[154:157], v[172:175], v[50:53]
	v_mfma_f32_16x16x32_bf16 v[38:41], v[146:149], v[180:183], v[38:41]
	v_mfma_f32_16x16x32_bf16 v[34:37], v[154:157], v[180:183], v[34:37]
	v_mfma_f32_16x16x32_bf16 v[22:25], v[146:149], v[198:201], v[22:25]
	v_mfma_f32_16x16x32_bf16 v[18:21], v[154:157], v[198:201], v[18:21]
	v_mfma_f32_16x16x32_bf16 v[6:9], v[146:149], v[208:211], v[6:9]
	v_mfma_f32_16x16x32_bf16 v[2:5], v[154:157], v[208:211], v[2:5]
	v_mfma_f32_16x16x32_bf16 v[54:57], v[150:153], v[176:179], v[54:57]
	v_mfma_f32_16x16x32_bf16 v[50:53], v[168:171], v[176:179], v[50:53]
	v_mfma_f32_16x16x32_bf16 v[38:41], v[150:153], v[184:187], v[38:41]
	v_mfma_f32_16x16x32_bf16 v[34:37], v[168:171], v[184:187], v[34:37]
	v_mfma_f32_16x16x32_bf16 v[22:25], v[150:153], v[204:207], v[22:25]
	v_mfma_f32_16x16x32_bf16 v[18:21], v[168:171], v[204:207], v[18:21]
	v_mfma_f32_16x16x32_bf16 v[6:9], v[150:153], v[222:225], v[6:9]
	v_mfma_f32_16x16x32_bf16 v[2:5], v[168:171], v[222:225], v[2:5]
	s_barrier
; #define PG8_STAGE(bufoff, gbase, voff) do { _Pragma("unroll") for (int _i = 0; _i < 2; ++_i) \
;         __builtin_amdgcn_global_load_lds((const unsigned*)((const char*)(gbase) + (voff)[_i]), (PG8_LAS unsigned*)(lds + (bufoff) + ldsw + _i * 8192), 16, 0, 0); } while (0)
; #define PG8_LDA(dst, b, h) do { _Pragma("unroll") for (int m = 0; m < 4; ++m) _Pragma("unroll") for (int k = 0; k < 2; ++k) dst[m][k] = *(const PG8_LAS bf16x8*)(lds + PG8_SA(b, h) + aoff + m * 2048 + k * 1024); } while (0)
; #define PG8_LDB(dst, b, h) do { _Pragma("unroll") for (int n = 0; n < 2; ++n) _Pragma("unroll") for (int k = 0; k < 2; ++k) dst[n][k] = *(const PG8_LAS bf16x8*)(lds + PG8_SB(b, h) + boff + n * 2048 + k * 1024); } while (0)
; #define PG8_MMA(ai, bj, At, Bt) do { __builtin_amdgcn_s_setprio(1); _Pragma("unroll") for (int m = 0; m < 4; ++m) _Pragma("unroll") for (int n = 0; n < 2; ++n) _Pragma("unroll") for (int k = 0; k < 2; ++k) \
;         acc[ai][bj][m][n] = __builtin_amdgcn_mfma_f32_16x16x32_bf16(Bt[n][k], At[m][k], acc[ai][bj][m][n], 0, 0, 0); __builtin_amdgcn_s_setprio(0); } while (0)
; #define PG8_WAIT_V(n) asm volatile("s_waitcnt vmcnt(" #n ")" ::: "memory")
; #define PG8_WAIT_L(n) asm volatile("s_waitcnt lgkmcnt(" #n ")" ::: "memory")
; #define PG8_BAR __builtin_amdgcn_s_barrier()
; template <class Epi, class Sched, bool ALIGN_EPI = false, bool SP2 = false>
; __device__ __forceinline__ void gemm_phase(PG8_LAS unsigned char* lds, const Gemm g, const Sched& S, const Epi& E) {
;     ...
;         for (int t = 0; t < nt; t += 2) {
;             const bool last = (t == nt - 2);
;             const char* a1 = cA + (size_t)(t + 1) * kstep;
;             const char* a2 = last ? nA : cA + (size_t)(t + 2) * kstep; const char* b2 = last ? nB : cB + (size_t)(t + 2) * kstep;
;             const char* a3 = a2 + kstep; const char* b3 = b2 + kstep;
;     ...
;             PG8_LDB(B0, 1, 0); PG8_LDB(B1, 1, 1); PG8_SCHED; PG8_LDA(At, 1, 0); PG8_STAGE(PG8_SA(0, 1), a2 + hstep, voffA);
;             PG8_WAIT_V(8); PG8_WAIT_L(0); PG8_BAR; PG8_MMA(0, 0, At, B0); PG8_MMA(0, 1, At, B1); PG8_BAR; PG8_SCHED;
;             PG8_LDA(At, 1, 1); PG8_STAGE(PG8_SB(1, 0), b3, voffB); PG8_STAGE(PG8_SB(1, 1), b3 + hstep, voffB); PG8_STAGE(PG8_SA(1, 0), a3, voffA);
;             PG8_WAIT_V(8); PG8_WAIT_L(0); PG8_BAR; PG8_MMA(1, 0, At, B0); PG8_MMA(1, 1, At, B1); PG8_BAR; PG8_SCHED;
	s_add_i32 s30, 0, 0x18000
	s_add_i32 s31, 0, 0x1c000
	v_add_u32_e32 v134, s30, v191
	v_add_u32_e32 v168, s31, v191
	ds_read_b128 v[114:117], v134
	ds_read_b128 v[126:129], v134 offset:1024
	ds_read_b128 v[130:133], v134 offset:2048
	ds_read_b128 v[134:137], v134 offset:3072
	ds_read_b128 v[146:149], v168
	ds_read_b128 v[150:153], v168 offset:1024
	ds_read_b128 v[154:157], v168 offset:2048
	ds_read_b128 v[168:171], v168 offset:3072
	s_add_u32 s20, s46, 0xb0000
	s_addc_u32 s21, s47, 0
	s_mov_b32 m0, s50
	v_lshl_add_u64 v[232:233], s[20:21], 0, v[162:163]
	ds_read_b128 v[172:175], v202 offset:32768
	ds_read_b128 v[176:179], v202 offset:33792
	ds_read_b128 v[180:183], v202 offset:34816
	ds_read_b128 v[184:187], v202 offset:35840
	ds_read_b128 v[198:201], v202 offset:36864
	ds_read_b128 v[204:207], v202 offset:37888
	ds_read_b128 v[208:211], v202 offset:38912
	ds_read_b128 v[222:225], v202 offset:39936
	global_load_lds_dwordx4 v[232:233], off
	v_lshl_add_u64 v[232:233], s[20:21], 0, v[160:161]
	s_mov_b32 m0, s51
	s_nop 0
	global_load_lds_dwordx4 v[232:233], off
	s_waitcnt vmcnt(8)
	s_waitcnt lgkmcnt(0)
	s_barrier
	s_waitcnt lgkmcnt(0)
	v_mfma_f32_16x16x32_bf16 v[142:145], v[114:117], v[172:175], v[142:145]
	v_mfma_f32_16x16x32_bf16 v[138:141], v[130:133], v[172:175], v[138:141]
	v_mfma_f32_16x16x32_bf16 v[110:113], v[114:117], v[180:183], v[110:113]
	v_mfma_f32_16x16x32_bf16 v[106:109], v[130:133], v[180:183], v[106:109]
	v_mfma_f32_16x16x32_bf16 v[94:97], v[114:117], v[198:201], v[94:97]
	v_mfma_f32_16x16x32_bf16 v[90:93], v[130:133], v[198:201], v[90:93]
	v_mfma_f32_16x16x32_bf16 v[78:81], v[114:117], v[208:211], v[78:81]
	v_mfma_f32_16x16x32_bf16 v[74:77], v[130:133], v[208:211], v[74:77]
	v_mfma_f32_16x16x32_bf16 v[142:145], v[126:129], v[176:179], v[142:145]
	v_mfma_f32_16x16x32_bf16 v[138:141], v[134:137], v[176:179], v[138:141]
	v_mfma_f32_16x16x32_bf16 v[110:113], v[126:129], v[184:187], v[110:113]
	v_mfma_f32_16x16x32_bf16 v[106:109], v[134:137], v[184:187], v[106:109]
	v_mfma_f32_16x16x32_bf16 v[94:97], v[126:129], v[204:207], v[94:97]
	v_mfma_f32_16x16x32_bf16 v[90:93], v[134:137], v[204:207], v[90:93]
	v_mfma_f32_16x16x32_bf16 v[78:81], v[126:129], v[222:225], v[78:81]
	v_mfma_f32_16x16x32_bf16 v[74:77], v[134:137], v[222:225], v[74:77]
	v_mfma_f32_16x16x32_bf16 v[122:125], v[146:149], v[172:175], v[122:125]
	v_mfma_f32_16x16x32_bf16 v[118:121], v[154:157], v[172:175], v[118:121]
	v_mfma_f32_16x16x32_bf16 v[102:105], v[146:149], v[180:183], v[102:105]
	v_mfma_f32_16x16x32_bf16 v[98:101], v[154:157], v[180:183], v[98:101]
	v_mfma_f32_16x16x32_bf16 v[86:89], v[146:149], v[198:201], v[86:89]
	v_mfma_f32_16x16x32_bf16 v[82:85], v[154:157], v[198:201], v[82:85]
	v_mfma_f32_16x16x32_bf16 v[70:73], v[146:149], v[208:211], v[70:73]
	v_mfma_f32_16x16x32_bf16 v[66:69], v[154:157], v[208:211], v[66:69]
	v_mfma_f32_16x16x32_bf16 v[122:125], v[150:153], v[176:179], v[122:125]
	v_mfma_f32_16x16x32_bf16 v[118:121], v[168:171], v[176:179], v[118:121]
	v_mfma_f32_16x16x32_bf16 v[102:105], v[150:153], v[184:187], v[102:105]
	v_mfma_f32_16x16x32_bf16 v[98:101], v[168:171], v[184:187], v[98:101]
	v_mfma_f32_16x16x32_bf16 v[86:89], v[150:153], v[204:207], v[86:89]
	v_mfma_f32_16x16x32_bf16 v[82:85], v[168:171], v[204:207], v[82:85]
	v_mfma_f32_16x16x32_bf16 v[70:73], v[150:153], v[222:225], v[70:73]
	v_mfma_f32_16x16x32_bf16 v[66:69], v[168:171], v[222:225], v[66:69]
	s_barrier
	s_add_i32 s20, s30, s33
	v_lshl_add_u64 v[188:189], v[188:189], 0, s[0:1]
	s_mov_b32 m0, s20
	ds_read_b128 v[172:175], v202 offset:49152
	ds_read_b128 v[176:179], v202 offset:50176
	ds_read_b128 v[180:183], v202 offset:51200
	ds_read_b128 v[184:187], v202 offset:52224
	ds_read_b128 v[198:201], v202 offset:53248
	ds_read_b128 v[204:207], v202 offset:54272
	ds_read_b128 v[208:211], v202 offset:55296
	ds_read_b128 v[222:225], v202 offset:56320
	global_load_lds_dwordx4 v[188:189], off
	s_add_i32 m0, s20, 0x2000
	s_add_u32 s20, s44, 0xb0080
	v_lshl_add_u64 v[188:189], v[226:227], 0, s[0:1]
	s_addc_u32 s21, s45, 0
	s_add_i32 s30, s31, s33
	global_load_lds_dwordx4 v[188:189], off
	v_lshl_add_u64 v[188:189], s[20:21], 0, v[0:1]
	s_mov_b32 m0, s30
	s_nop 0
	global_load_lds_dwordx4 v[188:189], off
	v_lshl_add_u64 v[188:189], s[20:21], 0, v[158:159]
	s_add_i32 m0, s30, 0x2000
	s_nop 0
	global_load_lds_dwordx4 v[188:189], off
	v_lshl_add_u64 v[188:189], v[228:229], 0, s[0:1]
	s_mov_b32 m0, s54
	s_nop 0
	global_load_lds_dwordx4 v[188:189], off
	v_lshl_add_u64 v[188:189], v[230:231], 0, s[0:1]
	s_mov_b32 m0, s55
	s_nop 0
	global_load_lds_dwordx4 v[188:189], off
	s_waitcnt vmcnt(8)
	s_waitcnt lgkmcnt(0)
	s_barrier
	s_waitcnt lgkmcnt(0)
	v_mfma_f32_16x16x32_bf16 v[62:65], v[114:117], v[172:175], v[62:65]
	v_mfma_f32_16x16x32_bf16 v[58:61], v[130:133], v[172:175], v[58:61]
	v_mfma_f32_16x16x32_bf16 v[46:49], v[114:117], v[180:183], v[46:49]
	v_mfma_f32_16x16x32_bf16 v[42:45], v[130:133], v[180:183], v[42:45]
	v_mfma_f32_16x16x32_bf16 v[30:33], v[114:117], v[198:201], v[30:33]
	v_mfma_f32_16x16x32_bf16 v[26:29], v[130:133], v[198:201], v[26:29]
	v_mfma_f32_16x16x32_bf16 v[14:17], v[114:117], v[208:211], v[14:17]
	v_mfma_f32_16x16x32_bf16 v[10:13], v[130:133], v[208:211], v[10:13]
	v_mfma_f32_16x16x32_bf16 v[62:65], v[126:129], v[176:179], v[62:65]
	v_mfma_f32_16x16x32_bf16 v[58:61], v[134:137], v[176:179], v[58:61]
	v_mfma_f32_16x16x32_bf16 v[46:49], v[126:129], v[184:187], v[46:49]
	v_mfma_f32_16x16x32_bf16 v[42:45], v[134:137], v[184:187], v[42:45]
	v_mfma_f32_16x16x32_bf16 v[30:33], v[126:129], v[204:207], v[30:33]
	v_mfma_f32_16x16x32_bf16 v[26:29], v[134:137], v[204:207], v[26:29]
	v_mfma_f32_16x16x32_bf16 v[14:17], v[126:129], v[222:225], v[14:17]
	v_mfma_f32_16x16x32_bf16 v[10:13], v[134:137], v[222:225], v[10:13]
	v_mfma_f32_16x16x32_bf16 v[54:57], v[146:149], v[172:175], v[54:57]
	v_mfma_f32_16x16x32_bf16 v[50:53], v[154:157], v[172:175], v[50:53]
	v_mfma_f32_16x16x32_bf16 v[38:41], v[146:149], v[180:183], v[38:41]
	v_mfma_f32_16x16x32_bf16 v[34:37], v[154:157], v[180:183], v[34:37]
	v_mfma_f32_16x16x32_bf16 v[22:25], v[146:149], v[198:201], v[22:25]
	v_mfma_f32_16x16x32_bf16 v[18:21], v[154:157], v[198:201], v[18:21]
	v_mfma_f32_16x16x32_bf16 v[6:9], v[146:149], v[208:211], v[6:9]
	v_mfma_f32_16x16x32_bf16 v[2:5], v[154:157], v[208:211], v[2:5]
	v_mfma_f32_16x16x32_bf16 v[54:57], v[150:153], v[176:179], v[54:57]
	v_mfma_f32_16x16x32_bf16 v[50:53], v[168:171], v[176:179], v[50:53]
	v_mfma_f32_16x16x32_bf16 v[38:41], v[150:153], v[184:187], v[38:41]
	v_mfma_f32_16x16x32_bf16 v[34:37], v[168:171], v[184:187], v[34:37]
	v_mfma_f32_16x16x32_bf16 v[22:25], v[150:153], v[204:207], v[22:25]
	v_mfma_f32_16x16x32_bf16 v[18:21], v[168:171], v[204:207], v[18:21]
	v_mfma_f32_16x16x32_bf16 v[6:9], v[150:153], v[222:225], v[6:9]
	v_mfma_f32_16x16x32_bf16 v[2:5], v[168:171], v[222:225], v[2:5]
	s_barrier
	s_add_i32 s59, s59, 2
	s_add_u32 s34, s34, 0x100
	s_addc_u32 s35, s35, 0
	s_cmp_gt_u32 s59, 41
	s_mov_b64 s[20:21], s[42:43]
	s_cbranch_scc0 .LBB0_868
